# speedup vs baseline: 1.0136x; 1.0040x over previous
; #define MFMA32(a, b, c) __builtin_amdgcn_mfma_f32_32x32x16_bf16((a), (b), (c), 0, 0, 0)
; #define TK_PREFETCH(t_, p_) do { const int tk0_ = ((t_) >> 3) * 64, hp_ = ((t_) & 7) * 2 + (p_); \
;         _Pragma("unroll") for (int i_ = 0; i_ < 4; ++i_) { const int c_ = tid + 256 * i_; pre[i_] = *(const u32x4*)(qp + (size_t)(tk0_ + (c_ >> 4)) * 2048 + hp_ * 128 + (c_ & 15) * 8); } } while (0)
; DI void topk_phase(unsigned char* smem_, const bf16_t* __restrict__ qp, const bf16_t* __restrict__ keys, int* __restrict__ eidx, float* __restrict__ gate) {
;     ...
;     for (int p = 0; p < 2; ++p) {
; #pragma unroll
;         for (int i = 0; i < 4; ++i) { const int c = tid + 256 * i; *(u32x4*)(As + (c >> 4) * LDA + (c & 15) * 8) = pre[i]; }
;         __syncthreads();
;         f32x16 acc[2];
; #pragma unroll
;         for (int i = 0; i < 16; ++i) { acc[0][i] = 0.f; acc[1][i] = 0.f; }
; #pragma unroll
;         for (int ks = 0; ks < 8; ++ks) {
; #pragma unroll
;             for (int th = 0; th < 2; ++th) { const bf16x8 qf = *(const bf16x8*)(As + (32 * th + l31) * LDA + ks * 16 + hi * 8); acc[th] = MFMA32(kf[p][ks], qf, acc[th]); }
;         }
; #pragma unroll
;         for (int th = 0; th < 2; ++th)
; #pragma unroll
;             for (int g = 0; g < 4; ++g) { f32x4 o; o.x = acc[th][4 * g]; o.y = acc[th][4 * g + 1]; o.z = acc[th][4 * g + 2]; o.w = acc[th][4 * g + 3]; *(f32x4*)(S + (32 * th + l31) * LDS_ + 32 * wid + 8 * g + 4 * hi) = o; }
;         __syncthreads();
;         if (p == 0) TK_PREFETCH(t, 1); else if (t + G < NT) TK_PREFETCH(t + G, 0);
;         unsigned v[32];
; #pragma unroll
;         for (int i = 0; i < 8; ++i) {
;             const f32x4 sv4 = *(const f32x4*)(S + row * LDS_ + 32 * q + 4 * i);
.LBB0_57:
	s_waitcnt vmcnt(0)
	ds_write_b128 v234, v[96:99]
	ds_write_b128 v234, v[100:103] offset:4352
	ds_write_b128 v234, v[104:107] offset:8704
	ds_write_b128 v234, v[108:111] offset:13056
	s_waitcnt lgkmcnt(0)
	s_barrier
	ds_read_b128 v[0:3], v235
	ds_read_b128 v[96:99], v235 offset:32
	s_waitcnt lgkmcnt(1)
	v_mfma_f32_32x32x16_bf16 v[16:31], v[32:35], v[0:3], 0
	ds_read_b128 v[0:3], v235 offset:8704
	s_and_b32 s24, s22, 0xffffffc0
	s_lshl_b32 s0, s0, 1
	s_add_u32 s0, s86, s0
	s_addc_u32 s1, s87, 0
	s_waitcnt lgkmcnt(1)
	v_mfma_f32_32x32x16_bf16 v[16:31], v[36:39], v[96:99], v[16:31]
	ds_read_b128 v[96:99], v235 offset:8736
	s_waitcnt lgkmcnt(1)
	v_mfma_f32_32x32x16_bf16 v[0:15], v[32:35], v[0:3], 0
	s_waitcnt lgkmcnt(0)
	v_mfma_f32_32x32x16_bf16 v[0:15], v[36:39], v[96:99], v[0:15]
	ds_read_b128 v[100:103], v235 offset:64
	ds_read_b128 v[104:107], v235 offset:8768
	ds_read_b128 v[108:111], v235 offset:96
	s_waitcnt lgkmcnt(2)
	v_mfma_f32_32x32x16_bf16 v[16:31], v[40:43], v[100:103], v[16:31]
	ds_read_b128 v[96:99], v235 offset:8800
	s_waitcnt lgkmcnt(2)
	v_mfma_f32_32x32x16_bf16 v[0:15], v[40:43], v[104:107], v[0:15]
	ds_read_b128 v[100:103], v235 offset:128
	s_waitcnt lgkmcnt(2)
	v_mfma_f32_32x32x16_bf16 v[16:31], v[44:47], v[108:111], v[16:31]
	ds_read_b128 v[104:107], v235 offset:8832
	s_waitcnt lgkmcnt(2)
	v_mfma_f32_32x32x16_bf16 v[0:15], v[44:47], v[96:99], v[0:15]
	ds_read_b128 v[108:111], v235 offset:160
	s_waitcnt lgkmcnt(2)
	v_mfma_f32_32x32x16_bf16 v[16:31], v[48:51], v[100:103], v[16:31]
	ds_read_b128 v[96:99], v235 offset:8864
	s_waitcnt lgkmcnt(2)
	v_mfma_f32_32x32x16_bf16 v[0:15], v[48:51], v[104:107], v[0:15]
	ds_read_b128 v[100:103], v235 offset:192
	s_waitcnt lgkmcnt(2)
	v_mfma_f32_32x32x16_bf16 v[16:31], v[52:55], v[108:111], v[16:31]
	ds_read_b128 v[104:107], v235 offset:8896
	s_waitcnt lgkmcnt(2)
	v_mfma_f32_32x32x16_bf16 v[0:15], v[52:55], v[96:99], v[0:15]
	ds_read_b128 v[108:111], v235 offset:224
	s_waitcnt lgkmcnt(2)
	v_mfma_f32_32x32x16_bf16 v[16:31], v[56:59], v[100:103], v[16:31]
	ds_read_b128 v[96:99], v235 offset:8928
	s_waitcnt lgkmcnt(2)
	v_mfma_f32_32x32x16_bf16 v[0:15], v[56:59], v[104:107], v[0:15]
	s_waitcnt lgkmcnt(1)
	v_mfma_f32_32x32x16_bf16 v[16:31], v[60:63], v[108:111], v[16:31]
	s_nop 0
	s_nop 10
	ds_write_b128 v236, v[16:19] offset:17408
	ds_write_b128 v236, v[20:23] offset:17440
	ds_write_b128 v236, v[24:27] offset:17472
	ds_write_b128 v236, v[28:31] offset:17504
	s_waitcnt lgkmcnt(4)
	v_mfma_f32_32x32x16_bf16 v[0:15], v[60:63], v[96:99], v[0:15]
	s_nop 11
	ds_write_b128 v236, v[0:3] offset:34304
	ds_write_b128 v236, v[4:7] offset:34336
	ds_write_b128 v236, v[8:11] offset:34368
	ds_write_b128 v236, v[12:15] offset:34400
	v_or_b32_e32 v0, s24, v165
	v_ashrrev_i32_e32 v1, 31, v0
	v_lshlrev_b64 v[0:1], 12, v[0:1]
	v_lshl_add_u64 v[0:1], s[0:1], 0, v[0:1]
	v_lshl_add_u64 v[0:1], v[0:1], 0, v[128:129]
	s_waitcnt lgkmcnt(0)
	s_barrier
	global_load_dwordx4 v[96:99], v[0:1], off offset:256
	v_or_b32_e32 v0, s24, v166
	v_ashrrev_i32_e32 v1, 31, v0
	v_lshlrev_b64 v[0:1], 12, v[0:1]
	v_lshl_add_u64 v[0:1], s[0:1], 0, v[0:1]
	v_lshl_add_u64 v[0:1], v[0:1], 0, v[128:129]
	global_load_dwordx4 v[100:103], v[0:1], off offset:256
	v_or_b32_e32 v0, s24, v167
	v_ashrrev_i32_e32 v1, 31, v0
	v_lshlrev_b64 v[0:1], 12, v[0:1]
	v_lshl_add_u64 v[0:1], s[0:1], 0, v[0:1]
	v_lshl_add_u64 v[0:1], v[0:1], 0, v[128:129]
	global_load_dwordx4 v[104:107], v[0:1], off offset:256
	v_or_b32_e32 v0, s24, v168
	v_ashrrev_i32_e32 v1, 31, v0
	v_lshlrev_b64 v[0:1], 12, v[0:1]
	v_lshl_add_u64 v[0:1], s[0:1], 0, v[0:1]
	v_lshl_add_u64 v[4:5], v[0:1], 0, v[128:129]
	ds_read_b128 v[0:3], v171 offset:17408
	global_load_dwordx4 v[108:111], v[4:5], off offset:256
	ds_read_b128 v[4:7], v171 offset:17424
	ds_read_b128 v[8:11], v171 offset:17440
	ds_read_b128 v[12:15], v171 offset:17456
	s_waitcnt lgkmcnt(3)
	v_ashrrev_i32_e32 v16, 31, v0


; DI unsigned fkey(float f) { const unsigned u = __float_as_uint(f); return (u & 0x80000000u) ? ~u : (u | 0x80000000u); }
; DI void topk_phase(unsigned char* smem_, const bf16_t* __restrict__ qp, const bf16_t* __restrict__ keys, int* __restrict__ eidx, float* __restrict__ gate) {
;     ...
;         for (int i = 0; i < 8; ++i) {
;             const f32x4 sv4 = *(const f32x4*)(S + row * LDS_ + 32 * q + 4 * i);
;             const int ib = 127 - (32 * q + 4 * i);
;             v[4 * i] = (fkey(sv4.x) & ~127u) | (unsigned)ib; v[4 * i + 1] = (fkey(sv4.y) & ~127u) | (unsigned)(ib - 1);
;             v[4 * i + 2] = (fkey(sv4.z) & ~127u) | (unsigned)(ib - 2); v[4 * i + 3] = (fkey(sv4.w) & ~127u) | (unsigned)(ib - 3);
;         }
	s_waitcnt lgkmcnt(0)
	v_not_b32_e32 v20, v15
	v_or_b32_e32 v21, 0x80000000, v15
	v_bitop3_b32 v0, v16, s98, v0 bitop3:0x56
	v_ashrrev_i32_e32 v16, 31, v1


; DI unsigned fkey(float f) { const unsigned u = __float_as_uint(f); return (u & 0x80000000u) ? ~u : (u | 0x80000000u); }
; DI void topk_phase(unsigned char* smem_, const bf16_t* __restrict__ qp, const bf16_t* __restrict__ keys, int* __restrict__ eidx, float* __restrict__ gate) {
;     ...
;         for (int i = 0; i < 8; ++i) {
;             const f32x4 sv4 = *(const f32x4*)(S + row * LDS_ + 32 * q + 4 * i);
;             const int ib = 127 - (32 * q + 4 * i);
;             v[4 * i] = (fkey(sv4.x) & ~127u) | (unsigned)ib; v[4 * i + 1] = (fkey(sv4.y) & ~127u) | (unsigned)(ib - 1);
;             v[4 * i + 2] = (fkey(sv4.z) & ~127u) | (unsigned)(ib - 2); v[4 * i + 3] = (fkey(sv4.w) & ~127u) | (unsigned)(ib - 3);
;         }
	v_and_b32_e32 v0, 0xffffff80, v0
	v_sub_u32_e32 v0, v0, v170
	v_bitop3_b32 v1, v16, s98, v1 bitop3:0x56
	v_ashrrev_i32_e32 v16, 31, v2


; DI unsigned fkey(float f) { const unsigned u = __float_as_uint(f); return (u & 0x80000000u) ? ~u : (u | 0x80000000u); }
; DI void topk_phase(unsigned char* smem_, const bf16_t* __restrict__ qp, const bf16_t* __restrict__ keys, int* __restrict__ eidx, float* __restrict__ gate) {
;     ...
;         for (int i = 0; i < 8; ++i) {
;             const f32x4 sv4 = *(const f32x4*)(S + row * LDS_ + 32 * q + 4 * i);
;             const int ib = 127 - (32 * q + 4 * i);
;             v[4 * i] = (fkey(sv4.x) & ~127u) | (unsigned)ib; v[4 * i + 1] = (fkey(sv4.y) & ~127u) | (unsigned)(ib - 1);
;             v[4 * i + 2] = (fkey(sv4.z) & ~127u) | (unsigned)(ib - 2); v[4 * i + 3] = (fkey(sv4.w) & ~127u) | (unsigned)(ib - 3);
;         }
	v_and_b32_e32 v1, 0xffffff80, v1
	v_sub_u32_e32 v1, v1, v170
	v_bitop3_b32 v2, v16, s98, v2 bitop3:0x56
	v_ashrrev_i32_e32 v16, 31, v3


; DI unsigned fkey(float f) { const unsigned u = __float_as_uint(f); return (u & 0x80000000u) ? ~u : (u | 0x80000000u); }
; DI void topk_phase(unsigned char* smem_, const bf16_t* __restrict__ qp, const bf16_t* __restrict__ keys, int* __restrict__ eidx, float* __restrict__ gate) {
;     ...
;         for (int i = 0; i < 8; ++i) {
;             const f32x4 sv4 = *(const f32x4*)(S + row * LDS_ + 32 * q + 4 * i);
;             const int ib = 127 - (32 * q + 4 * i);
;             v[4 * i] = (fkey(sv4.x) & ~127u) | (unsigned)ib; v[4 * i + 1] = (fkey(sv4.y) & ~127u) | (unsigned)(ib - 1);
;             v[4 * i + 2] = (fkey(sv4.z) & ~127u) | (unsigned)(ib - 2); v[4 * i + 3] = (fkey(sv4.w) & ~127u) | (unsigned)(ib - 3);
;         }
	v_and_b32_e32 v2, 0xffffff80, v2
	v_sub_u32_e32 v2, v2, v170
	v_bitop3_b32 v3, v16, s98, v3 bitop3:0x56
	v_ashrrev_i32_e32 v16, 31, v4


; DI unsigned fkey(float f) { const unsigned u = __float_as_uint(f); return (u & 0x80000000u) ? ~u : (u | 0x80000000u); }
; DI void topk_phase(unsigned char* smem_, const bf16_t* __restrict__ qp, const bf16_t* __restrict__ keys, int* __restrict__ eidx, float* __restrict__ gate) {
;     ...
;         for (int i = 0; i < 8; ++i) {
;             const f32x4 sv4 = *(const f32x4*)(S + row * LDS_ + 32 * q + 4 * i);
;             const int ib = 127 - (32 * q + 4 * i);
;             v[4 * i] = (fkey(sv4.x) & ~127u) | (unsigned)ib; v[4 * i + 1] = (fkey(sv4.y) & ~127u) | (unsigned)(ib - 1);
;             v[4 * i + 2] = (fkey(sv4.z) & ~127u) | (unsigned)(ib - 2); v[4 * i + 3] = (fkey(sv4.w) & ~127u) | (unsigned)(ib - 3);
;         }
	v_and_b32_e32 v3, 0xffffff80, v3
	v_sub_u32_e32 v3, v3, v170
	v_bitop3_b32 v4, v16, s98, v4 bitop3:0x56
	v_ashrrev_i32_e32 v16, 31, v5


; DI unsigned fkey(float f) { const unsigned u = __float_as_uint(f); return (u & 0x80000000u) ? ~u : (u | 0x80000000u); }
; DI void topk_phase(unsigned char* smem_, const bf16_t* __restrict__ qp, const bf16_t* __restrict__ keys, int* __restrict__ eidx, float* __restrict__ gate) {
;     ...
;         for (int i = 0; i < 8; ++i) {
;             const f32x4 sv4 = *(const f32x4*)(S + row * LDS_ + 32 * q + 4 * i);
;             const int ib = 127 - (32 * q + 4 * i);
;             v[4 * i] = (fkey(sv4.x) & ~127u) | (unsigned)ib; v[4 * i + 1] = (fkey(sv4.y) & ~127u) | (unsigned)(ib - 1);
;             v[4 * i + 2] = (fkey(sv4.z) & ~127u) | (unsigned)(ib - 2); v[4 * i + 3] = (fkey(sv4.w) & ~127u) | (unsigned)(ib - 3);
;         }
	v_and_b32_e32 v4, 0xffffff80, v4
	v_sub_u32_e32 v4, v4, v177
	v_bitop3_b32 v5, v16, s98, v5 bitop3:0x56
	v_ashrrev_i32_e32 v16, 31, v6


; DI unsigned fkey(float f) { const unsigned u = __float_as_uint(f); return (u & 0x80000000u) ? ~u : (u | 0x80000000u); }
; DI void topk_phase(unsigned char* smem_, const bf16_t* __restrict__ qp, const bf16_t* __restrict__ keys, int* __restrict__ eidx, float* __restrict__ gate) {
;     ...
;         for (int i = 0; i < 8; ++i) {
;             const f32x4 sv4 = *(const f32x4*)(S + row * LDS_ + 32 * q + 4 * i);
;             const int ib = 127 - (32 * q + 4 * i);
;             v[4 * i] = (fkey(sv4.x) & ~127u) | (unsigned)ib; v[4 * i + 1] = (fkey(sv4.y) & ~127u) | (unsigned)(ib - 1);
;             v[4 * i + 2] = (fkey(sv4.z) & ~127u) | (unsigned)(ib - 2); v[4 * i + 3] = (fkey(sv4.w) & ~127u) | (unsigned)(ib - 3);
;         }
	v_and_b32_e32 v5, 0xffffff80, v5
	v_sub_u32_e32 v5, v5, v177
	v_bitop3_b32 v6, v16, s98, v6 bitop3:0x56
	v_ashrrev_i32_e32 v16, 31, v7


; DI unsigned fkey(float f) { const unsigned u = __float_as_uint(f); return (u & 0x80000000u) ? ~u : (u | 0x80000000u); }
; DI void topk_phase(unsigned char* smem_, const bf16_t* __restrict__ qp, const bf16_t* __restrict__ keys, int* __restrict__ eidx, float* __restrict__ gate) {
;     ...
;         for (int i = 0; i < 8; ++i) {
;             const f32x4 sv4 = *(const f32x4*)(S + row * LDS_ + 32 * q + 4 * i);
;             const int ib = 127 - (32 * q + 4 * i);
;             v[4 * i] = (fkey(sv4.x) & ~127u) | (unsigned)ib; v[4 * i + 1] = (fkey(sv4.y) & ~127u) | (unsigned)(ib - 1);
;             v[4 * i + 2] = (fkey(sv4.z) & ~127u) | (unsigned)(ib - 2); v[4 * i + 3] = (fkey(sv4.w) & ~127u) | (unsigned)(ib - 3);
;         }
	v_and_b32_e32 v6, 0xffffff80, v6
	v_sub_u32_e32 v6, v6, v177
	v_bitop3_b32 v7, v16, s98, v7 bitop3:0x56
	v_ashrrev_i32_e32 v16, 31, v8


; DI unsigned fkey(float f) { const unsigned u = __float_as_uint(f); return (u & 0x80000000u) ? ~u : (u | 0x80000000u); }
; DI void topk_phase(unsigned char* smem_, const bf16_t* __restrict__ qp, const bf16_t* __restrict__ keys, int* __restrict__ eidx, float* __restrict__ gate) {
;     ...
;         for (int i = 0; i < 8; ++i) {
;             const f32x4 sv4 = *(const f32x4*)(S + row * LDS_ + 32 * q + 4 * i);
;             const int ib = 127 - (32 * q + 4 * i);
;             v[4 * i] = (fkey(sv4.x) & ~127u) | (unsigned)ib; v[4 * i + 1] = (fkey(sv4.y) & ~127u) | (unsigned)(ib - 1);
;             v[4 * i + 2] = (fkey(sv4.z) & ~127u) | (unsigned)(ib - 2); v[4 * i + 3] = (fkey(sv4.w) & ~127u) | (unsigned)(ib - 3);
;         }
	v_and_b32_e32 v7, 0xffffff80, v7
	v_sub_u32_e32 v7, v7, v177
	v_bitop3_b32 v8, v16, s98, v8 bitop3:0x56
	v_ashrrev_i32_e32 v16, 31, v9


; DI unsigned fkey(float f) { const unsigned u = __float_as_uint(f); return (u & 0x80000000u) ? ~u : (u | 0x80000000u); }
; DI void topk_phase(unsigned char* smem_, const bf16_t* __restrict__ qp, const bf16_t* __restrict__ keys, int* __restrict__ eidx, float* __restrict__ gate) {
;     ...
;         for (int i = 0; i < 8; ++i) {
;             const f32x4 sv4 = *(const f32x4*)(S + row * LDS_ + 32 * q + 4 * i);
;             const int ib = 127 - (32 * q + 4 * i);
;             v[4 * i] = (fkey(sv4.x) & ~127u) | (unsigned)ib; v[4 * i + 1] = (fkey(sv4.y) & ~127u) | (unsigned)(ib - 1);
;             v[4 * i + 2] = (fkey(sv4.z) & ~127u) | (unsigned)(ib - 2); v[4 * i + 3] = (fkey(sv4.w) & ~127u) | (unsigned)(ib - 3);
;         }
	v_and_b32_e32 v8, 0xffffff80, v8
	v_sub_u32_e32 v8, v8, v178
	v_bitop3_b32 v9, v16, s98, v9 bitop3:0x56
	v_ashrrev_i32_e32 v16, 31, v10


; DI unsigned fkey(float f) { const unsigned u = __float_as_uint(f); return (u & 0x80000000u) ? ~u : (u | 0x80000000u); }
; DI void topk_phase(unsigned char* smem_, const bf16_t* __restrict__ qp, const bf16_t* __restrict__ keys, int* __restrict__ eidx, float* __restrict__ gate) {
;     ...
;         for (int i = 0; i < 8; ++i) {
;             const f32x4 sv4 = *(const f32x4*)(S + row * LDS_ + 32 * q + 4 * i);
;             const int ib = 127 - (32 * q + 4 * i);
;             v[4 * i] = (fkey(sv4.x) & ~127u) | (unsigned)ib; v[4 * i + 1] = (fkey(sv4.y) & ~127u) | (unsigned)(ib - 1);
;             v[4 * i + 2] = (fkey(sv4.z) & ~127u) | (unsigned)(ib - 2); v[4 * i + 3] = (fkey(sv4.w) & ~127u) | (unsigned)(ib - 3);
;         }
	v_and_b32_e32 v9, 0xffffff80, v9
	v_sub_u32_e32 v9, v9, v178
	v_bitop3_b32 v10, v16, s98, v10 bitop3:0x56
	v_and_b32_e32 v10, 0xffffff80, v10
	v_sub_u32_e32 v10, v10, v178
	v_add_u32_e32 v16, 0x7d, v10
	v_not_b32_e32 v10, v11
	v_or_b32_e32 v17, 0x80000000, v11
	v_cmp_gt_i32_e32 vcc, 0, v11
	v_ashrrev_i32_e32 v11, 31, v12
	v_add_u32_e32 v0, 0x7f, v0
	v_cndmask_b32_e32 v10, v17, v10, vcc
	v_and_b32_e32 v10, 0xffffff80, v10
	v_sub_u32_e32 v10, v10, v178
	v_add_u32_e32 v17, 0x7c, v10


; DI unsigned fkey(float f) { const unsigned u = __float_as_uint(f); return (u & 0x80000000u) ? ~u : (u | 0x80000000u); }
; DI void topk_phase(unsigned char* smem_, const bf16_t* __restrict__ qp, const bf16_t* __restrict__ keys, int* __restrict__ eidx, float* __restrict__ gate) {
;     ...
;         for (int i = 0; i < 8; ++i) {
;             const f32x4 sv4 = *(const f32x4*)(S + row * LDS_ + 32 * q + 4 * i);
;             const int ib = 127 - (32 * q + 4 * i);
;             v[4 * i] = (fkey(sv4.x) & ~127u) | (unsigned)ib; v[4 * i + 1] = (fkey(sv4.y) & ~127u) | (unsigned)(ib - 1);
;             v[4 * i + 2] = (fkey(sv4.z) & ~127u) | (unsigned)(ib - 2); v[4 * i + 3] = (fkey(sv4.w) & ~127u) | (unsigned)(ib - 3);
;         }
	v_add_u32_e32 v1, 0x7e, v1
	v_add_u32_e32 v2, 0x7d, v2
	v_bitop3_b32 v10, v11, s98, v12 bitop3:0x56
	v_and_b32_e32 v10, 0xffffff80, v10
	v_sub_u32_e32 v10, v10, v179
	v_add_u32_e32 v18, 0x7f, v10
	v_ashrrev_i32_e32 v10, 31, v13


; DI unsigned fkey(float f) { const unsigned u = __float_as_uint(f); return (u & 0x80000000u) ? ~u : (u | 0x80000000u); }
; DI void topk_phase(unsigned char* smem_, const bf16_t* __restrict__ qp, const bf16_t* __restrict__ keys, int* __restrict__ eidx, float* __restrict__ gate) {
;     ...
;         for (int i = 0; i < 8; ++i) {
;             const f32x4 sv4 = *(const f32x4*)(S + row * LDS_ + 32 * q + 4 * i);
;             const int ib = 127 - (32 * q + 4 * i);
;             v[4 * i] = (fkey(sv4.x) & ~127u) | (unsigned)ib; v[4 * i + 1] = (fkey(sv4.y) & ~127u) | (unsigned)(ib - 1);
;             v[4 * i + 2] = (fkey(sv4.z) & ~127u) | (unsigned)(ib - 2); v[4 * i + 3] = (fkey(sv4.w) & ~127u) | (unsigned)(ib - 3);
;         }
	v_add_u32_e32 v3, 0x7c, v3
	v_add_u32_e32 v4, 0x7f, v4
	v_bitop3_b32 v10, v10, s98, v13 bitop3:0x56
	v_and_b32_e32 v10, 0xffffff80, v10
	v_sub_u32_e32 v10, v10, v179
	v_add_u32_e32 v19, 0x7e, v10
	v_ashrrev_i32_e32 v10, 31, v14


; DI unsigned fkey(float f) { const unsigned u = __float_as_uint(f); return (u & 0x80000000u) ? ~u : (u | 0x80000000u); }
; DI void topk_phase(unsigned char* smem_, const bf16_t* __restrict__ qp, const bf16_t* __restrict__ keys, int* __restrict__ eidx, float* __restrict__ gate) {
;     ...
;         for (int i = 0; i < 8; ++i) {
;             const f32x4 sv4 = *(const f32x4*)(S + row * LDS_ + 32 * q + 4 * i);
;             const int ib = 127 - (32 * q + 4 * i);
;             v[4 * i] = (fkey(sv4.x) & ~127u) | (unsigned)ib; v[4 * i + 1] = (fkey(sv4.y) & ~127u) | (unsigned)(ib - 1);
;             v[4 * i + 2] = (fkey(sv4.z) & ~127u) | (unsigned)(ib - 2); v[4 * i + 3] = (fkey(sv4.w) & ~127u) | (unsigned)(ib - 3);
;         }
	v_add_u32_e32 v5, 0x7e, v5
	v_add_u32_e32 v6, 0x7d, v6
	v_bitop3_b32 v10, v10, s98, v14 bitop3:0x56
	v_and_b32_e32 v10, 0xffffff80, v10
	v_sub_u32_e32 v10, v10, v179
	v_add_u32_e32 v14, 0x7d, v10
	ds_read_b128 v[10:13], v171 offset:17472
	v_cmp_gt_i32_e32 vcc, 0, v15
	v_add_u32_e32 v7, 0x7c, v7
	v_add_u32_e32 v8, 0x7f, v8
	v_cndmask_b32_e32 v15, v21, v20, vcc
	s_waitcnt lgkmcnt(0)
	v_ashrrev_i32_e32 v20, 31, v10


; DI unsigned fkey(float f) { const unsigned u = __float_as_uint(f); return (u & 0x80000000u) ? ~u : (u | 0x80000000u); }
; DI void topk_phase(unsigned char* smem_, const bf16_t* __restrict__ qp, const bf16_t* __restrict__ keys, int* __restrict__ eidx, float* __restrict__ gate) {
;     ...
;         for (int i = 0; i < 8; ++i) {
;             const f32x4 sv4 = *(const f32x4*)(S + row * LDS_ + 32 * q + 4 * i);
;             const int ib = 127 - (32 * q + 4 * i);
;             v[4 * i] = (fkey(sv4.x) & ~127u) | (unsigned)ib; v[4 * i + 1] = (fkey(sv4.y) & ~127u) | (unsigned)(ib - 1);
;             v[4 * i + 2] = (fkey(sv4.z) & ~127u) | (unsigned)(ib - 2); v[4 * i + 3] = (fkey(sv4.w) & ~127u) | (unsigned)(ib - 3);
;         }
	v_not_b32_e32 v23, v13
	v_or_b32_e32 v24, 0x80000000, v13
	v_bitop3_b32 v10, v20, s98, v10 bitop3:0x56
	v_and_b32_e32 v10, 0xffffff80, v10
	v_sub_u32_e32 v10, v10, v180
	v_add_u32_e32 v20, 0x7f, v10
	v_not_b32_e32 v10, v11
	v_or_b32_e32 v21, 0x80000000, v11
	v_cmp_gt_i32_e32 vcc, 0, v11
	v_ashrrev_i32_e32 v11, 31, v12
	v_and_b32_e32 v15, 0xffffff80, v15
	v_cndmask_b32_e32 v10, v21, v10, vcc
	v_and_b32_e32 v10, 0xffffff80, v10
	v_sub_u32_e32 v10, v10, v180
	v_add_u32_e32 v21, 0x7e, v10


; DI unsigned fkey(float f) { const unsigned u = __float_as_uint(f); return (u & 0x80000000u) ? ~u : (u | 0x80000000u); }
; DI void topk_phase(unsigned char* smem_, const bf16_t* __restrict__ qp, const bf16_t* __restrict__ keys, int* __restrict__ eidx, float* __restrict__ gate) {
;     ...
;         for (int i = 0; i < 8; ++i) {
;             const f32x4 sv4 = *(const f32x4*)(S + row * LDS_ + 32 * q + 4 * i);
;             const int ib = 127 - (32 * q + 4 * i);
;             v[4 * i] = (fkey(sv4.x) & ~127u) | (unsigned)ib; v[4 * i + 1] = (fkey(sv4.y) & ~127u) | (unsigned)(ib - 1);
;             v[4 * i + 2] = (fkey(sv4.z) & ~127u) | (unsigned)(ib - 2); v[4 * i + 3] = (fkey(sv4.w) & ~127u) | (unsigned)(ib - 3);
;         }
	v_sub_u32_e32 v15, v15, v179
	v_add_u32_e32 v9, 0x7e, v9
	v_bitop3_b32 v10, v11, s98, v12 bitop3:0x56
	v_and_b32_e32 v10, 0xffffff80, v10
	v_sub_u32_e32 v10, v10, v180
	v_add_u32_e32 v22, 0x7d, v10
	v_cmp_gt_i32_e32 vcc, 0, v13
	ds_read_b128 v[10:13], v171 offset:17488
	v_add_u32_e32 v15, 0x7c, v15
	v_cndmask_b32_e32 v23, v24, v23, vcc
	v_and_b32_e32 v23, 0xffffff80, v23
	v_sub_u32_e32 v23, v23, v180
	s_waitcnt lgkmcnt(0)
	v_ashrrev_i32_e32 v24, 31, v10


; DI unsigned fkey(float f) { const unsigned u = __float_as_uint(f); return (u & 0x80000000u) ? ~u : (u | 0x80000000u); }
; DI void topk_phase(unsigned char* smem_, const bf16_t* __restrict__ qp, const bf16_t* __restrict__ keys, int* __restrict__ eidx, float* __restrict__ gate) {
;     ...
;         for (int i = 0; i < 8; ++i) {
;             const f32x4 sv4 = *(const f32x4*)(S + row * LDS_ + 32 * q + 4 * i);
;             const int ib = 127 - (32 * q + 4 * i);
;             v[4 * i] = (fkey(sv4.x) & ~127u) | (unsigned)ib; v[4 * i + 1] = (fkey(sv4.y) & ~127u) | (unsigned)(ib - 1);
;             v[4 * i + 2] = (fkey(sv4.z) & ~127u) | (unsigned)(ib - 2); v[4 * i + 3] = (fkey(sv4.w) & ~127u) | (unsigned)(ib - 3);
;         }
	v_not_b32_e32 v27, v13
	v_or_b32_e32 v28, 0x80000000, v13
	v_bitop3_b32 v10, v24, s98, v10 bitop3:0x56
	v_and_b32_e32 v10, 0xffffff80, v10
	v_sub_u32_e32 v10, v10, v181
	v_add_u32_e32 v24, 0x7f, v10
	v_not_b32_e32 v10, v11
	v_or_b32_e32 v25, 0x80000000, v11
	v_cmp_gt_i32_e32 vcc, 0, v11
	v_ashrrev_i32_e32 v11, 31, v12
	v_add_u32_e32 v23, 0x7c, v23
	v_cndmask_b32_e32 v10, v25, v10, vcc
	v_and_b32_e32 v10, 0xffffff80, v10
	v_sub_u32_e32 v10, v10, v181
	v_add_u32_e32 v25, 0x7e, v10


; DI unsigned fkey(float f) { const unsigned u = __float_as_uint(f); return (u & 0x80000000u) ? ~u : (u | 0x80000000u); }
; DI void topk_phase(unsigned char* smem_, const bf16_t* __restrict__ qp, const bf16_t* __restrict__ keys, int* __restrict__ eidx, float* __restrict__ gate) {
;     ...
;         for (int i = 0; i < 8; ++i) {
;             const f32x4 sv4 = *(const f32x4*)(S + row * LDS_ + 32 * q + 4 * i);
;             const int ib = 127 - (32 * q + 4 * i);
;             v[4 * i] = (fkey(sv4.x) & ~127u) | (unsigned)ib; v[4 * i + 1] = (fkey(sv4.y) & ~127u) | (unsigned)(ib - 1);
;             v[4 * i + 2] = (fkey(sv4.z) & ~127u) | (unsigned)(ib - 2); v[4 * i + 3] = (fkey(sv4.w) & ~127u) | (unsigned)(ib - 3);
;         }
	s_nop 1
	v_bitop3_b32 v10, v11, s98, v12 bitop3:0x56
	v_and_b32_e32 v10, 0xffffff80, v10
	v_sub_u32_e32 v10, v10, v181
	v_add_u32_e32 v26, 0x7d, v10
	v_cmp_gt_i32_e32 vcc, 0, v13
	ds_read_b128 v[10:13], v171 offset:17504
	s_waitcnt lgkmcnt(0)
	v_ashrrev_i32_e32 v29, 31, v10
	v_cndmask_b32_e32 v27, v28, v27, vcc


; DI unsigned fkey(float f) { const unsigned u = __float_as_uint(f); return (u & 0x80000000u) ? ~u : (u | 0x80000000u); }
; DI void topk_phase(unsigned char* smem_, const bf16_t* __restrict__ qp, const bf16_t* __restrict__ keys, int* __restrict__ eidx, float* __restrict__ gate) {
;     ...
;         for (int i = 0; i < 8; ++i) {
;             const f32x4 sv4 = *(const f32x4*)(S + row * LDS_ + 32 * q + 4 * i);
;             const int ib = 127 - (32 * q + 4 * i);
;             v[4 * i] = (fkey(sv4.x) & ~127u) | (unsigned)ib; v[4 * i + 1] = (fkey(sv4.y) & ~127u) | (unsigned)(ib - 1);
;             v[4 * i + 2] = (fkey(sv4.z) & ~127u) | (unsigned)(ib - 2); v[4 * i + 3] = (fkey(sv4.w) & ~127u) | (unsigned)(ib - 3);
;         }
	v_not_b32_e32 v31, v13
	v_or_b32_e32 v116, 0x80000000, v13
	v_bitop3_b32 v10, v29, s98, v10 bitop3:0x56
	v_and_b32_e32 v10, 0xffffff80, v10
	v_sub_u32_e32 v10, v10, v182
	v_add_u32_e32 v28, 0x7f, v10
	v_not_b32_e32 v10, v11
	v_or_b32_e32 v29, 0x80000000, v11
	v_cmp_gt_i32_e32 vcc, 0, v11
	v_ashrrev_i32_e32 v11, 31, v12
	v_and_b32_e32 v27, 0xffffff80, v27
	v_cndmask_b32_e32 v10, v29, v10, vcc
	v_and_b32_e32 v10, 0xffffff80, v10
	v_sub_u32_e32 v10, v10, v182
	v_add_u32_e32 v29, 0x7e, v10


; DI unsigned fkey(float f) { const unsigned u = __float_as_uint(f); return (u & 0x80000000u) ? ~u : (u | 0x80000000u); }
; DI void topk_phase(unsigned char* smem_, const bf16_t* __restrict__ qp, const bf16_t* __restrict__ keys, int* __restrict__ eidx, float* __restrict__ gate) {
;     ...
;         for (int i = 0; i < 8; ++i) {
;             const f32x4 sv4 = *(const f32x4*)(S + row * LDS_ + 32 * q + 4 * i);
;             const int ib = 127 - (32 * q + 4 * i);
;             v[4 * i] = (fkey(sv4.x) & ~127u) | (unsigned)ib; v[4 * i + 1] = (fkey(sv4.y) & ~127u) | (unsigned)(ib - 1);
;             v[4 * i + 2] = (fkey(sv4.z) & ~127u) | (unsigned)(ib - 2); v[4 * i + 3] = (fkey(sv4.w) & ~127u) | (unsigned)(ib - 3);
;         }
	v_sub_u32_e32 v27, v27, v181
	v_add_u32_e32 v27, 0x7c, v27
	v_bitop3_b32 v10, v11, s98, v12 bitop3:0x56
	v_and_b32_e32 v10, 0xffffff80, v10
	v_sub_u32_e32 v10, v10, v182
	v_add_u32_e32 v30, 0x7d, v10
	v_cmp_gt_i32_e32 vcc, 0, v13
	ds_read_b128 v[10:13], v171 offset:17520
	s_waitcnt lgkmcnt(0)
	v_ashrrev_i32_e32 v117, 31, v10
	v_cndmask_b32_e32 v31, v116, v31, vcc


; DI unsigned fkey(float f) { const unsigned u = __float_as_uint(f); return (u & 0x80000000u) ? ~u : (u | 0x80000000u); }
; DI void topk_phase(unsigned char* smem_, const bf16_t* __restrict__ qp, const bf16_t* __restrict__ keys, int* __restrict__ eidx, float* __restrict__ gate) {
;     ...
;         for (int i = 0; i < 8; ++i) {
;             const f32x4 sv4 = *(const f32x4*)(S + row * LDS_ + 32 * q + 4 * i);
;             const int ib = 127 - (32 * q + 4 * i);
;             v[4 * i] = (fkey(sv4.x) & ~127u) | (unsigned)ib; v[4 * i + 1] = (fkey(sv4.y) & ~127u) | (unsigned)(ib - 1);
;             v[4 * i + 2] = (fkey(sv4.z) & ~127u) | (unsigned)(ib - 2); v[4 * i + 3] = (fkey(sv4.w) & ~127u) | (unsigned)(ib - 3);
;         }
	v_and_b32_e32 v31, 0xffffff80, v31
	v_sub_u32_e32 v31, v31, v182
	v_bitop3_b32 v10, v117, s98, v10 bitop3:0x56
	v_ashrrev_i32_e32 v116, 31, v11


; DI unsigned fkey(float f) { const unsigned u = __float_as_uint(f); return (u & 0x80000000u) ? ~u : (u | 0x80000000u); }
; DI void topk_phase(unsigned char* smem_, const bf16_t* __restrict__ qp, const bf16_t* __restrict__ keys, int* __restrict__ eidx, float* __restrict__ gate) {
;     ...
;         for (int i = 0; i < 8; ++i) {
;             const f32x4 sv4 = *(const f32x4*)(S + row * LDS_ + 32 * q + 4 * i);
;             const int ib = 127 - (32 * q + 4 * i);
;             v[4 * i] = (fkey(sv4.x) & ~127u) | (unsigned)ib; v[4 * i + 1] = (fkey(sv4.y) & ~127u) | (unsigned)(ib - 1);
;             v[4 * i + 2] = (fkey(sv4.z) & ~127u) | (unsigned)(ib - 2); v[4 * i + 3] = (fkey(sv4.w) & ~127u) | (unsigned)(ib - 3);
;         }
	v_and_b32_e32 v10, 0xffffff80, v10
	v_sub_u32_e32 v10, v10, v183
	v_bitop3_b32 v11, v116, s98, v11 bitop3:0x56
	v_ashrrev_i32_e32 v116, 31, v12


; DI unsigned fkey(float f) { const unsigned u = __float_as_uint(f); return (u & 0x80000000u) ? ~u : (u | 0x80000000u); }
; DI void topk_phase(unsigned char* smem_, const bf16_t* __restrict__ qp, const bf16_t* __restrict__ keys, int* __restrict__ eidx, float* __restrict__ gate) {
;     ...
;         for (int i = 0; i < 8; ++i) {
;             const f32x4 sv4 = *(const f32x4*)(S + row * LDS_ + 32 * q + 4 * i);
;             const int ib = 127 - (32 * q + 4 * i);
;             v[4 * i] = (fkey(sv4.x) & ~127u) | (unsigned)ib; v[4 * i + 1] = (fkey(sv4.y) & ~127u) | (unsigned)(ib - 1);
;             v[4 * i + 2] = (fkey(sv4.z) & ~127u) | (unsigned)(ib - 2); v[4 * i + 3] = (fkey(sv4.w) & ~127u) | (unsigned)(ib - 3);
;         }
	v_and_b32_e32 v11, 0xffffff80, v11
	v_sub_u32_e32 v11, v11, v183
	v_bitop3_b32 v12, v116, s98, v12 bitop3:0x56
	v_ashrrev_i32_e32 v116, 31, v13


; DI unsigned fkey(float f) { const unsigned u = __float_as_uint(f); return (u & 0x80000000u) ? ~u : (u | 0x80000000u); }
; template <int N> DI void bitonic_sort_desc(unsigned (&v)[N]) {
; #pragma unroll
;     for (int k = 2; k <= N; k <<= 1)
; #pragma unroll
;         for (int j = k >> 1; j > 0; j >>= 1)
; #pragma unroll
;             for (int i = 0; i < N; ++i) { const int l = i ^ j; if (l > i) { if ((i & k) == 0) cswap(v[i], v[l]); else cswap(v[l], v[i]); } }
; }
; DI void topk_phase(unsigned char* smem_, const bf16_t* __restrict__ qp, const bf16_t* __restrict__ keys, int* __restrict__ eidx, float* __restrict__ gate) {
;     ...
;         for (int i = 0; i < 8; ++i) {
;             const f32x4 sv4 = *(const f32x4*)(S + row * LDS_ + 32 * q + 4 * i);
;             const int ib = 127 - (32 * q + 4 * i);
;             v[4 * i] = (fkey(sv4.x) & ~127u) | (unsigned)ib; v[4 * i + 1] = (fkey(sv4.y) & ~127u) | (unsigned)(ib - 1);
;             v[4 * i + 2] = (fkey(sv4.z) & ~127u) | (unsigned)(ib - 2); v[4 * i + 3] = (fkey(sv4.w) & ~127u) | (unsigned)(ib - 3);
;         }
	v_and_b32_e32 v12, 0xffffff80, v12
	v_sub_u32_e32 v12, v12, v183
	v_bitop3_b32 v13, v116, s98, v13 bitop3:0x56
	v_and_b32_e32 v13, 0xffffff80, v13
	v_sub_u32_e32 v13, v13, v183
	v_add_u32_e32 v31, 0x7c, v31
	v_add_u32_e32 v10, 0x7f, v10
	v_add_u32_e32 v11, 0x7e, v11
	v_add_u32_e32 v12, 0x7d, v12
	v_add_u32_e32 v13, 0x7c, v13
	v_max_u32_e32 v116, v0, v1
	v_min_u32_e32 v0, v0, v1
	v_max_u32_e32 v1, v3, v2
	v_min_u32_e32 v2, v3, v2
	v_max_u32_e32 v3, v4, v5
	v_min_u32_e32 v4, v4, v5
	v_max_u32_e32 v5, v7, v6
	v_min_u32_e32 v6, v7, v6
	v_max_u32_e32 v7, v8, v9
	v_min_u32_e32 v8, v8, v9
	v_max_u32_e32 v9, v17, v16
	v_min_u32_e32 v16, v17, v16
	v_max_u32_e32 v17, v18, v19
	v_min_u32_e32 v18, v18, v19
	v_max_u32_e32 v19, v15, v14
	v_min_u32_e32 v14, v15, v14
	v_max_u32_e32 v15, v20, v21
	v_min_u32_e32 v20, v20, v21
	v_max_u32_e32 v21, v23, v22
	v_min_u32_e32 v22, v23, v22
	v_max_u32_e32 v23, v24, v25
	v_min_u32_e32 v24, v24, v25
	v_max_u32_e32 v25, v27, v26
	v_min_u32_e32 v26, v27, v26
	v_max_u32_e32 v27, v28, v29
	v_min_u32_e32 v28, v28, v29
	v_max_u32_e32 v29, v31, v30
	v_min_u32_e32 v30, v31, v30
	v_max_u32_e32 v31, v10, v11
	v_min_u32_e32 v10, v10, v11
	v_max_u32_e32 v11, v13, v12
	v_min_u32_e32 v12, v13, v12
	v_max_u32_e32 v13, v116, v2
	v_min_u32_e32 v2, v116, v2
	v_max_u32_e32 v116, v0, v1
	v_min_u32_e32 v0, v0, v1
	v_max_u32_e32 v1, v6, v3
	v_min_u32_e32 v3, v6, v3
	v_max_u32_e32 v6, v5, v4
	v_min_u32_e32 v4, v5, v4
	v_max_u32_e32 v5, v7, v16
	v_min_u32_e32 v7, v7, v16
	v_max_u32_e32 v16, v8, v9
	v_min_u32_e32 v8, v8, v9
	v_max_u32_e32 v9, v14, v17
	v_min_u32_e32 v14, v14, v17
	v_max_u32_e32 v17, v19, v18
	v_min_u32_e32 v18, v19, v18
	v_max_u32_e32 v19, v15, v22
	v_min_u32_e32 v15, v15, v22
	v_max_u32_e32 v22, v20, v21
	v_min_u32_e32 v20, v20, v21
	v_max_u32_e32 v21, v26, v23
	v_min_u32_e32 v23, v26, v23
	v_max_u32_e32 v26, v25, v24
	v_min_u32_e32 v24, v25, v24
	v_max_u32_e32 v25, v27, v30
	v_min_u32_e32 v27, v27, v30
	v_max_u32_e32 v30, v28, v29
	v_min_u32_e32 v28, v28, v29
	v_max_u32_e32 v29, v12, v31
	v_min_u32_e32 v12, v12, v31
	v_max_u32_e32 v31, v11, v10
	v_min_u32_e32 v10, v11, v10
	v_max_u32_e32 v11, v13, v116
	v_min_u32_e32 v13, v13, v116
	v_max_u32_e32 v116, v2, v0
	v_min_u32_e32 v0, v2, v0
	v_max_u32_e32 v2, v4, v3
	v_min_u32_e32 v3, v4, v3
	v_max_u32_e32 v4, v6, v1
	v_min_u32_e32 v1, v6, v1
	v_max_u32_e32 v6, v5, v16
	v_min_u32_e32 v5, v5, v16
	v_max_u32_e32 v16, v7, v8
	v_min_u32_e32 v7, v7, v8
	v_max_u32_e32 v8, v18, v14
	v_min_u32_e32 v14, v18, v14
	v_max_u32_e32 v18, v17, v9
	v_min_u32_e32 v9, v17, v9
	v_max_u32_e32 v17, v19, v22
	v_min_u32_e32 v19, v19, v22
	v_max_u32_e32 v22, v15, v20
	v_min_u32_e32 v15, v15, v20
	v_max_u32_e32 v20, v24, v23
	v_min_u32_e32 v23, v24, v23
	v_max_u32_e32 v24, v26, v21
	v_min_u32_e32 v21, v26, v21
	v_max_u32_e32 v26, v25, v30
	v_min_u32_e32 v25, v25, v30
	v_max_u32_e32 v30, v27, v28
	v_min_u32_e32 v27, v27, v28
	v_max_u32_e32 v28, v10, v12
	v_min_u32_e32 v10, v10, v12
	v_max_u32_e32 v12, v31, v29
	v_min_u32_e32 v29, v31, v29
	v_max_u32_e32 v31, v11, v3
	v_min_u32_e32 v3, v11, v3
	v_max_u32_e32 v11, v13, v2
	v_min_u32_e32 v2, v13, v2
	v_max_u32_e32 v13, v116, v1
	v_min_u32_e32 v1, v116, v1
	v_max_u32_e32 v116, v0, v4
	v_min_u32_e32 v0, v0, v4
	v_max_u32_e32 v4, v14, v6
	v_min_u32_e32 v6, v14, v6
	v_max_u32_e32 v14, v8, v5
	v_min_u32_e32 v5, v8, v5
	v_max_u32_e32 v8, v9, v16
	v_min_u32_e32 v9, v9, v16
	v_max_u32_e32 v16, v18, v7
	v_min_u32_e32 v7, v18, v7
	v_max_u32_e32 v18, v17, v23
	v_min_u32_e32 v17, v17, v23
	v_max_u32_e32 v23, v19, v20
	v_min_u32_e32 v19, v19, v20
	v_max_u32_e32 v20, v22, v21
	v_min_u32_e32 v21, v22, v21
	v_max_u32_e32 v22, v15, v24
	v_min_u32_e32 v15, v15, v24
	v_max_u32_e32 v24, v10, v26
	v_min_u32_e32 v10, v10, v26
	v_max_u32_e32 v26, v28, v25
	v_min_u32_e32 v25, v28, v25
	v_max_u32_e32 v28, v29, v30
	v_min_u32_e32 v29, v29, v30
	v_max_u32_e32 v30, v12, v27
	v_min_u32_e32 v12, v12, v27
	v_max_u32_e32 v27, v31, v13
	v_min_u32_e32 v13, v31, v13
	v_max_u32_e32 v31, v11, v116
	v_min_u32_e32 v11, v11, v116
	v_max_u32_e32 v116, v3, v1
	v_min_u32_e32 v1, v3, v1
	v_max_u32_e32 v3, v2, v0
	v_min_u32_e32 v0, v2, v0
	v_max_u32_e32 v2, v9, v6
	v_min_u32_e32 v6, v9, v6
	v_max_u32_e32 v9, v7, v5
	v_min_u32_e32 v5, v7, v5
	v_max_u32_e32 v7, v8, v4
	v_min_u32_e32 v4, v8, v4
	v_max_u32_e32 v8, v16, v14
	v_min_u32_e32 v14, v16, v14
	v_max_u32_e32 v16, v18, v20
	v_min_u32_e32 v18, v18, v20
	v_max_u32_e32 v20, v23, v22
	v_min_u32_e32 v22, v23, v22
	v_max_u32_e32 v23, v17, v21
	v_min_u32_e32 v17, v17, v21
	v_max_u32_e32 v21, v19, v15
	v_min_u32_e32 v15, v19, v15
	v_max_u32_e32 v19, v29, v10
	v_min_u32_e32 v10, v29, v10
	v_max_u32_e32 v29, v12, v25
	v_min_u32_e32 v12, v12, v25
	v_max_u32_e32 v25, v28, v24
	v_min_u32_e32 v24, v28, v24
	v_max_u32_e32 v28, v30, v26
	v_min_u32_e32 v26, v30, v26
	v_max_u32_e32 v30, v27, v31
	v_min_u32_e32 v27, v27, v31
	v_max_u32_e32 v31, v13, v11
	v_min_u32_e32 v11, v13, v11
	v_max_u32_e32 v13, v116, v3
	v_min_u32_e32 v3, v116, v3
	v_max_u32_e32 v116, v1, v0
	v_min_u32_e32 v0, v1, v0
	v_max_u32_e32 v1, v5, v6
	v_min_u32_e32 v5, v5, v6
	v_max_u32_e32 v6, v9, v2
	v_min_u32_e32 v2, v9, v2
	v_max_u32_e32 v9, v14, v4
	v_min_u32_e32 v4, v14, v4
	v_max_u32_e32 v14, v8, v7
	v_min_u32_e32 v7, v8, v7
	v_max_u32_e32 v8, v16, v20
	v_min_u32_e32 v16, v16, v20
	v_max_u32_e32 v20, v18, v22
	v_min_u32_e32 v18, v18, v22
	v_max_u32_e32 v22, v23, v21
	v_min_u32_e32 v21, v23, v21
	v_max_u32_e32 v23, v17, v15
	v_min_u32_e32 v15, v17, v15
	v_max_u32_e32 v17, v12, v10
	v_min_u32_e32 v10, v12, v10
	v_max_u32_e32 v12, v29, v19
	v_min_u32_e32 v19, v29, v19
	v_max_u32_e32 v29, v26, v24
; template <int N> DI void bitonic_sort_desc(unsigned (&v)[N]) {
; #pragma unroll
;     for (int k = 2; k <= N; k <<= 1)
; #pragma unroll
;         for (int j = k >> 1; j > 0; j >>= 1)
; #pragma unroll
;             for (int i = 0; i < N; ++i) { const int l = i ^ j; if (l > i) { if ((i & k) == 0) cswap(v[i], v[l]); else cswap(v[l], v[i]); } }
; }
; DI void merge_top16(unsigned (&v)[16], int st) {
;     unsigned x[16];
; #pragma unroll
;     for (int i = 0; i < 16; ++i) x[i] = (unsigned)__shfl_xor((int)v[15 - i], st);
; #pragma unroll
;     for (int i = 0; i < 16; ++i) v[i] = max(v[i], x[i]);
; #pragma unroll
;     for (int j = 8; j > 0; j >>= 1)
; #pragma unroll
;         for (int i = 0; i < 16; ++i) { const int l = i ^ j; if (l > i) cswap(v[i], v[l]); }
; }
; DI void topk_phase(unsigned char* smem_, const bf16_t* __restrict__ qp, const bf16_t* __restrict__ keys, int* __restrict__ eidx, float* __restrict__ gate) {
;     ...
;         bitonic_sort_desc<32>(v);
;         unsigned t16[16];
; #pragma unroll
;         for (int i = 0; i < 16; ++i) t16[i] = v[i];
;         merge_top16(t16, 1);
	v_min_u32_e32 v24, v26, v24
	v_max_u32_e32 v26, v28, v25
	v_min_u32_e32 v25, v28, v25
	v_max_u32_e32 v28, v30, v5
	v_min_u32_e32 v5, v30, v5
	v_max_u32_e32 v30, v27, v1
	v_min_u32_e32 v1, v27, v1
	v_max_u32_e32 v27, v31, v2
	v_min_u32_e32 v2, v31, v2
	v_max_u32_e32 v31, v11, v6
	v_min_u32_e32 v6, v11, v6
	v_max_u32_e32 v11, v13, v4
	v_min_u32_e32 v4, v13, v4
	v_max_u32_e32 v13, v3, v9
	v_min_u32_e32 v3, v3, v9
	v_max_u32_e32 v9, v116, v7
	v_min_u32_e32 v7, v116, v7
	v_max_u32_e32 v116, v0, v14
	v_min_u32_e32 v0, v0, v14
	v_max_u32_e32 v14, v10, v8
	v_min_u32_e32 v8, v10, v8
	v_max_u32_e32 v10, v17, v16
	v_min_u32_e32 v16, v17, v16
	v_max_u32_e32 v17, v19, v20
	v_min_u32_e32 v19, v19, v20
	v_max_u32_e32 v20, v12, v18
	v_min_u32_e32 v12, v12, v18
	v_max_u32_e32 v18, v24, v22
	v_min_u32_e32 v22, v24, v22
	v_max_u32_e32 v24, v29, v21
	v_min_u32_e32 v21, v29, v21
	v_max_u32_e32 v29, v25, v23
	v_min_u32_e32 v23, v25, v23
	v_max_u32_e32 v25, v26, v15
	v_min_u32_e32 v15, v26, v15
	v_max_u32_e32 v26, v28, v11
	v_min_u32_e32 v11, v28, v11
	v_max_u32_e32 v28, v30, v13
	v_min_u32_e32 v13, v30, v13
	v_max_u32_e32 v30, v27, v9
	v_min_u32_e32 v9, v27, v9
	v_max_u32_e32 v27, v31, v116
	v_min_u32_e32 v31, v31, v116
	v_max_u32_e32 v116, v5, v4
	v_min_u32_e32 v4, v5, v4
	v_max_u32_e32 v5, v1, v3
	v_min_u32_e32 v1, v1, v3
	v_max_u32_e32 v3, v2, v7
	v_min_u32_e32 v2, v2, v7
	v_max_u32_e32 v7, v6, v0
	v_min_u32_e32 v0, v6, v0
	v_max_u32_e32 v6, v22, v8
	v_min_u32_e32 v8, v22, v8
	v_max_u32_e32 v22, v21, v16
	v_min_u32_e32 v16, v21, v16
	v_max_u32_e32 v21, v23, v19
	v_min_u32_e32 v19, v23, v19
	v_max_u32_e32 v23, v15, v12
	v_min_u32_e32 v12, v15, v12
	v_max_u32_e32 v15, v18, v14
	v_min_u32_e32 v14, v18, v14
	v_max_u32_e32 v18, v24, v10
	v_min_u32_e32 v10, v24, v10
	v_max_u32_e32 v24, v29, v17
	v_min_u32_e32 v17, v29, v17
	v_max_u32_e32 v29, v25, v20
	v_min_u32_e32 v20, v25, v20
	v_max_u32_e32 v25, v26, v30
	v_min_u32_e32 v26, v26, v30
	v_max_u32_e32 v30, v28, v27
	v_min_u32_e32 v27, v28, v27
	v_max_u32_e32 v28, v11, v9
	v_min_u32_e32 v9, v11, v9
	v_max_u32_e32 v11, v13, v31
	v_min_u32_e32 v13, v13, v31
	v_max_u32_e32 v31, v116, v3
	v_min_u32_e32 v3, v116, v3
	v_max_u32_e32 v116, v5, v7
	v_min_u32_e32 v5, v5, v7
	v_max_u32_e32 v7, v4, v2
	v_min_u32_e32 v2, v4, v2
	v_max_u32_e32 v4, v1, v0
	v_min_u32_e32 v0, v1, v0
	v_max_u32_e32 v1, v19, v8
	v_min_u32_e32 v8, v19, v8
	v_max_u32_e32 v19, v12, v16
	v_min_u32_e32 v12, v12, v16
	v_max_u32_e32 v16, v21, v6
	v_min_u32_e32 v6, v21, v6
	v_max_u32_e32 v21, v23, v22
	v_min_u32_e32 v22, v23, v22
	v_max_u32_e32 v23, v17, v14
	v_min_u32_e32 v14, v17, v14
	v_max_u32_e32 v17, v20, v10
	v_min_u32_e32 v10, v20, v10
	v_max_u32_e32 v20, v24, v15
	v_min_u32_e32 v15, v24, v15
	v_max_u32_e32 v24, v29, v18
	v_min_u32_e32 v18, v29, v18
	v_min_u32_e32 v29, v25, v30
	v_min_u32_e32 v117, v26, v27
	v_min_u32_e32 v118, v28, v11
	v_min_u32_e32 v119, v9, v13
	v_min_u32_e32 v120, v31, v116
	v_min_u32_e32 v121, v3, v5
	v_min_u32_e32 v122, v7, v4
	v_min_u32_e32 v123, v2, v0
	v_min_u32_e32 v124, v12, v8
	v_min_u32_e32 v125, v19, v1
	v_min_u32_e32 v126, v22, v6
	v_min_u32_e32 v127, v21, v16
	v_min_u32_e32 v142, v10, v14
	v_min_u32_e32 v143, v17, v23
	v_min_u32_e32 v144, v18, v15
	v_min_u32_e32 v145, v24, v20
	v_max3_u32 v25, v25, v30, v124
	v_max3_u32 v8, v29, v12, v8
	v_max3_u32 v12, v26, v27, v125
	v_max3_u32 v1, v117, v19, v1
	v_max3_u32 v11, v28, v11, v126
	v_max3_u32 v6, v118, v22, v6
	v_max3_u32 v9, v9, v13, v127
	v_max3_u32 v13, v119, v21, v16
	v_max3_u32 v16, v31, v116, v142
	v_max3_u32 v10, v120, v10, v14
	v_max3_u32 v3, v3, v5, v143
	v_max3_u32 v5, v121, v17, v23
	v_max3_u32 v4, v7, v4, v144
	v_max3_u32 v7, v122, v18, v15
	v_max3_u32 v0, v2, v0, v145
	v_max3_u32 v2, v123, v24, v20
	v_max_u32_e32 v14, v25, v16
	v_min_u32_e32 v15, v25, v16
	v_max_u32_e32 v16, v8, v10
	v_min_u32_e32 v8, v8, v10
	v_max_u32_e32 v10, v12, v3
	v_min_u32_e32 v3, v12, v3
	v_max_u32_e32 v12, v1, v5
	v_min_u32_e32 v1, v1, v5
	v_max_u32_e32 v5, v11, v4
	v_min_u32_e32 v4, v11, v4
	v_max_u32_e32 v11, v6, v7
	v_min_u32_e32 v6, v6, v7
	v_max_u32_e32 v7, v9, v0
	v_min_u32_e32 v0, v9, v0
	v_max_u32_e32 v9, v13, v2
	v_min_u32_e32 v2, v13, v2
	v_max_u32_e32 v13, v14, v5
	v_min_u32_e32 v5, v14, v5
	v_max_u32_e32 v14, v16, v11
	v_min_u32_e32 v11, v16, v11
	v_max_u32_e32 v16, v10, v7
	v_min_u32_e32 v7, v10, v7
	v_max_u32_e32 v10, v12, v9
	v_min_u32_e32 v9, v12, v9
	v_max_u32_e32 v12, v15, v4
	v_min_u32_e32 v4, v15, v4
	v_max_u32_e32 v15, v8, v6
	v_min_u32_e32 v6, v8, v6
	v_max_u32_e32 v8, v3, v0
	v_min_u32_e32 v0, v3, v0
	v_max_u32_e32 v3, v1, v2
	v_min_u32_e32 v1, v1, v2
	v_max_u32_e32 v2, v13, v16
	v_min_u32_e32 v13, v13, v16
	v_max_u32_e32 v16, v14, v10
	v_min_u32_e32 v10, v14, v10
	v_max_u32_e32 v14, v5, v7
	v_min_u32_e32 v5, v5, v7
	v_max_u32_e32 v7, v11, v9
	v_min_u32_e32 v9, v11, v9
	v_max_u32_e32 v11, v12, v8
	v_min_u32_e32 v8, v12, v8
	v_max_u32_e32 v12, v15, v3
	v_min_u32_e32 v3, v15, v3
	v_max_u32_e32 v15, v4, v0
	v_min_u32_e32 v0, v4, v0
	v_max_u32_e32 v4, v6, v1
	v_min_u32_e32 v1, v6, v1
	v_max_u32_e32 v6, v2, v16
	v_min_u32_e32 v2, v2, v16
	v_max_u32_e32 v16, v13, v10
	v_min_u32_e32 v10, v13, v10
	v_max_u32_e32 v13, v14, v7
	v_min_u32_e32 v7, v14, v7
	v_max_u32_e32 v14, v5, v9
	v_min_u32_e32 v5, v5, v9
	v_max_u32_e32 v9, v11, v12
	v_min_u32_e32 v11, v11, v12
	v_max_u32_e32 v12, v8, v3
	v_min_u32_e32 v3, v8, v3
	v_max_u32_e32 v8, v15, v4
	v_min_u32_e32 v4, v15, v4
	v_max_u32_e32 v15, v0, v1
	v_min_u32_e32 v0, v0, v1
	s_nop 1
	v_mov_b32_dpp v1, v0 quad_perm:[1,0,3,2] row_mask:0xf bank_mask:0xf
	v_mov_b32_dpp v17, v15 quad_perm:[1,0,3,2] row_mask:0xf bank_mask:0xf
	v_mov_b32_dpp v18, v4 quad_perm:[1,0,3,2] row_mask:0xf bank_mask:0xf
	v_mov_b32_dpp v19, v8 quad_perm:[1,0,3,2] row_mask:0xf bank_mask:0xf
	v_mov_b32_dpp v20, v3 quad_perm:[1,0,3,2] row_mask:0xf bank_mask:0xf
	v_mov_b32_dpp v21, v12 quad_perm:[1,0,3,2] row_mask:0xf bank_mask:0xf
	v_mov_b32_dpp v22, v11 quad_perm:[1,0,3,2] row_mask:0xf bank_mask:0xf
	v_mov_b32_dpp v23, v9 quad_perm:[1,0,3,2] row_mask:0xf bank_mask:0xf
	v_mov_b32_dpp v24, v5 quad_perm:[1,0,3,2] row_mask:0xf bank_mask:0xf
	v_mov_b32_dpp v25, v14 quad_perm:[1,0,3,2] row_mask:0xf bank_mask:0xf
	v_mov_b32_dpp v26, v7 quad_perm:[1,0,3,2] row_mask:0xf bank_mask:0xf
	v_mov_b32_dpp v27, v13 quad_perm:[1,0,3,2] row_mask:0xf bank_mask:0xf
	v_mov_b32_dpp v28, v10 quad_perm:[1,0,3,2] row_mask:0xf bank_mask:0xf
	v_mov_b32_dpp v29, v16 quad_perm:[1,0,3,2] row_mask:0xf bank_mask:0xf
	v_mov_b32_dpp v30, v2 quad_perm:[1,0,3,2] row_mask:0xf bank_mask:0xf
	v_mov_b32_dpp v31, v6 quad_perm:[1,0,3,2] row_mask:0xf bank_mask:0xf
	s_waitcnt lgkmcnt(0)
; DI void merge_top16(unsigned (&v)[16], int st) {
;     unsigned x[16];
; #pragma unroll
;     for (int i = 0; i < 16; ++i) x[i] = (unsigned)__shfl_xor((int)v[15 - i], st);
; #pragma unroll
;     for (int i = 0; i < 16; ++i) v[i] = max(v[i], x[i]);
; #pragma unroll
;     for (int j = 8; j > 0; j >>= 1)
; #pragma unroll
;         for (int i = 0; i < 16; ++i) { const int l = i ^ j; if (l > i) cswap(v[i], v[l]); }
; }
; DI void topk_phase(unsigned char* smem_, const bf16_t* __restrict__ qp, const bf16_t* __restrict__ keys, int* __restrict__ eidx, float* __restrict__ gate) {
;     ...
;         merge_top16(t16, 2);
; #pragma unroll
;         for (int i = 0; i < 16; ++i) if ((i >> 2) == q) { const int idx = 127 - (int)(t16[i] & 127u); SI[row * 32 + 16 * p + i] = idx; SV[row * 32 + 16 * p + i] = S[row * LDS_ + idx]; }
	v_max_u32_e32 v1, v6, v1
	v_max_u32_e32 v2, v2, v17
	v_max_u32_e32 v6, v16, v18
	v_max_u32_e32 v10, v10, v19
	v_max_u32_e32 v13, v13, v20
	v_max_u32_e32 v7, v7, v21
	v_max_u32_e32 v14, v14, v22
	v_max_u32_e32 v5, v5, v23
	v_max_u32_e32 v9, v9, v24
	v_max_u32_e32 v11, v11, v25
	v_max_u32_e32 v12, v12, v26
	v_max_u32_e32 v3, v3, v27
	v_max_u32_e32 v8, v8, v28
	v_max_u32_e32 v4, v4, v29
	v_max_u32_e32 v15, v15, v30
	v_max_u32_e32 v0, v0, v31
	v_max_u32_e32 v16, v1, v9
	v_min_u32_e32 v1, v1, v9
	v_max_u32_e32 v9, v2, v11
	v_min_u32_e32 v2, v2, v11
	v_max_u32_e32 v11, v6, v12
	v_min_u32_e32 v6, v6, v12
	v_max_u32_e32 v12, v10, v3
	v_min_u32_e32 v3, v10, v3
	v_max_u32_e32 v10, v13, v8
	v_min_u32_e32 v8, v13, v8
	v_max_u32_e32 v13, v7, v4
	v_min_u32_e32 v4, v7, v4
	v_max_u32_e32 v7, v14, v15
	v_min_u32_e32 v14, v14, v15
	v_max_u32_e32 v15, v5, v0
	v_min_u32_e32 v0, v5, v0
	v_max_u32_e32 v5, v16, v10
	v_min_u32_e32 v10, v16, v10
	v_max_u32_e32 v16, v9, v13
	v_min_u32_e32 v9, v9, v13
	v_max_u32_e32 v13, v11, v7
	v_min_u32_e32 v7, v11, v7
	v_max_u32_e32 v11, v12, v15
	v_min_u32_e32 v12, v12, v15
	v_max_u32_e32 v15, v1, v8
	v_min_u32_e32 v1, v1, v8
	v_max_u32_e32 v8, v2, v4
	v_min_u32_e32 v2, v2, v4
	v_max_u32_e32 v4, v6, v14
	v_min_u32_e32 v6, v6, v14
	v_max_u32_e32 v14, v3, v0
	v_min_u32_e32 v0, v3, v0
	v_max_u32_e32 v3, v5, v13
	v_min_u32_e32 v5, v5, v13
	v_max_u32_e32 v13, v16, v11
	v_min_u32_e32 v11, v16, v11
	v_max_u32_e32 v16, v10, v7
	v_min_u32_e32 v7, v10, v7
	v_max_u32_e32 v10, v9, v12
	v_min_u32_e32 v9, v9, v12
	v_max_u32_e32 v12, v15, v4
	v_min_u32_e32 v4, v15, v4
	v_max_u32_e32 v15, v8, v14
	v_min_u32_e32 v8, v8, v14
	v_max_u32_e32 v14, v1, v6
	v_min_u32_e32 v1, v1, v6
	v_max_u32_e32 v6, v2, v0
	v_min_u32_e32 v0, v2, v0
	v_max_u32_e32 v2, v3, v13
	v_min_u32_e32 v3, v3, v13
	v_max_u32_e32 v13, v5, v11
	v_min_u32_e32 v5, v5, v11
	v_max_u32_e32 v11, v16, v10
	v_min_u32_e32 v10, v16, v10
	v_max_u32_e32 v16, v7, v9
	v_min_u32_e32 v7, v7, v9
	v_max_u32_e32 v9, v12, v15
	v_min_u32_e32 v12, v12, v15
	v_max_u32_e32 v15, v4, v8
	v_min_u32_e32 v17, v4, v8
	v_max_u32_e32 v18, v14, v6
	v_min_u32_e32 v14, v14, v6
	v_max_u32_e32 v19, v1, v0
	v_min_u32_e32 v20, v1, v0
	s_nop 1
	v_mov_b32_dpp v0, v20 quad_perm:[2,3,0,1] row_mask:0xf bank_mask:0xf
	v_mov_b32_dpp v1, v19 quad_perm:[2,3,0,1] row_mask:0xf bank_mask:0xf
	v_mov_b32_dpp v4, v14 quad_perm:[2,3,0,1] row_mask:0xf bank_mask:0xf
	v_mov_b32_dpp v6, v18 quad_perm:[2,3,0,1] row_mask:0xf bank_mask:0xf
	v_mov_b32_dpp v8, v17 quad_perm:[2,3,0,1] row_mask:0xf bank_mask:0xf
	v_mov_b32_dpp v21, v15 quad_perm:[2,3,0,1] row_mask:0xf bank_mask:0xf
	v_mov_b32_dpp v22, v12 quad_perm:[2,3,0,1] row_mask:0xf bank_mask:0xf
	v_mov_b32_dpp v23, v9 quad_perm:[2,3,0,1] row_mask:0xf bank_mask:0xf
	v_mov_b32_dpp v24, v7 quad_perm:[2,3,0,1] row_mask:0xf bank_mask:0xf
	v_mov_b32_dpp v25, v16 quad_perm:[2,3,0,1] row_mask:0xf bank_mask:0xf
	v_mov_b32_dpp v26, v10 quad_perm:[2,3,0,1] row_mask:0xf bank_mask:0xf
	v_mov_b32_dpp v27, v11 quad_perm:[2,3,0,1] row_mask:0xf bank_mask:0xf
	v_mov_b32_dpp v28, v5 quad_perm:[2,3,0,1] row_mask:0xf bank_mask:0xf
	v_mov_b32_dpp v29, v13 quad_perm:[2,3,0,1] row_mask:0xf bank_mask:0xf
	v_mov_b32_dpp v30, v3 quad_perm:[2,3,0,1] row_mask:0xf bank_mask:0xf
	v_mov_b32_dpp v31, v2 quad_perm:[2,3,0,1] row_mask:0xf bank_mask:0xf
	s_waitcnt lgkmcnt(0)
	v_max_u32_e32 v0, v2, v0
	v_max_u32_e32 v1, v3, v1
	v_max_u32_e32 v2, v13, v4
	v_max_u32_e32 v3, v5, v6
	v_max_u32_e32 v4, v11, v8
	v_max_u32_e32 v5, v10, v21
	v_max_u32_e32 v6, v16, v22
	v_max_u32_e32 v7, v7, v23
	v_max_u32_e32 v8, v9, v24
	v_max_u32_e32 v9, v12, v25
	v_max_u32_e32 v10, v15, v26
	v_max_u32_e32 v11, v17, v27
	v_max_u32_e32 v12, v18, v28
	v_max_u32_e32 v13, v14, v29
	v_max_u32_e32 v14, v19, v30
	v_max_u32_e32 v15, v20, v31
	v_max_u32_e32 v16, v0, v8
	v_max_u32_e32 v17, v1, v9
	v_max_u32_e32 v18, v2, v10
	v_max_u32_e32 v19, v3, v11
	v_max_u32_e32 v20, v4, v12
	v_max_u32_e32 v21, v5, v13
	v_max_u32_e32 v22, v6, v14
	v_max_u32_e32 v23, v7, v15
	s_or_b64 s[0:1], s[4:5], s[6:7]
	s_or_b64 vcc, s[6:7], s[10:11]
	v_min_u32_e32 v0, v0, v8
	v_min_u32_e32 v1, v1, v9
	v_min_u32_e32 v2, v2, v10
	v_min_u32_e32 v3, v3, v11
	v_min_u32_e32 v4, v4, v12
	v_min_u32_e32 v5, v5, v13
	v_min_u32_e32 v6, v6, v14
	v_min_u32_e32 v7, v7, v15
	v_add_u32_e32 v116, 0xf000, v184
	v_cndmask_b32_e64 v0, v0, v16, s[0:1]
	v_cndmask_b32_e64 v1, v1, v17, s[0:1]
	v_cndmask_b32_e64 v2, v2, v18, s[0:1]
	v_cndmask_b32_e64 v3, v3, v19, s[0:1]
	v_cndmask_b32_e64 v4, v4, v20, s[0:1]
	v_cndmask_b32_e64 v5, v5, v21, s[0:1]
	v_cndmask_b32_e64 v6, v6, v22, s[0:1]
	v_cndmask_b32_e64 v7, v7, v23, s[0:1]
	v_max_u32_e32 v8, v0, v4
	v_max_u32_e32 v9, v1, v5
	v_max_u32_e32 v10, v2, v6
	v_max_u32_e32 v11, v3, v7
	v_min_u32_e32 v12, v0, v4
	v_min_u32_e32 v13, v1, v5
	v_min_u32_e32 v14, v2, v6
	v_min_u32_e32 v15, v3, v7
	v_cndmask_b32_e32 v0, v8, v12, vcc
	v_cndmask_b32_e32 v1, v9, v13, vcc
	v_cndmask_b32_e32 v2, v10, v14, vcc
	v_cndmask_b32_e32 v3, v11, v15, vcc
	v_max_u32_e32 v4, v0, v2
	v_min_u32_e32 v5, v0, v2
	v_max_u32_e32 v6, v1, v3
	v_min_u32_e32 v7, v1, v3
	v_max_u32_e32 v0, v4, v6
	v_min_u32_e32 v1, v4, v6
	v_max_u32_e32 v2, v5, v7
	v_min_u32_e32 v3, v5, v7
	v_xor_b32_e32 v0, -1, v0
	v_xor_b32_e32 v1, -1, v1
	v_xor_b32_e32 v2, -1, v2
	v_xor_b32_e32 v3, -1, v3
	v_and_b32_e32 v0, 0x7f, v0
	v_and_b32_e32 v1, 0x7f, v1
	v_and_b32_e32 v2, 0x7f, v2
	v_and_b32_e32 v3, 0x7f, v3
	v_lshl_add_u32 v4, v0, 2, v169
	v_lshl_add_u32 v5, v1, 2, v169
	v_lshl_add_u32 v6, v2, 2, v169
	v_lshl_add_u32 v7, v3, 2, v169
	ds_read_b32 v4, v4 offset:17408
	ds_read_b32 v5, v5 offset:17408
	ds_read_b32 v6, v6 offset:17408
	ds_read_b32 v7, v7 offset:17408
	ds_write_b128 v253, v[0:3] offset:61440
	s_waitcnt lgkmcnt(1)
	ds_write_b128 v253, v[4:7] offset:53248
	s_waitcnt vmcnt(3)
	ds_write_b128 v234, v[96:99]
	s_waitcnt vmcnt(2)
	ds_write_b128 v234, v[100:103] offset:4352
	s_waitcnt vmcnt(1)
	ds_write_b128 v234, v[104:107] offset:8704
	s_waitcnt vmcnt(0)
	ds_write_b128 v234, v[108:111] offset:13056
	s_waitcnt lgkmcnt(0)
	s_barrier
; #define MFMA32(a, b, c) __builtin_amdgcn_mfma_f32_32x32x16_bf16((a), (b), (c), 0, 0, 0)
; #define TK_PREFETCH(t_, p_) do { const int tk0_ = ((t_) >> 3) * 64, hp_ = ((t_) & 7) * 2 + (p_); \
;         _Pragma("unroll") for (int i_ = 0; i_ < 4; ++i_) { const int c_ = tid + 256 * i_; pre[i_] = *(const u32x4*)(qp + (size_t)(tk0_ + (c_ >> 4)) * 2048 + hp_ * 128 + (c_ & 15) * 8); } } while (0)
; DI void topk_phase(unsigned char* smem_, const bf16_t* __restrict__ qp, const bf16_t* __restrict__ keys, int* __restrict__ eidx, float* __restrict__ gate) {
;     ...
;         for (int ks = 0; ks < 8; ++ks) {
; #pragma unroll
;             for (int th = 0; th < 2; ++th) { const bf16x8 qf = *(const bf16x8*)(As + (32 * th + l31) * LDA + ks * 16 + hi * 8); acc[th] = MFMA32(kf[p][ks], qf, acc[th]); }
;         }
; #pragma unroll
;         for (int th = 0; th < 2; ++th)
; #pragma unroll
;             for (int g = 0; g < 4; ++g) { f32x4 o; o.x = acc[th][4 * g]; o.y = acc[th][4 * g + 1]; o.z = acc[th][4 * g + 2]; o.w = acc[th][4 * g + 3]; *(f32x4*)(S + (32 * th + l31) * LDS_ + 32 * wid + 8 * g + 4 * hi) = o; }
;         __syncthreads();
;         if (p == 0) TK_PREFETCH(t, 1); else if (t + G < NT) TK_PREFETCH(t + G, 0);
	ds_read_b128 v[0:3], v235
	ds_read_b128 v[118:121], v235 offset:32
	s_waitcnt lgkmcnt(1)
	v_mfma_f32_32x32x16_bf16 v[16:31], v[64:67], v[0:3], 0
	ds_read_b128 v[0:3], v235 offset:8704
	s_add_i32 s18, s18, s82
	s_cmpk_gt_i32 s18, 0xfff
	s_cselect_b64 s[0:1], -1, 0
	v_readlane_b32 s16, v251, 51
	s_add_i32 s22, s16, s22
	s_and_b64 vcc, exec, s[0:1]
	s_waitcnt lgkmcnt(1)
	v_mfma_f32_32x32x16_bf16 v[16:31], v[68:71], v[118:121], v[16:31]
	ds_read_b128 v[118:121], v235 offset:8736
	s_waitcnt lgkmcnt(1)
	v_mfma_f32_32x32x16_bf16 v[0:15], v[64:67], v[0:3], 0
	s_waitcnt lgkmcnt(0)
	v_mfma_f32_32x32x16_bf16 v[0:15], v[68:71], v[118:121], v[0:15]
	ds_read_b128 v[130:133], v235 offset:64
	ds_read_b128 v[134:137], v235 offset:8768
	ds_read_b128 v[138:141], v235 offset:96
	s_waitcnt lgkmcnt(2)
	v_mfma_f32_32x32x16_bf16 v[16:31], v[72:75], v[130:133], v[16:31]
	ds_read_b128 v[118:121], v235 offset:8800
	s_waitcnt lgkmcnt(2)
	v_mfma_f32_32x32x16_bf16 v[0:15], v[72:75], v[134:137], v[0:15]
	ds_read_b128 v[130:133], v235 offset:128
	s_waitcnt lgkmcnt(2)
	v_mfma_f32_32x32x16_bf16 v[16:31], v[76:79], v[138:141], v[16:31]
	ds_read_b128 v[134:137], v235 offset:8832
	s_waitcnt lgkmcnt(2)
	v_mfma_f32_32x32x16_bf16 v[0:15], v[76:79], v[118:121], v[0:15]
	ds_read_b128 v[138:141], v235 offset:160
	s_waitcnt lgkmcnt(2)
	v_mfma_f32_32x32x16_bf16 v[16:31], v[80:83], v[130:133], v[16:31]
	ds_read_b128 v[118:121], v235 offset:8864
	s_waitcnt lgkmcnt(2)
	v_mfma_f32_32x32x16_bf16 v[0:15], v[80:83], v[134:137], v[0:15]
	ds_read_b128 v[130:133], v235 offset:192
	s_waitcnt lgkmcnt(2)
	v_mfma_f32_32x32x16_bf16 v[16:31], v[84:87], v[138:141], v[16:31]
	ds_read_b128 v[134:137], v235 offset:8896
	s_waitcnt lgkmcnt(2)
	v_mfma_f32_32x32x16_bf16 v[0:15], v[84:87], v[118:121], v[0:15]
	ds_read_b128 v[138:141], v235 offset:224
	s_waitcnt lgkmcnt(2)
	v_mfma_f32_32x32x16_bf16 v[16:31], v[88:91], v[130:133], v[16:31]
	ds_read_b128 v[118:121], v235 offset:8928
	s_waitcnt lgkmcnt(2)
	v_mfma_f32_32x32x16_bf16 v[0:15], v[88:91], v[134:137], v[0:15]
	s_waitcnt lgkmcnt(1)
	v_mfma_f32_32x32x16_bf16 v[16:31], v[92:95], v[138:141], v[16:31]
	s_nop 0
	s_nop 10
	ds_write_b128 v236, v[16:19] offset:17408
	ds_write_b128 v236, v[20:23] offset:17440
	ds_write_b128 v236, v[24:27] offset:17472
	ds_write_b128 v236, v[28:31] offset:17504
	s_waitcnt lgkmcnt(4)
	v_mfma_f32_32x32x16_bf16 v[0:15], v[92:95], v[118:121], v[0:15]
	s_nop 11
	ds_write_b128 v236, v[0:3] offset:34304
	ds_write_b128 v236, v[4:7] offset:34336
	ds_write_b128 v236, v[8:11] offset:34368
	ds_write_b128 v236, v[12:15] offset:34400
	s_waitcnt lgkmcnt(0)
	s_barrier
	s_cbranch_vccnz .LBB0_67
	s_and_b32 s16, s22, 0xffffffc0
	s_and_b32 s17, s21, 0x700
	v_or_b32_e32 v2, s16, v165
	s_lshl_b32 s60, s17, 1
	v_ashrrev_i32_e32 v3, 31, v2
	v_or_b32_e32 v4, s16, v166
	v_lshl_add_u64 v[0:1], v[114:115], 0, s[60:61]
	v_lshlrev_b64 v[2:3], 12, v[2:3]
	v_ashrrev_i32_e32 v5, 31, v4
	v_lshl_add_u64 v[2:3], v[0:1], 0, v[2:3]
	v_lshlrev_b64 v[4:5], 12, v[4:5]
	v_lshl_add_u64 v[4:5], v[0:1], 0, v[4:5]
	global_load_dwordx4 v[96:99], v[2:3], off
	global_load_dwordx4 v[100:103], v[4:5], off
	v_or_b32_e32 v2, s16, v167
	v_ashrrev_i32_e32 v3, 31, v2
	v_or_b32_e32 v4, s16, v168
	v_lshlrev_b64 v[2:3], 12, v[2:3]
	v_ashrrev_i32_e32 v5, 31, v4
	v_lshl_add_u64 v[2:3], v[0:1], 0, v[2:3]
	v_lshlrev_b64 v[4:5], 12, v[4:5]
	v_lshl_add_u64 v[0:1], v[0:1], 0, v[4:5]
	global_load_dwordx4 v[104:107], v[2:3], off
	global_load_dwordx4 v[108:111], v[0:1], off
.LBB0_67:
	ds_read_b128 v[0:3], v171 offset:17408
	ds_read_b128 v[4:7], v171 offset:17424
	ds_read_b128 v[8:11], v171 offset:17440
	ds_read_b128 v[12:15], v171 offset:17456
	s_waitcnt lgkmcnt(3)
	v_ashrrev_i32_e32 v16, 31, v0


; DI unsigned fkey(float f) { const unsigned u = __float_as_uint(f); return (u & 0x80000000u) ? ~u : (u | 0x80000000u); }
; DI void topk_phase(unsigned char* smem_, const bf16_t* __restrict__ qp, const bf16_t* __restrict__ keys, int* __restrict__ eidx, float* __restrict__ gate) {
;     ...
;             const f32x4 sv4 = *(const f32x4*)(S + row * LDS_ + 32 * q + 4 * i);
;             const int ib = 127 - (32 * q + 4 * i);
;             v[4 * i] = (fkey(sv4.x) & ~127u) | (unsigned)ib; v[4 * i + 1] = (fkey(sv4.y) & ~127u) | (unsigned)(ib - 1);
;             v[4 * i + 2] = (fkey(sv4.z) & ~127u) | (unsigned)(ib - 2); v[4 * i + 3] = (fkey(sv4.w) & ~127u) | (unsigned)(ib - 3);
	s_nop 1
	v_bitop3_b32 v0, v16, s98, v0 bitop3:0x56
	v_and_b32_e32 v0, 0xffffff80, v0
	v_sub_u32_e32 v0, v0, v170
	v_add_u32_e32 v16, 0x7f, v0
	v_not_b32_e32 v0, v1
	v_or_b32_e32 v17, 0x80000000, v1
	v_cmp_gt_i32_e32 vcc, 0, v1
	v_ashrrev_i32_e32 v1, 31, v2
	s_nop 0
	v_cndmask_b32_e32 v0, v17, v0, vcc
	v_and_b32_e32 v0, 0xffffff80, v0
	v_sub_u32_e32 v0, v0, v170
	v_add_u32_e32 v17, 0x7e, v0


; DI unsigned fkey(float f) { const unsigned u = __float_as_uint(f); return (u & 0x80000000u) ? ~u : (u | 0x80000000u); }
; DI void topk_phase(unsigned char* smem_, const bf16_t* __restrict__ qp, const bf16_t* __restrict__ keys, int* __restrict__ eidx, float* __restrict__ gate) {
;     ...
;             const f32x4 sv4 = *(const f32x4*)(S + row * LDS_ + 32 * q + 4 * i);
;             const int ib = 127 - (32 * q + 4 * i);
;             v[4 * i] = (fkey(sv4.x) & ~127u) | (unsigned)ib; v[4 * i + 1] = (fkey(sv4.y) & ~127u) | (unsigned)(ib - 1);
;             v[4 * i + 2] = (fkey(sv4.z) & ~127u) | (unsigned)(ib - 2); v[4 * i + 3] = (fkey(sv4.w) & ~127u) | (unsigned)(ib - 3);
	s_nop 1
	v_bitop3_b32 v0, v1, s98, v2 bitop3:0x56
	v_and_b32_e32 v0, 0xffffff80, v0
	v_sub_u32_e32 v0, v0, v170
	v_add_u32_e32 v18, 0x7d, v0
	v_ashrrev_i32_e32 v0, 31, v3


; DI unsigned fkey(float f) { const unsigned u = __float_as_uint(f); return (u & 0x80000000u) ? ~u : (u | 0x80000000u); }
; DI void topk_phase(unsigned char* smem_, const bf16_t* __restrict__ qp, const bf16_t* __restrict__ keys, int* __restrict__ eidx, float* __restrict__ gate) {
;     ...
;             const f32x4 sv4 = *(const f32x4*)(S + row * LDS_ + 32 * q + 4 * i);
;             const int ib = 127 - (32 * q + 4 * i);
;             v[4 * i] = (fkey(sv4.x) & ~127u) | (unsigned)ib; v[4 * i + 1] = (fkey(sv4.y) & ~127u) | (unsigned)(ib - 1);
;             v[4 * i + 2] = (fkey(sv4.z) & ~127u) | (unsigned)(ib - 2); v[4 * i + 3] = (fkey(sv4.w) & ~127u) | (unsigned)(ib - 3);
	s_nop 1
	v_bitop3_b32 v0, v0, s98, v3 bitop3:0x56
	v_and_b32_e32 v0, 0xffffff80, v0
	v_sub_u32_e32 v0, v0, v170
	v_add_u32_e32 v19, 0x7c, v0
	s_waitcnt lgkmcnt(2)
	v_ashrrev_i32_e32 v0, 31, v4


; DI unsigned fkey(float f) { const unsigned u = __float_as_uint(f); return (u & 0x80000000u) ? ~u : (u | 0x80000000u); }
; DI void topk_phase(unsigned char* smem_, const bf16_t* __restrict__ qp, const bf16_t* __restrict__ keys, int* __restrict__ eidx, float* __restrict__ gate) {
;     ...
;             const f32x4 sv4 = *(const f32x4*)(S + row * LDS_ + 32 * q + 4 * i);
;             const int ib = 127 - (32 * q + 4 * i);
;             v[4 * i] = (fkey(sv4.x) & ~127u) | (unsigned)ib; v[4 * i + 1] = (fkey(sv4.y) & ~127u) | (unsigned)(ib - 1);
;             v[4 * i + 2] = (fkey(sv4.z) & ~127u) | (unsigned)(ib - 2); v[4 * i + 3] = (fkey(sv4.w) & ~127u) | (unsigned)(ib - 3);
	s_nop 1
	v_bitop3_b32 v0, v0, s98, v4 bitop3:0x56
	v_and_b32_e32 v0, 0xffffff80, v0
	v_sub_u32_e32 v0, v0, v177
	v_add_u32_e32 v20, 0x7f, v0
	v_ashrrev_i32_e32 v0, 31, v5


; DI unsigned fkey(float f) { const unsigned u = __float_as_uint(f); return (u & 0x80000000u) ? ~u : (u | 0x80000000u); }
; DI void topk_phase(unsigned char* smem_, const bf16_t* __restrict__ qp, const bf16_t* __restrict__ keys, int* __restrict__ eidx, float* __restrict__ gate) {
;     ...
;             const f32x4 sv4 = *(const f32x4*)(S + row * LDS_ + 32 * q + 4 * i);
;             const int ib = 127 - (32 * q + 4 * i);
;             v[4 * i] = (fkey(sv4.x) & ~127u) | (unsigned)ib; v[4 * i + 1] = (fkey(sv4.y) & ~127u) | (unsigned)(ib - 1);
;             v[4 * i + 2] = (fkey(sv4.z) & ~127u) | (unsigned)(ib - 2); v[4 * i + 3] = (fkey(sv4.w) & ~127u) | (unsigned)(ib - 3);
	s_nop 1
	v_bitop3_b32 v0, v0, s98, v5 bitop3:0x56
	v_and_b32_e32 v0, 0xffffff80, v0
	v_sub_u32_e32 v0, v0, v177
	v_add_u32_e32 v21, 0x7e, v0
	v_ashrrev_i32_e32 v0, 31, v6


; DI unsigned fkey(float f) { const unsigned u = __float_as_uint(f); return (u & 0x80000000u) ? ~u : (u | 0x80000000u); }
; DI void topk_phase(unsigned char* smem_, const bf16_t* __restrict__ qp, const bf16_t* __restrict__ keys, int* __restrict__ eidx, float* __restrict__ gate) {
;     ...
;             const f32x4 sv4 = *(const f32x4*)(S + row * LDS_ + 32 * q + 4 * i);
;             const int ib = 127 - (32 * q + 4 * i);
;             v[4 * i] = (fkey(sv4.x) & ~127u) | (unsigned)ib; v[4 * i + 1] = (fkey(sv4.y) & ~127u) | (unsigned)(ib - 1);
;             v[4 * i + 2] = (fkey(sv4.z) & ~127u) | (unsigned)(ib - 2); v[4 * i + 3] = (fkey(sv4.w) & ~127u) | (unsigned)(ib - 3);
	s_nop 1
	v_bitop3_b32 v0, v0, s98, v6 bitop3:0x56
	v_and_b32_e32 v0, 0xffffff80, v0
	v_sub_u32_e32 v0, v0, v177
	v_add_u32_e32 v22, 0x7d, v0
	v_ashrrev_i32_e32 v0, 31, v7


; DI unsigned fkey(float f) { const unsigned u = __float_as_uint(f); return (u & 0x80000000u) ? ~u : (u | 0x80000000u); }
; DI void topk_phase(unsigned char* smem_, const bf16_t* __restrict__ qp, const bf16_t* __restrict__ keys, int* __restrict__ eidx, float* __restrict__ gate) {
;     ...
;             const f32x4 sv4 = *(const f32x4*)(S + row * LDS_ + 32 * q + 4 * i);
;             const int ib = 127 - (32 * q + 4 * i);
;             v[4 * i] = (fkey(sv4.x) & ~127u) | (unsigned)ib; v[4 * i + 1] = (fkey(sv4.y) & ~127u) | (unsigned)(ib - 1);
;             v[4 * i + 2] = (fkey(sv4.z) & ~127u) | (unsigned)(ib - 2); v[4 * i + 3] = (fkey(sv4.w) & ~127u) | (unsigned)(ib - 3);
	s_nop 1
	v_bitop3_b32 v0, v0, s98, v7 bitop3:0x56
	v_and_b32_e32 v0, 0xffffff80, v0
	v_sub_u32_e32 v0, v0, v177
	v_add_u32_e32 v23, 0x7c, v0
	s_waitcnt lgkmcnt(1)
	v_ashrrev_i32_e32 v0, 31, v8


; DI unsigned fkey(float f) { const unsigned u = __float_as_uint(f); return (u & 0x80000000u) ? ~u : (u | 0x80000000u); }
; DI void topk_phase(unsigned char* smem_, const bf16_t* __restrict__ qp, const bf16_t* __restrict__ keys, int* __restrict__ eidx, float* __restrict__ gate) {
;     ...
;             const f32x4 sv4 = *(const f32x4*)(S + row * LDS_ + 32 * q + 4 * i);
;             const int ib = 127 - (32 * q + 4 * i);
;             v[4 * i] = (fkey(sv4.x) & ~127u) | (unsigned)ib; v[4 * i + 1] = (fkey(sv4.y) & ~127u) | (unsigned)(ib - 1);
;             v[4 * i + 2] = (fkey(sv4.z) & ~127u) | (unsigned)(ib - 2); v[4 * i + 3] = (fkey(sv4.w) & ~127u) | (unsigned)(ib - 3);
	s_nop 1
	v_bitop3_b32 v0, v0, s98, v8 bitop3:0x56
	v_and_b32_e32 v0, 0xffffff80, v0
	v_sub_u32_e32 v0, v0, v178
	v_add_u32_e32 v8, 0x7f, v0
	v_ashrrev_i32_e32 v0, 31, v9


; DI unsigned fkey(float f) { const unsigned u = __float_as_uint(f); return (u & 0x80000000u) ? ~u : (u | 0x80000000u); }
; DI void topk_phase(unsigned char* smem_, const bf16_t* __restrict__ qp, const bf16_t* __restrict__ keys, int* __restrict__ eidx, float* __restrict__ gate) {
;     ...
;             const f32x4 sv4 = *(const f32x4*)(S + row * LDS_ + 32 * q + 4 * i);
;             const int ib = 127 - (32 * q + 4 * i);
;             v[4 * i] = (fkey(sv4.x) & ~127u) | (unsigned)ib; v[4 * i + 1] = (fkey(sv4.y) & ~127u) | (unsigned)(ib - 1);
;             v[4 * i + 2] = (fkey(sv4.z) & ~127u) | (unsigned)(ib - 2); v[4 * i + 3] = (fkey(sv4.w) & ~127u) | (unsigned)(ib - 3);
	s_nop 1
	v_bitop3_b32 v0, v0, s98, v9 bitop3:0x56
	v_and_b32_e32 v0, 0xffffff80, v0
	v_sub_u32_e32 v0, v0, v178
	v_add_u32_e32 v9, 0x7e, v0
	v_ashrrev_i32_e32 v0, 31, v10


; DI unsigned fkey(float f) { const unsigned u = __float_as_uint(f); return (u & 0x80000000u) ? ~u : (u | 0x80000000u); }
; DI void topk_phase(unsigned char* smem_, const bf16_t* __restrict__ qp, const bf16_t* __restrict__ keys, int* __restrict__ eidx, float* __restrict__ gate) {
;     ...
;             const f32x4 sv4 = *(const f32x4*)(S + row * LDS_ + 32 * q + 4 * i);
;             const int ib = 127 - (32 * q + 4 * i);
;             v[4 * i] = (fkey(sv4.x) & ~127u) | (unsigned)ib; v[4 * i + 1] = (fkey(sv4.y) & ~127u) | (unsigned)(ib - 1);
;             v[4 * i + 2] = (fkey(sv4.z) & ~127u) | (unsigned)(ib - 2); v[4 * i + 3] = (fkey(sv4.w) & ~127u) | (unsigned)(ib - 3);
	s_nop 1
	v_bitop3_b32 v0, v0, s98, v10 bitop3:0x56
	v_and_b32_e32 v0, 0xffffff80, v0
	v_sub_u32_e32 v0, v0, v178
	v_add_u32_e32 v10, 0x7d, v0
	v_ashrrev_i32_e32 v0, 31, v11


; DI unsigned fkey(float f) { const unsigned u = __float_as_uint(f); return (u & 0x80000000u) ? ~u : (u | 0x80000000u); }
; DI void topk_phase(unsigned char* smem_, const bf16_t* __restrict__ qp, const bf16_t* __restrict__ keys, int* __restrict__ eidx, float* __restrict__ gate) {
;     ...
;             const f32x4 sv4 = *(const f32x4*)(S + row * LDS_ + 32 * q + 4 * i);
;             const int ib = 127 - (32 * q + 4 * i);
;             v[4 * i] = (fkey(sv4.x) & ~127u) | (unsigned)ib; v[4 * i + 1] = (fkey(sv4.y) & ~127u) | (unsigned)(ib - 1);
;             v[4 * i + 2] = (fkey(sv4.z) & ~127u) | (unsigned)(ib - 2); v[4 * i + 3] = (fkey(sv4.w) & ~127u) | (unsigned)(ib - 3);
	s_nop 1
	v_bitop3_b32 v0, v0, s98, v11 bitop3:0x56
	v_and_b32_e32 v0, 0xffffff80, v0
	v_sub_u32_e32 v0, v0, v178
	v_add_u32_e32 v11, 0x7c, v0
	s_waitcnt lgkmcnt(0)
	v_ashrrev_i32_e32 v0, 31, v12


; DI unsigned fkey(float f) { const unsigned u = __float_as_uint(f); return (u & 0x80000000u) ? ~u : (u | 0x80000000u); }
; DI void topk_phase(unsigned char* smem_, const bf16_t* __restrict__ qp, const bf16_t* __restrict__ keys, int* __restrict__ eidx, float* __restrict__ gate) {
;     ...
;             const f32x4 sv4 = *(const f32x4*)(S + row * LDS_ + 32 * q + 4 * i);
;             const int ib = 127 - (32 * q + 4 * i);
;             v[4 * i] = (fkey(sv4.x) & ~127u) | (unsigned)ib; v[4 * i + 1] = (fkey(sv4.y) & ~127u) | (unsigned)(ib - 1);
;             v[4 * i + 2] = (fkey(sv4.z) & ~127u) | (unsigned)(ib - 2); v[4 * i + 3] = (fkey(sv4.w) & ~127u) | (unsigned)(ib - 3);
	s_nop 1
	v_bitop3_b32 v0, v0, s98, v12 bitop3:0x56
	v_and_b32_e32 v0, 0xffffff80, v0
	v_sub_u32_e32 v0, v0, v179
	v_add_u32_e32 v12, 0x7f, v0
	v_ashrrev_i32_e32 v0, 31, v13


; DI unsigned fkey(float f) { const unsigned u = __float_as_uint(f); return (u & 0x80000000u) ? ~u : (u | 0x80000000u); }
; DI void topk_phase(unsigned char* smem_, const bf16_t* __restrict__ qp, const bf16_t* __restrict__ keys, int* __restrict__ eidx, float* __restrict__ gate) {
;     ...
;             const f32x4 sv4 = *(const f32x4*)(S + row * LDS_ + 32 * q + 4 * i);
;             const int ib = 127 - (32 * q + 4 * i);
;             v[4 * i] = (fkey(sv4.x) & ~127u) | (unsigned)ib; v[4 * i + 1] = (fkey(sv4.y) & ~127u) | (unsigned)(ib - 1);
;             v[4 * i + 2] = (fkey(sv4.z) & ~127u) | (unsigned)(ib - 2); v[4 * i + 3] = (fkey(sv4.w) & ~127u) | (unsigned)(ib - 3);
	s_nop 1
	v_bitop3_b32 v0, v0, s98, v13 bitop3:0x56
	v_and_b32_e32 v0, 0xffffff80, v0
	v_sub_u32_e32 v0, v0, v179
	v_add_u32_e32 v13, 0x7e, v0
	v_ashrrev_i32_e32 v0, 31, v14


; DI unsigned fkey(float f) { const unsigned u = __float_as_uint(f); return (u & 0x80000000u) ? ~u : (u | 0x80000000u); }
; DI void topk_phase(unsigned char* smem_, const bf16_t* __restrict__ qp, const bf16_t* __restrict__ keys, int* __restrict__ eidx, float* __restrict__ gate) {
;     ...
;             const f32x4 sv4 = *(const f32x4*)(S + row * LDS_ + 32 * q + 4 * i);
;             const int ib = 127 - (32 * q + 4 * i);
;             v[4 * i] = (fkey(sv4.x) & ~127u) | (unsigned)ib; v[4 * i + 1] = (fkey(sv4.y) & ~127u) | (unsigned)(ib - 1);
;             v[4 * i + 2] = (fkey(sv4.z) & ~127u) | (unsigned)(ib - 2); v[4 * i + 3] = (fkey(sv4.w) & ~127u) | (unsigned)(ib - 3);
	s_nop 1
	v_bitop3_b32 v0, v0, s98, v14 bitop3:0x56
	v_and_b32_e32 v0, 0xffffff80, v0
	v_sub_u32_e32 v0, v0, v179
	v_add_u32_e32 v14, 0x7d, v0
	v_ashrrev_i32_e32 v0, 31, v15


; DI unsigned fkey(float f) { const unsigned u = __float_as_uint(f); return (u & 0x80000000u) ? ~u : (u | 0x80000000u); }
; DI void topk_phase(unsigned char* smem_, const bf16_t* __restrict__ qp, const bf16_t* __restrict__ keys, int* __restrict__ eidx, float* __restrict__ gate) {
;     ...
;             const f32x4 sv4 = *(const f32x4*)(S + row * LDS_ + 32 * q + 4 * i);
;             const int ib = 127 - (32 * q + 4 * i);
;             v[4 * i] = (fkey(sv4.x) & ~127u) | (unsigned)ib; v[4 * i + 1] = (fkey(sv4.y) & ~127u) | (unsigned)(ib - 1);
;             v[4 * i + 2] = (fkey(sv4.z) & ~127u) | (unsigned)(ib - 2); v[4 * i + 3] = (fkey(sv4.w) & ~127u) | (unsigned)(ib - 3);
	s_nop 1
	v_bitop3_b32 v4, v0, s98, v15 bitop3:0x56
	ds_read_b128 v[0:3], v171 offset:17472
	v_and_b32_e32 v4, 0xffffff80, v4
	v_sub_u32_e32 v4, v4, v179
	v_add_u32_e32 v15, 0x7c, v4
	ds_read_b128 v[4:7], v171 offset:17488
	s_waitcnt lgkmcnt(1)
	v_ashrrev_i32_e32 v24, 31, v0


; DI unsigned fkey(float f) { const unsigned u = __float_as_uint(f); return (u & 0x80000000u) ? ~u : (u | 0x80000000u); }
; DI void topk_phase(unsigned char* smem_, const bf16_t* __restrict__ qp, const bf16_t* __restrict__ keys, int* __restrict__ eidx, float* __restrict__ gate) {
;     ...
;             const f32x4 sv4 = *(const f32x4*)(S + row * LDS_ + 32 * q + 4 * i);
;             const int ib = 127 - (32 * q + 4 * i);
;             v[4 * i] = (fkey(sv4.x) & ~127u) | (unsigned)ib; v[4 * i + 1] = (fkey(sv4.y) & ~127u) | (unsigned)(ib - 1);
;             v[4 * i + 2] = (fkey(sv4.z) & ~127u) | (unsigned)(ib - 2); v[4 * i + 3] = (fkey(sv4.w) & ~127u) | (unsigned)(ib - 3);
	s_nop 1
	v_bitop3_b32 v0, v24, s98, v0 bitop3:0x56
	v_and_b32_e32 v0, 0xffffff80, v0
	v_sub_u32_e32 v0, v0, v180
	v_add_u32_e32 v24, 0x7f, v0
	v_not_b32_e32 v0, v1
	v_or_b32_e32 v25, 0x80000000, v1
	v_cmp_gt_i32_e32 vcc, 0, v1
	v_ashrrev_i32_e32 v1, 31, v2
	s_nop 0
	v_cndmask_b32_e32 v0, v25, v0, vcc
	v_and_b32_e32 v0, 0xffffff80, v0
	v_sub_u32_e32 v0, v0, v180
	v_add_u32_e32 v25, 0x7e, v0


; DI unsigned fkey(float f) { const unsigned u = __float_as_uint(f); return (u & 0x80000000u) ? ~u : (u | 0x80000000u); }
; DI void topk_phase(unsigned char* smem_, const bf16_t* __restrict__ qp, const bf16_t* __restrict__ keys, int* __restrict__ eidx, float* __restrict__ gate) {
;     ...
;             const f32x4 sv4 = *(const f32x4*)(S + row * LDS_ + 32 * q + 4 * i);
;             const int ib = 127 - (32 * q + 4 * i);
;             v[4 * i] = (fkey(sv4.x) & ~127u) | (unsigned)ib; v[4 * i + 1] = (fkey(sv4.y) & ~127u) | (unsigned)(ib - 1);
;             v[4 * i + 2] = (fkey(sv4.z) & ~127u) | (unsigned)(ib - 2); v[4 * i + 3] = (fkey(sv4.w) & ~127u) | (unsigned)(ib - 3);
	s_nop 1
	v_bitop3_b32 v0, v1, s98, v2 bitop3:0x56
	v_and_b32_e32 v0, 0xffffff80, v0
	v_sub_u32_e32 v0, v0, v180
	v_add_u32_e32 v26, 0x7d, v0
	v_ashrrev_i32_e32 v0, 31, v3


; DI unsigned fkey(float f) { const unsigned u = __float_as_uint(f); return (u & 0x80000000u) ? ~u : (u | 0x80000000u); }
; DI void topk_phase(unsigned char* smem_, const bf16_t* __restrict__ qp, const bf16_t* __restrict__ keys, int* __restrict__ eidx, float* __restrict__ gate) {
;     ...
;             const f32x4 sv4 = *(const f32x4*)(S + row * LDS_ + 32 * q + 4 * i);
;             const int ib = 127 - (32 * q + 4 * i);
;             v[4 * i] = (fkey(sv4.x) & ~127u) | (unsigned)ib; v[4 * i + 1] = (fkey(sv4.y) & ~127u) | (unsigned)(ib - 1);
;             v[4 * i + 2] = (fkey(sv4.z) & ~127u) | (unsigned)(ib - 2); v[4 * i + 3] = (fkey(sv4.w) & ~127u) | (unsigned)(ib - 3);
	s_nop 1
	v_bitop3_b32 v0, v0, s98, v3 bitop3:0x56
	v_and_b32_e32 v0, 0xffffff80, v0
	v_sub_u32_e32 v0, v0, v180
	v_add_u32_e32 v27, 0x7c, v0
	s_waitcnt lgkmcnt(0)
	v_ashrrev_i32_e32 v0, 31, v4


; DI unsigned fkey(float f) { const unsigned u = __float_as_uint(f); return (u & 0x80000000u) ? ~u : (u | 0x80000000u); }
; DI void topk_phase(unsigned char* smem_, const bf16_t* __restrict__ qp, const bf16_t* __restrict__ keys, int* __restrict__ eidx, float* __restrict__ gate) {
;     ...
;             const f32x4 sv4 = *(const f32x4*)(S + row * LDS_ + 32 * q + 4 * i);
;             const int ib = 127 - (32 * q + 4 * i);
;             v[4 * i] = (fkey(sv4.x) & ~127u) | (unsigned)ib; v[4 * i + 1] = (fkey(sv4.y) & ~127u) | (unsigned)(ib - 1);
;             v[4 * i + 2] = (fkey(sv4.z) & ~127u) | (unsigned)(ib - 2); v[4 * i + 3] = (fkey(sv4.w) & ~127u) | (unsigned)(ib - 3);
	s_nop 1
	v_bitop3_b32 v0, v0, s98, v4 bitop3:0x56
	v_and_b32_e32 v0, 0xffffff80, v0
	v_sub_u32_e32 v0, v0, v181
	v_add_u32_e32 v28, 0x7f, v0
	v_ashrrev_i32_e32 v0, 31, v5


; DI unsigned fkey(float f) { const unsigned u = __float_as_uint(f); return (u & 0x80000000u) ? ~u : (u | 0x80000000u); }
; DI void topk_phase(unsigned char* smem_, const bf16_t* __restrict__ qp, const bf16_t* __restrict__ keys, int* __restrict__ eidx, float* __restrict__ gate) {
;     ...
;             const f32x4 sv4 = *(const f32x4*)(S + row * LDS_ + 32 * q + 4 * i);
;             const int ib = 127 - (32 * q + 4 * i);
;             v[4 * i] = (fkey(sv4.x) & ~127u) | (unsigned)ib; v[4 * i + 1] = (fkey(sv4.y) & ~127u) | (unsigned)(ib - 1);
;             v[4 * i + 2] = (fkey(sv4.z) & ~127u) | (unsigned)(ib - 2); v[4 * i + 3] = (fkey(sv4.w) & ~127u) | (unsigned)(ib - 3);
	s_nop 1
	v_bitop3_b32 v0, v0, s98, v5 bitop3:0x56
	v_and_b32_e32 v0, 0xffffff80, v0
	v_sub_u32_e32 v0, v0, v181
	v_add_u32_e32 v29, 0x7e, v0
	v_ashrrev_i32_e32 v0, 31, v6


; DI unsigned fkey(float f) { const unsigned u = __float_as_uint(f); return (u & 0x80000000u) ? ~u : (u | 0x80000000u); }
; DI void topk_phase(unsigned char* smem_, const bf16_t* __restrict__ qp, const bf16_t* __restrict__ keys, int* __restrict__ eidx, float* __restrict__ gate) {
;     ...
;             const f32x4 sv4 = *(const f32x4*)(S + row * LDS_ + 32 * q + 4 * i);
;             const int ib = 127 - (32 * q + 4 * i);
;             v[4 * i] = (fkey(sv4.x) & ~127u) | (unsigned)ib; v[4 * i + 1] = (fkey(sv4.y) & ~127u) | (unsigned)(ib - 1);
;             v[4 * i + 2] = (fkey(sv4.z) & ~127u) | (unsigned)(ib - 2); v[4 * i + 3] = (fkey(sv4.w) & ~127u) | (unsigned)(ib - 3);
	s_nop 1
	v_bitop3_b32 v0, v0, s98, v6 bitop3:0x56
	v_and_b32_e32 v0, 0xffffff80, v0
	v_sub_u32_e32 v0, v0, v181
	v_add_u32_e32 v30, 0x7d, v0
	v_ashrrev_i32_e32 v0, 31, v7


; DI unsigned fkey(float f) { const unsigned u = __float_as_uint(f); return (u & 0x80000000u) ? ~u : (u | 0x80000000u); }
; DI void topk_phase(unsigned char* smem_, const bf16_t* __restrict__ qp, const bf16_t* __restrict__ keys, int* __restrict__ eidx, float* __restrict__ gate) {
;     ...
;             const f32x4 sv4 = *(const f32x4*)(S + row * LDS_ + 32 * q + 4 * i);
;             const int ib = 127 - (32 * q + 4 * i);
;             v[4 * i] = (fkey(sv4.x) & ~127u) | (unsigned)ib; v[4 * i + 1] = (fkey(sv4.y) & ~127u) | (unsigned)(ib - 1);
;             v[4 * i + 2] = (fkey(sv4.z) & ~127u) | (unsigned)(ib - 2); v[4 * i + 3] = (fkey(sv4.w) & ~127u) | (unsigned)(ib - 3);
	s_nop 1
	v_bitop3_b32 v4, v0, s98, v7 bitop3:0x56
	ds_read_b128 v[0:3], v171 offset:17504
	v_and_b32_e32 v4, 0xffffff80, v4
	v_sub_u32_e32 v4, v4, v181
	v_add_u32_e32 v31, 0x7c, v4
	ds_read_b128 v[4:7], v171 offset:17520
	s_waitcnt lgkmcnt(1)
	v_ashrrev_i32_e32 v117, 31, v0


; DI unsigned fkey(float f) { const unsigned u = __float_as_uint(f); return (u & 0x80000000u) ? ~u : (u | 0x80000000u); }
; DI void topk_phase(unsigned char* smem_, const bf16_t* __restrict__ qp, const bf16_t* __restrict__ keys, int* __restrict__ eidx, float* __restrict__ gate) {
;     ...
;             const f32x4 sv4 = *(const f32x4*)(S + row * LDS_ + 32 * q + 4 * i);
;             const int ib = 127 - (32 * q + 4 * i);
;             v[4 * i] = (fkey(sv4.x) & ~127u) | (unsigned)ib; v[4 * i + 1] = (fkey(sv4.y) & ~127u) | (unsigned)(ib - 1);
;             v[4 * i + 2] = (fkey(sv4.z) & ~127u) | (unsigned)(ib - 2); v[4 * i + 3] = (fkey(sv4.w) & ~127u) | (unsigned)(ib - 3);
	s_nop 1
	v_bitop3_b32 v0, v117, s98, v0 bitop3:0x56
	v_ashrrev_i32_e32 v117, 31, v1


; DI unsigned fkey(float f) { const unsigned u = __float_as_uint(f); return (u & 0x80000000u) ? ~u : (u | 0x80000000u); }
; DI void topk_phase(unsigned char* smem_, const bf16_t* __restrict__ qp, const bf16_t* __restrict__ keys, int* __restrict__ eidx, float* __restrict__ gate) {
;     ...
;             const f32x4 sv4 = *(const f32x4*)(S + row * LDS_ + 32 * q + 4 * i);
;             const int ib = 127 - (32 * q + 4 * i);
;             v[4 * i] = (fkey(sv4.x) & ~127u) | (unsigned)ib; v[4 * i + 1] = (fkey(sv4.y) & ~127u) | (unsigned)(ib - 1);
;             v[4 * i + 2] = (fkey(sv4.z) & ~127u) | (unsigned)(ib - 2); v[4 * i + 3] = (fkey(sv4.w) & ~127u) | (unsigned)(ib - 3);
	v_and_b32_e32 v0, 0xffffff80, v0
	v_sub_u32_e32 v0, v0, v182
	v_bitop3_b32 v1, v117, s98, v1 bitop3:0x56
	v_ashrrev_i32_e32 v117, 31, v2


; DI unsigned fkey(float f) { const unsigned u = __float_as_uint(f); return (u & 0x80000000u) ? ~u : (u | 0x80000000u); }
; DI void topk_phase(unsigned char* smem_, const bf16_t* __restrict__ qp, const bf16_t* __restrict__ keys, int* __restrict__ eidx, float* __restrict__ gate) {
;     ...
;             const f32x4 sv4 = *(const f32x4*)(S + row * LDS_ + 32 * q + 4 * i);
;             const int ib = 127 - (32 * q + 4 * i);
;             v[4 * i] = (fkey(sv4.x) & ~127u) | (unsigned)ib; v[4 * i + 1] = (fkey(sv4.y) & ~127u) | (unsigned)(ib - 1);
;             v[4 * i + 2] = (fkey(sv4.z) & ~127u) | (unsigned)(ib - 2); v[4 * i + 3] = (fkey(sv4.w) & ~127u) | (unsigned)(ib - 3);
	v_and_b32_e32 v1, 0xffffff80, v1
	v_sub_u32_e32 v1, v1, v182
	v_bitop3_b32 v2, v117, s98, v2 bitop3:0x56
	v_ashrrev_i32_e32 v117, 31, v3


; DI unsigned fkey(float f) { const unsigned u = __float_as_uint(f); return (u & 0x80000000u) ? ~u : (u | 0x80000000u); }
; DI void topk_phase(unsigned char* smem_, const bf16_t* __restrict__ qp, const bf16_t* __restrict__ keys, int* __restrict__ eidx, float* __restrict__ gate) {
;     ...
;             const f32x4 sv4 = *(const f32x4*)(S + row * LDS_ + 32 * q + 4 * i);
;             const int ib = 127 - (32 * q + 4 * i);
;             v[4 * i] = (fkey(sv4.x) & ~127u) | (unsigned)ib; v[4 * i + 1] = (fkey(sv4.y) & ~127u) | (unsigned)(ib - 1);
;             v[4 * i + 2] = (fkey(sv4.z) & ~127u) | (unsigned)(ib - 2); v[4 * i + 3] = (fkey(sv4.w) & ~127u) | (unsigned)(ib - 3);
	v_and_b32_e32 v2, 0xffffff80, v2
	v_sub_u32_e32 v2, v2, v182
	v_bitop3_b32 v3, v117, s98, v3 bitop3:0x56
	s_waitcnt lgkmcnt(0)
	v_ashrrev_i32_e32 v117, 31, v4


; DI unsigned fkey(float f) { const unsigned u = __float_as_uint(f); return (u & 0x80000000u) ? ~u : (u | 0x80000000u); }
; DI void topk_phase(unsigned char* smem_, const bf16_t* __restrict__ qp, const bf16_t* __restrict__ keys, int* __restrict__ eidx, float* __restrict__ gate) {
;     ...
;             const f32x4 sv4 = *(const f32x4*)(S + row * LDS_ + 32 * q + 4 * i);
;             const int ib = 127 - (32 * q + 4 * i);
;             v[4 * i] = (fkey(sv4.x) & ~127u) | (unsigned)ib; v[4 * i + 1] = (fkey(sv4.y) & ~127u) | (unsigned)(ib - 1);
;             v[4 * i + 2] = (fkey(sv4.z) & ~127u) | (unsigned)(ib - 2); v[4 * i + 3] = (fkey(sv4.w) & ~127u) | (unsigned)(ib - 3);
	v_and_b32_e32 v3, 0xffffff80, v3
	v_sub_u32_e32 v3, v3, v182
	v_bitop3_b32 v4, v117, s98, v4 bitop3:0x56
	v_ashrrev_i32_e32 v117, 31, v5


; DI unsigned fkey(float f) { const unsigned u = __float_as_uint(f); return (u & 0x80000000u) ? ~u : (u | 0x80000000u); }
; DI void topk_phase(unsigned char* smem_, const bf16_t* __restrict__ qp, const bf16_t* __restrict__ keys, int* __restrict__ eidx, float* __restrict__ gate) {
;     ...
;             const f32x4 sv4 = *(const f32x4*)(S + row * LDS_ + 32 * q + 4 * i);
;             const int ib = 127 - (32 * q + 4 * i);
;             v[4 * i] = (fkey(sv4.x) & ~127u) | (unsigned)ib; v[4 * i + 1] = (fkey(sv4.y) & ~127u) | (unsigned)(ib - 1);
;             v[4 * i + 2] = (fkey(sv4.z) & ~127u) | (unsigned)(ib - 2); v[4 * i + 3] = (fkey(sv4.w) & ~127u) | (unsigned)(ib - 3);
	v_and_b32_e32 v4, 0xffffff80, v4
	v_sub_u32_e32 v4, v4, v183
	v_bitop3_b32 v5, v117, s98, v5 bitop3:0x56
	v_ashrrev_i32_e32 v117, 31, v6


; DI unsigned fkey(float f) { const unsigned u = __float_as_uint(f); return (u & 0x80000000u) ? ~u : (u | 0x80000000u); }
; DI void topk_phase(unsigned char* smem_, const bf16_t* __restrict__ qp, const bf16_t* __restrict__ keys, int* __restrict__ eidx, float* __restrict__ gate) {
;     ...
;             const f32x4 sv4 = *(const f32x4*)(S + row * LDS_ + 32 * q + 4 * i);
;             const int ib = 127 - (32 * q + 4 * i);
;             v[4 * i] = (fkey(sv4.x) & ~127u) | (unsigned)ib; v[4 * i + 1] = (fkey(sv4.y) & ~127u) | (unsigned)(ib - 1);
;             v[4 * i + 2] = (fkey(sv4.z) & ~127u) | (unsigned)(ib - 2); v[4 * i + 3] = (fkey(sv4.w) & ~127u) | (unsigned)(ib - 3);
	v_and_b32_e32 v5, 0xffffff80, v5
	v_sub_u32_e32 v5, v5, v183
	v_bitop3_b32 v6, v117, s98, v6 bitop3:0x56
	v_ashrrev_i32_e32 v117, 31, v7


; DI unsigned fkey(float f) { const unsigned u = __float_as_uint(f); return (u & 0x80000000u) ? ~u : (u | 0x80000000u); }
; template <int N> DI void bitonic_sort_desc(unsigned (&v)[N]) {
; #pragma unroll
;     for (int k = 2; k <= N; k <<= 1)
; #pragma unroll
;         for (int j = k >> 1; j > 0; j >>= 1)
; #pragma unroll
;             for (int i = 0; i < N; ++i) { const int l = i ^ j; if (l > i) { if ((i & k) == 0) cswap(v[i], v[l]); else cswap(v[l], v[i]); } }
; DI void topk_phase(unsigned char* smem_, const bf16_t* __restrict__ qp, const bf16_t* __restrict__ keys, int* __restrict__ eidx, float* __restrict__ gate) {
;     ...
;             v[4 * i] = (fkey(sv4.x) & ~127u) | (unsigned)ib; v[4 * i + 1] = (fkey(sv4.y) & ~127u) | (unsigned)(ib - 1);
;             v[4 * i + 2] = (fkey(sv4.z) & ~127u) | (unsigned)(ib - 2); v[4 * i + 3] = (fkey(sv4.w) & ~127u) | (unsigned)(ib - 3);
;         }
;         bitonic_sort_desc<32>(v);
	v_and_b32_e32 v6, 0xffffff80, v6
	v_sub_u32_e32 v6, v6, v183
	v_bitop3_b32 v7, v117, s98, v7 bitop3:0x56
	v_and_b32_e32 v7, 0xffffff80, v7
	v_sub_u32_e32 v7, v7, v183
	v_add_u32_e32 v0, 0x7f, v0
	v_add_u32_e32 v1, 0x7e, v1
	v_add_u32_e32 v2, 0x7d, v2
	v_add_u32_e32 v3, 0x7c, v3
	v_add_u32_e32 v4, 0x7f, v4
	v_add_u32_e32 v5, 0x7e, v5
	v_add_u32_e32 v6, 0x7d, v6
	v_add_u32_e32 v7, 0x7c, v7
	v_max_u32_e32 v117, v16, v17
	v_min_u32_e32 v16, v16, v17
	v_max_u32_e32 v17, v19, v18
	v_min_u32_e32 v18, v19, v18
	v_max_u32_e32 v19, v20, v21
	v_min_u32_e32 v20, v20, v21
	v_max_u32_e32 v21, v23, v22
	v_min_u32_e32 v22, v23, v22
	v_max_u32_e32 v23, v8, v9
	v_min_u32_e32 v8, v8, v9
	v_max_u32_e32 v9, v11, v10
	v_min_u32_e32 v10, v11, v10
	v_max_u32_e32 v11, v12, v13
	v_min_u32_e32 v12, v12, v13
	v_max_u32_e32 v13, v15, v14
	v_min_u32_e32 v14, v15, v14
	v_max_u32_e32 v15, v24, v25
	v_min_u32_e32 v24, v24, v25
	v_max_u32_e32 v25, v27, v26
	v_min_u32_e32 v26, v27, v26
	v_max_u32_e32 v27, v28, v29
	v_min_u32_e32 v28, v28, v29
	v_max_u32_e32 v29, v31, v30
	v_min_u32_e32 v30, v31, v30
	v_max_u32_e32 v31, v0, v1
	v_min_u32_e32 v0, v0, v1
	v_max_u32_e32 v1, v3, v2
	v_min_u32_e32 v2, v3, v2
	v_max_u32_e32 v3, v4, v5
	v_min_u32_e32 v4, v4, v5
	v_max_u32_e32 v5, v7, v6
	v_min_u32_e32 v6, v7, v6
	v_max_u32_e32 v7, v117, v18
	v_min_u32_e32 v18, v117, v18
	v_max_u32_e32 v117, v16, v17
	v_min_u32_e32 v16, v16, v17
	v_max_u32_e32 v17, v22, v19
	v_min_u32_e32 v19, v22, v19
	v_max_u32_e32 v22, v21, v20
	v_min_u32_e32 v20, v21, v20
	v_max_u32_e32 v21, v23, v10
	v_min_u32_e32 v10, v23, v10
	v_max_u32_e32 v23, v8, v9
	v_min_u32_e32 v8, v8, v9
	v_max_u32_e32 v9, v14, v11
	v_min_u32_e32 v11, v14, v11
	v_max_u32_e32 v14, v13, v12
	v_min_u32_e32 v12, v13, v12
	v_max_u32_e32 v13, v15, v26
	v_min_u32_e32 v15, v15, v26
	v_max_u32_e32 v26, v24, v25
	v_min_u32_e32 v24, v24, v25
	v_max_u32_e32 v25, v30, v27
	v_min_u32_e32 v27, v30, v27
	v_max_u32_e32 v30, v29, v28
	v_min_u32_e32 v28, v29, v28
	v_max_u32_e32 v29, v31, v2
	v_min_u32_e32 v2, v31, v2
	v_max_u32_e32 v31, v0, v1
	v_min_u32_e32 v0, v0, v1
	v_max_u32_e32 v1, v6, v3
	v_min_u32_e32 v3, v6, v3
	v_max_u32_e32 v6, v5, v4
	v_min_u32_e32 v4, v5, v4
	v_max_u32_e32 v5, v7, v117
	v_min_u32_e32 v7, v7, v117
	v_max_u32_e32 v117, v18, v16
	v_min_u32_e32 v16, v18, v16
	v_max_u32_e32 v18, v20, v19
	v_min_u32_e32 v19, v20, v19
	v_max_u32_e32 v20, v22, v17
	v_min_u32_e32 v17, v22, v17
	v_max_u32_e32 v22, v21, v23
	v_min_u32_e32 v21, v21, v23
	v_max_u32_e32 v23, v10, v8
	v_min_u32_e32 v8, v10, v8
	v_max_u32_e32 v10, v12, v11
	v_min_u32_e32 v11, v12, v11
	v_max_u32_e32 v12, v14, v9
	v_min_u32_e32 v9, v14, v9
	v_max_u32_e32 v14, v13, v26
	v_min_u32_e32 v13, v13, v26
	v_max_u32_e32 v26, v15, v24
	v_min_u32_e32 v15, v15, v24
	v_max_u32_e32 v24, v28, v27
	v_min_u32_e32 v27, v28, v27
	v_max_u32_e32 v28, v30, v25
	v_min_u32_e32 v25, v30, v25
	v_max_u32_e32 v30, v29, v31
	v_min_u32_e32 v29, v29, v31
	v_max_u32_e32 v31, v2, v0
	v_min_u32_e32 v0, v2, v0
	v_max_u32_e32 v2, v4, v3
	v_min_u32_e32 v3, v4, v3
	v_max_u32_e32 v4, v6, v1
	v_min_u32_e32 v1, v6, v1
	v_max_u32_e32 v6, v5, v19
	v_min_u32_e32 v5, v5, v19
	v_max_u32_e32 v19, v7, v18
	v_min_u32_e32 v7, v7, v18
	v_max_u32_e32 v18, v117, v17
	v_min_u32_e32 v17, v117, v17
	v_max_u32_e32 v117, v16, v20
	v_min_u32_e32 v16, v16, v20
	v_max_u32_e32 v20, v11, v22
	v_min_u32_e32 v11, v11, v22
	v_max_u32_e32 v22, v10, v21
	v_min_u32_e32 v10, v10, v21
	v_max_u32_e32 v21, v9, v23
	v_min_u32_e32 v9, v9, v23
	v_max_u32_e32 v23, v12, v8
	v_min_u32_e32 v8, v12, v8
	v_max_u32_e32 v12, v14, v27
	v_min_u32_e32 v14, v14, v27
	v_max_u32_e32 v27, v13, v24
	v_min_u32_e32 v13, v13, v24
	v_max_u32_e32 v24, v26, v25
	v_min_u32_e32 v25, v26, v25
	v_max_u32_e32 v26, v15, v28
	v_min_u32_e32 v15, v15, v28
	v_max_u32_e32 v28, v3, v30
	v_min_u32_e32 v3, v3, v30
	v_max_u32_e32 v30, v2, v29
	v_min_u32_e32 v2, v2, v29
	v_max_u32_e32 v29, v1, v31
	v_min_u32_e32 v1, v1, v31
	v_max_u32_e32 v31, v4, v0
	v_min_u32_e32 v0, v4, v0
	v_max_u32_e32 v4, v6, v18
	v_min_u32_e32 v6, v6, v18
	v_max_u32_e32 v18, v19, v117
	v_min_u32_e32 v19, v19, v117
	v_max_u32_e32 v117, v5, v17
	v_min_u32_e32 v5, v5, v17
	v_max_u32_e32 v17, v7, v16
	v_min_u32_e32 v7, v7, v16
	v_max_u32_e32 v16, v9, v11
	v_min_u32_e32 v9, v9, v11
	v_max_u32_e32 v11, v8, v10
	v_min_u32_e32 v8, v8, v10
	v_max_u32_e32 v10, v21, v20
	v_min_u32_e32 v20, v21, v20
	v_max_u32_e32 v21, v23, v22
	v_min_u32_e32 v22, v23, v22
	v_max_u32_e32 v23, v12, v24
	v_min_u32_e32 v12, v12, v24
	v_max_u32_e32 v24, v27, v26
	v_min_u32_e32 v26, v27, v26
	v_max_u32_e32 v27, v14, v25
	v_min_u32_e32 v14, v14, v25
	v_max_u32_e32 v25, v13, v15
	v_min_u32_e32 v13, v13, v15
	v_max_u32_e32 v15, v1, v3
	v_min_u32_e32 v1, v1, v3
	v_max_u32_e32 v3, v0, v2
	v_min_u32_e32 v0, v0, v2
	v_max_u32_e32 v2, v29, v28
	v_min_u32_e32 v28, v29, v28
	v_max_u32_e32 v29, v31, v30
	v_min_u32_e32 v30, v31, v30
	v_max_u32_e32 v31, v4, v18
	v_min_u32_e32 v4, v4, v18
	v_max_u32_e32 v18, v6, v19
	v_min_u32_e32 v6, v6, v19
	v_max_u32_e32 v19, v117, v17
	v_min_u32_e32 v17, v117, v17
	v_max_u32_e32 v117, v5, v7
	v_min_u32_e32 v5, v5, v7
	v_max_u32_e32 v7, v8, v9
	v_min_u32_e32 v8, v8, v9
	v_max_u32_e32 v9, v11, v16
	v_min_u32_e32 v11, v11, v16
	v_max_u32_e32 v16, v22, v20
	v_min_u32_e32 v20, v22, v20
	v_max_u32_e32 v22, v21, v10
	v_min_u32_e32 v10, v21, v10
	v_max_u32_e32 v21, v23, v24
	v_min_u32_e32 v23, v23, v24
	v_max_u32_e32 v24, v12, v26
	v_min_u32_e32 v12, v12, v26
	v_max_u32_e32 v26, v27, v25
	v_min_u32_e32 v25, v27, v25
	v_max_u32_e32 v27, v14, v13
	v_min_u32_e32 v13, v14, v13
	v_max_u32_e32 v14, v0, v1
	v_min_u32_e32 v0, v0, v1
; DI void merge_top16(unsigned (&v)[16], int st) {
;     unsigned x[16];
; #pragma unroll
;     for (int i = 0; i < 16; ++i) x[i] = (unsigned)__shfl_xor((int)v[15 - i], st);
; #pragma unroll
;     for (int i = 0; i < 16; ++i) v[i] = max(v[i], x[i]);
; #pragma unroll
;     for (int j = 8; j > 0; j >>= 1)
; #pragma unroll
;         for (int i = 0; i < 16; ++i) { const int l = i ^ j; if (l > i) cswap(v[i], v[l]); }
; DI void topk_phase(unsigned char* smem_, const bf16_t* __restrict__ qp, const bf16_t* __restrict__ keys, int* __restrict__ eidx, float* __restrict__ gate) {
;     ...
;         bitonic_sort_desc<32>(v);
;         unsigned t16[16];
; #pragma unroll
;         for (int i = 0; i < 16; ++i) t16[i] = v[i];
;         merge_top16(t16, 1);
	v_max_u32_e32 v1, v3, v15
	v_min_u32_e32 v3, v3, v15
	v_max_u32_e32 v15, v30, v28
	v_min_u32_e32 v28, v30, v28
	v_max_u32_e32 v30, v29, v2
	v_min_u32_e32 v2, v29, v2
	v_max_u32_e32 v29, v31, v8
	v_min_u32_e32 v8, v31, v8
	v_max_u32_e32 v31, v4, v7
	v_min_u32_e32 v4, v4, v7
	v_max_u32_e32 v7, v18, v11
	v_min_u32_e32 v11, v18, v11
	v_max_u32_e32 v18, v6, v9
	v_min_u32_e32 v6, v6, v9
	v_max_u32_e32 v9, v19, v20
	v_min_u32_e32 v19, v19, v20
	v_max_u32_e32 v20, v17, v16
	v_min_u32_e32 v16, v17, v16
	v_max_u32_e32 v17, v117, v10
	v_min_u32_e32 v10, v117, v10
	v_max_u32_e32 v117, v5, v22
	v_min_u32_e32 v5, v5, v22
	v_max_u32_e32 v22, v0, v21
	v_min_u32_e32 v0, v0, v21
	v_max_u32_e32 v21, v14, v23
	v_min_u32_e32 v14, v14, v23
	v_max_u32_e32 v23, v3, v24
	v_min_u32_e32 v3, v3, v24
	v_max_u32_e32 v24, v1, v12
	v_min_u32_e32 v1, v1, v12
	v_max_u32_e32 v12, v28, v26
	v_min_u32_e32 v26, v28, v26
	v_max_u32_e32 v28, v15, v25
	v_min_u32_e32 v15, v15, v25
	v_max_u32_e32 v25, v2, v27
	v_min_u32_e32 v2, v2, v27
	v_max_u32_e32 v27, v30, v13
	v_min_u32_e32 v13, v30, v13
	v_max_u32_e32 v30, v29, v9
	v_min_u32_e32 v9, v29, v9
	v_max_u32_e32 v29, v31, v20
	v_min_u32_e32 v20, v31, v20
	v_max_u32_e32 v31, v7, v17
	v_min_u32_e32 v7, v7, v17
	v_max_u32_e32 v17, v18, v117
	v_min_u32_e32 v18, v18, v117
	v_max_u32_e32 v117, v8, v19
	v_min_u32_e32 v8, v8, v19
	v_max_u32_e32 v19, v4, v16
	v_min_u32_e32 v4, v4, v16
	v_max_u32_e32 v16, v11, v10
	v_min_u32_e32 v10, v11, v10
	v_max_u32_e32 v11, v6, v5
	v_min_u32_e32 v5, v6, v5
	v_max_u32_e32 v6, v26, v0
	v_min_u32_e32 v0, v26, v0
	v_max_u32_e32 v26, v15, v14
	v_min_u32_e32 v14, v15, v14
	v_max_u32_e32 v15, v2, v3
	v_min_u32_e32 v2, v2, v3
	v_max_u32_e32 v3, v13, v1
	v_min_u32_e32 v1, v13, v1
	v_max_u32_e32 v13, v12, v22
	v_min_u32_e32 v12, v12, v22
	v_max_u32_e32 v22, v28, v21
	v_min_u32_e32 v21, v28, v21
	v_max_u32_e32 v28, v25, v23
	v_min_u32_e32 v23, v25, v23
	v_max_u32_e32 v25, v27, v24
	v_min_u32_e32 v24, v27, v24
	v_max_u32_e32 v27, v30, v31
	v_min_u32_e32 v30, v30, v31
	v_max_u32_e32 v31, v29, v17
	v_min_u32_e32 v17, v29, v17
	v_max_u32_e32 v29, v9, v7
	v_min_u32_e32 v7, v9, v7
	v_max_u32_e32 v9, v20, v18
	v_min_u32_e32 v18, v20, v18
	v_max_u32_e32 v20, v117, v16
	v_min_u32_e32 v16, v117, v16
	v_max_u32_e32 v117, v19, v11
	v_min_u32_e32 v11, v19, v11
	v_max_u32_e32 v19, v8, v10
	v_min_u32_e32 v8, v8, v10
	v_max_u32_e32 v10, v4, v5
	v_min_u32_e32 v4, v4, v5
	v_max_u32_e32 v5, v2, v0
	v_min_u32_e32 v0, v2, v0
	v_max_u32_e32 v2, v1, v14
	v_min_u32_e32 v1, v1, v14
	v_max_u32_e32 v14, v15, v6
	v_min_u32_e32 v6, v15, v6
	v_max_u32_e32 v15, v3, v26
	v_min_u32_e32 v3, v3, v26
	v_max_u32_e32 v26, v23, v12
	v_min_u32_e32 v12, v23, v12
	v_max_u32_e32 v23, v24, v21
	v_min_u32_e32 v21, v24, v21
	v_max_u32_e32 v24, v28, v13
	v_min_u32_e32 v13, v28, v13
	v_max_u32_e32 v28, v25, v22
	v_min_u32_e32 v22, v25, v22
	v_min_u32_e32 v25, v27, v31
	v_min_u32_e32 v118, v30, v17
	v_min_u32_e32 v119, v29, v9
	v_min_u32_e32 v120, v7, v18
	v_min_u32_e32 v121, v20, v117
	v_min_u32_e32 v122, v16, v11
	v_min_u32_e32 v123, v19, v10
	v_min_u32_e32 v124, v8, v4
	v_min_u32_e32 v125, v1, v0
	v_min_u32_e32 v126, v2, v5
	v_min_u32_e32 v127, v3, v6
	v_min_u32_e32 v142, v15, v14
	v_min_u32_e32 v143, v21, v12
	v_min_u32_e32 v144, v23, v26
	v_min_u32_e32 v145, v22, v13
	v_min_u32_e32 v146, v28, v24
	v_max3_u32 v27, v27, v31, v125
	v_max3_u32 v0, v25, v1, v0
	v_max3_u32 v1, v30, v17, v126
	v_max3_u32 v2, v118, v2, v5
	v_max3_u32 v5, v29, v9, v127
	v_max3_u32 v3, v119, v3, v6
	v_max3_u32 v6, v7, v18, v142
	v_max3_u32 v7, v120, v15, v14
	v_max3_u32 v9, v20, v117, v143
	v_max3_u32 v12, v121, v21, v12
	v_max3_u32 v11, v16, v11, v144
	v_max3_u32 v14, v122, v23, v26
	v_max3_u32 v10, v19, v10, v145
	v_max3_u32 v13, v123, v22, v13
	v_max3_u32 v4, v8, v4, v146
	v_max3_u32 v8, v124, v28, v24
	v_max_u32_e32 v15, v27, v9
	v_min_u32_e32 v9, v27, v9
	v_max_u32_e32 v16, v0, v12
	v_min_u32_e32 v0, v0, v12
	v_max_u32_e32 v12, v1, v11
	v_min_u32_e32 v1, v1, v11
	v_max_u32_e32 v11, v2, v14
	v_min_u32_e32 v2, v2, v14
	v_max_u32_e32 v14, v5, v10
	v_min_u32_e32 v5, v5, v10
	v_max_u32_e32 v10, v3, v13
	v_min_u32_e32 v3, v3, v13
	v_max_u32_e32 v13, v6, v4
	v_min_u32_e32 v4, v6, v4
	v_max_u32_e32 v6, v7, v8
	v_min_u32_e32 v7, v7, v8
	v_max_u32_e32 v8, v15, v14
	v_min_u32_e32 v14, v15, v14
	v_max_u32_e32 v15, v16, v10
	v_min_u32_e32 v10, v16, v10
	v_max_u32_e32 v16, v12, v13
	v_min_u32_e32 v12, v12, v13
	v_max_u32_e32 v13, v11, v6
	v_min_u32_e32 v6, v11, v6
	v_max_u32_e32 v11, v9, v5
	v_min_u32_e32 v5, v9, v5
	v_max_u32_e32 v9, v0, v3
	v_min_u32_e32 v0, v0, v3
	v_max_u32_e32 v3, v1, v4
	v_min_u32_e32 v1, v1, v4
	v_max_u32_e32 v4, v2, v7
	v_min_u32_e32 v2, v2, v7
	v_max_u32_e32 v7, v8, v16
	v_min_u32_e32 v8, v8, v16
	v_max_u32_e32 v16, v15, v13
	v_min_u32_e32 v13, v15, v13
	v_max_u32_e32 v15, v14, v12
	v_min_u32_e32 v12, v14, v12
	v_max_u32_e32 v14, v10, v6
	v_min_u32_e32 v6, v10, v6
	v_max_u32_e32 v10, v11, v3
	v_min_u32_e32 v3, v11, v3
	v_max_u32_e32 v11, v9, v4
	v_min_u32_e32 v4, v9, v4
	v_max_u32_e32 v9, v5, v1
	v_min_u32_e32 v1, v5, v1
	v_max_u32_e32 v5, v0, v2
	v_min_u32_e32 v0, v0, v2
	v_max_u32_e32 v2, v7, v16
	v_min_u32_e32 v7, v7, v16
	v_max_u32_e32 v16, v8, v13
	v_min_u32_e32 v8, v8, v13
	v_max_u32_e32 v13, v15, v14
	v_min_u32_e32 v14, v15, v14
	v_max_u32_e32 v15, v12, v6
	v_min_u32_e32 v6, v12, v6
	v_max_u32_e32 v12, v10, v11
	v_min_u32_e32 v10, v10, v11
	v_max_u32_e32 v11, v3, v4
	v_min_u32_e32 v3, v3, v4
	v_max_u32_e32 v4, v9, v5
	v_min_u32_e32 v5, v9, v5
	v_max_u32_e32 v9, v1, v0
	v_min_u32_e32 v0, v1, v0
	s_nop 1
	v_mov_b32_dpp v1, v0 quad_perm:[1,0,3,2] row_mask:0xf bank_mask:0xf
	v_mov_b32_dpp v17, v9 quad_perm:[1,0,3,2] row_mask:0xf bank_mask:0xf
	v_mov_b32_dpp v18, v5 quad_perm:[1,0,3,2] row_mask:0xf bank_mask:0xf
	v_mov_b32_dpp v19, v4 quad_perm:[1,0,3,2] row_mask:0xf bank_mask:0xf
	v_mov_b32_dpp v20, v3 quad_perm:[1,0,3,2] row_mask:0xf bank_mask:0xf
	v_mov_b32_dpp v21, v11 quad_perm:[1,0,3,2] row_mask:0xf bank_mask:0xf
	v_mov_b32_dpp v22, v10 quad_perm:[1,0,3,2] row_mask:0xf bank_mask:0xf
	v_mov_b32_dpp v23, v12 quad_perm:[1,0,3,2] row_mask:0xf bank_mask:0xf
	v_mov_b32_dpp v24, v6 quad_perm:[1,0,3,2] row_mask:0xf bank_mask:0xf
	v_mov_b32_dpp v25, v15 quad_perm:[1,0,3,2] row_mask:0xf bank_mask:0xf
	v_mov_b32_dpp v26, v14 quad_perm:[1,0,3,2] row_mask:0xf bank_mask:0xf
	v_mov_b32_dpp v27, v13 quad_perm:[1,0,3,2] row_mask:0xf bank_mask:0xf
	v_mov_b32_dpp v28, v8 quad_perm:[1,0,3,2] row_mask:0xf bank_mask:0xf
	v_mov_b32_dpp v29, v16 quad_perm:[1,0,3,2] row_mask:0xf bank_mask:0xf
	v_mov_b32_dpp v30, v7 quad_perm:[1,0,3,2] row_mask:0xf bank_mask:0xf
	v_mov_b32_dpp v31, v2 quad_perm:[1,0,3,2] row_mask:0xf bank_mask:0xf
	s_waitcnt lgkmcnt(0)
; DI void merge_top16(unsigned (&v)[16], int st) {
;     unsigned x[16];
; #pragma unroll
;     for (int i = 0; i < 16; ++i) x[i] = (unsigned)__shfl_xor((int)v[15 - i], st);
; #pragma unroll
;     for (int i = 0; i < 16; ++i) v[i] = max(v[i], x[i]);
; #pragma unroll
;     for (int j = 8; j > 0; j >>= 1)
; #pragma unroll
;         for (int i = 0; i < 16; ++i) { const int l = i ^ j; if (l > i) cswap(v[i], v[l]); }
; DI void topk_phase(unsigned char* smem_, const bf16_t* __restrict__ qp, const bf16_t* __restrict__ keys, int* __restrict__ eidx, float* __restrict__ gate) {
;     ...
;         merge_top16(t16, 1);
;         merge_top16(t16, 2);
; #pragma unroll
;         for (int i = 0; i < 16; ++i) if ((i >> 2) == q) { const int idx = 127 - (int)(t16[i] & 127u); SI[row * 32 + 16 * p + i] = idx; SV[row * 32 + 16 * p + i] = S[row * LDS_ + idx]; }
;     }
;     __syncthreads();
;     constexpr unsigned KT[13] = {0x03020100u, 0x07060504u, 0x0b0a0908u, 0x0f0e0d0cu, 0x13121110u, 0x17161514u, 0x23222120u, 0x32313024u, 0x42414033u, 0x61605150u, 0x90807170u, 0xd0c0b0a0u, 0x0000f0e0u};
;     unsigned c16[16];
; #pragma unroll
;     for (int i = 0; i < 13; ++i) {
;         const unsigned ab = (KT[i] >> (8 * q)) & 255u;
;         const float c = SV[row * 32 + (ab >> 4)] + SV[row * 32 + 16 + (ab & 15u)];
	v_max_u32_e32 v1, v2, v1
	v_max_u32_e32 v2, v7, v17
	v_max_u32_e32 v7, v16, v18
	v_max_u32_e32 v8, v8, v19
	v_max_u32_e32 v13, v13, v20
	v_max_u32_e32 v14, v14, v21
	v_max_u32_e32 v15, v15, v22
	v_max_u32_e32 v6, v6, v23
	v_max_u32_e32 v12, v12, v24
	v_max_u32_e32 v10, v10, v25
	v_max_u32_e32 v11, v11, v26
	v_max_u32_e32 v3, v3, v27
	v_max_u32_e32 v4, v4, v28
	v_max_u32_e32 v5, v5, v29
	v_max_u32_e32 v9, v9, v30
	v_max_u32_e32 v0, v0, v31
	v_max_u32_e32 v16, v1, v12
	v_min_u32_e32 v1, v1, v12
	v_max_u32_e32 v12, v2, v10
	v_min_u32_e32 v2, v2, v10
	v_max_u32_e32 v10, v7, v11
	v_min_u32_e32 v7, v7, v11
	v_max_u32_e32 v11, v8, v3
	v_min_u32_e32 v3, v8, v3
	v_max_u32_e32 v8, v13, v4
	v_min_u32_e32 v4, v13, v4
	v_max_u32_e32 v13, v14, v5
	v_min_u32_e32 v5, v14, v5
	v_max_u32_e32 v14, v15, v9
	v_min_u32_e32 v9, v15, v9
	v_max_u32_e32 v15, v6, v0
	v_min_u32_e32 v0, v6, v0
	v_max_u32_e32 v6, v16, v8
	v_min_u32_e32 v8, v16, v8
	v_max_u32_e32 v16, v12, v13
	v_min_u32_e32 v12, v12, v13
	v_max_u32_e32 v13, v10, v14
	v_min_u32_e32 v10, v10, v14
	v_max_u32_e32 v14, v11, v15
	v_min_u32_e32 v11, v11, v15
	v_max_u32_e32 v15, v1, v4
	v_min_u32_e32 v1, v1, v4
	v_max_u32_e32 v4, v2, v5
	v_min_u32_e32 v2, v2, v5
	v_max_u32_e32 v5, v7, v9
	v_min_u32_e32 v7, v7, v9
	v_max_u32_e32 v9, v3, v0
	v_min_u32_e32 v0, v3, v0
	v_max_u32_e32 v3, v6, v13
	v_min_u32_e32 v6, v6, v13
	v_max_u32_e32 v13, v16, v14
	v_min_u32_e32 v14, v16, v14
	v_max_u32_e32 v16, v8, v10
	v_min_u32_e32 v8, v8, v10
	v_max_u32_e32 v10, v12, v11
	v_min_u32_e32 v11, v12, v11
	v_max_u32_e32 v12, v15, v5
	v_min_u32_e32 v5, v15, v5
	v_max_u32_e32 v15, v4, v9
	v_min_u32_e32 v4, v4, v9
	v_max_u32_e32 v9, v1, v7
	v_min_u32_e32 v1, v1, v7
	v_max_u32_e32 v7, v2, v0
	v_min_u32_e32 v0, v2, v0
	v_max_u32_e32 v2, v3, v13
	v_min_u32_e32 v3, v3, v13
	v_max_u32_e32 v13, v6, v14
	v_min_u32_e32 v6, v6, v14
	v_max_u32_e32 v14, v16, v10
	v_min_u32_e32 v10, v16, v10
	v_max_u32_e32 v16, v8, v11
	v_min_u32_e32 v8, v8, v11
	v_max_u32_e32 v11, v12, v15
	v_min_u32_e32 v12, v12, v15
	v_max_u32_e32 v15, v5, v4
	v_min_u32_e32 v17, v5, v4
	v_max_u32_e32 v18, v9, v7
	v_min_u32_e32 v19, v9, v7
	v_max_u32_e32 v20, v1, v0
	v_min_u32_e32 v21, v1, v0
	s_nop 1
	v_mov_b32_dpp v0, v21 quad_perm:[2,3,0,1] row_mask:0xf bank_mask:0xf
	v_mov_b32_dpp v1, v20 quad_perm:[2,3,0,1] row_mask:0xf bank_mask:0xf
	v_mov_b32_dpp v4, v19 quad_perm:[2,3,0,1] row_mask:0xf bank_mask:0xf
	v_mov_b32_dpp v5, v18 quad_perm:[2,3,0,1] row_mask:0xf bank_mask:0xf
	v_mov_b32_dpp v7, v17 quad_perm:[2,3,0,1] row_mask:0xf bank_mask:0xf
	v_mov_b32_dpp v9, v15 quad_perm:[2,3,0,1] row_mask:0xf bank_mask:0xf
	v_mov_b32_dpp v22, v12 quad_perm:[2,3,0,1] row_mask:0xf bank_mask:0xf
	v_mov_b32_dpp v23, v11 quad_perm:[2,3,0,1] row_mask:0xf bank_mask:0xf
	v_mov_b32_dpp v24, v8 quad_perm:[2,3,0,1] row_mask:0xf bank_mask:0xf
	v_mov_b32_dpp v25, v16 quad_perm:[2,3,0,1] row_mask:0xf bank_mask:0xf
	v_mov_b32_dpp v26, v10 quad_perm:[2,3,0,1] row_mask:0xf bank_mask:0xf
	v_mov_b32_dpp v27, v14 quad_perm:[2,3,0,1] row_mask:0xf bank_mask:0xf
	v_mov_b32_dpp v28, v6 quad_perm:[2,3,0,1] row_mask:0xf bank_mask:0xf
	v_mov_b32_dpp v29, v13 quad_perm:[2,3,0,1] row_mask:0xf bank_mask:0xf
	v_mov_b32_dpp v30, v3 quad_perm:[2,3,0,1] row_mask:0xf bank_mask:0xf
	v_mov_b32_dpp v31, v2 quad_perm:[2,3,0,1] row_mask:0xf bank_mask:0xf
	s_waitcnt lgkmcnt(0)
	v_max_u32_e32 v0, v2, v0
	v_max_u32_e32 v1, v3, v1
	v_max_u32_e32 v2, v13, v4
	v_max_u32_e32 v3, v6, v5
	v_max_u32_e32 v4, v14, v7
	v_max_u32_e32 v5, v10, v9
	v_max_u32_e32 v6, v16, v22
	v_max_u32_e32 v7, v8, v23
	v_max_u32_e32 v8, v11, v24
	v_max_u32_e32 v9, v12, v25
	v_max_u32_e32 v10, v15, v26
	v_max_u32_e32 v11, v17, v27
	v_max_u32_e32 v12, v18, v28
	v_max_u32_e32 v13, v19, v29
	v_max_u32_e32 v14, v20, v30
	v_max_u32_e32 v15, v21, v31
	v_max_u32_e32 v16, v0, v8
	v_max_u32_e32 v17, v1, v9
	v_max_u32_e32 v18, v2, v10
	v_max_u32_e32 v19, v3, v11
	v_max_u32_e32 v20, v4, v12
	v_max_u32_e32 v21, v5, v13
	v_max_u32_e32 v22, v6, v14
	v_max_u32_e32 v23, v7, v15
	s_or_b64 s[16:17], s[4:5], s[6:7]
	s_or_b64 vcc, s[6:7], s[10:11]
	v_min_u32_e32 v0, v0, v8
	v_min_u32_e32 v1, v1, v9
	v_min_u32_e32 v2, v2, v10
	v_min_u32_e32 v3, v3, v11
	v_min_u32_e32 v4, v4, v12
	v_min_u32_e32 v5, v5, v13
	v_min_u32_e32 v6, v6, v14
	v_min_u32_e32 v7, v7, v15
	v_cndmask_b32_e64 v0, v0, v16, s[16:17]
	v_cndmask_b32_e64 v1, v1, v17, s[16:17]
	v_cndmask_b32_e64 v2, v2, v18, s[16:17]
	v_cndmask_b32_e64 v3, v3, v19, s[16:17]
	v_cndmask_b32_e64 v4, v4, v20, s[16:17]
	v_cndmask_b32_e64 v5, v5, v21, s[16:17]
	v_cndmask_b32_e64 v6, v6, v22, s[16:17]
	v_cndmask_b32_e64 v7, v7, v23, s[16:17]
	v_max_u32_e32 v8, v0, v4
	v_max_u32_e32 v9, v1, v5
	v_max_u32_e32 v10, v2, v6
	v_max_u32_e32 v11, v3, v7
	v_min_u32_e32 v12, v0, v4
	v_min_u32_e32 v13, v1, v5
	v_min_u32_e32 v14, v2, v6
	v_min_u32_e32 v15, v3, v7
	v_cndmask_b32_e32 v0, v8, v12, vcc
	v_cndmask_b32_e32 v1, v9, v13, vcc
	v_cndmask_b32_e32 v2, v10, v14, vcc
	v_cndmask_b32_e32 v3, v11, v15, vcc
	v_max_u32_e32 v4, v0, v2
	v_min_u32_e32 v5, v0, v2
	v_max_u32_e32 v6, v1, v3
	v_min_u32_e32 v7, v1, v3
	v_max_u32_e32 v0, v4, v6
	v_min_u32_e32 v1, v4, v6
	v_max_u32_e32 v2, v5, v7
	v_min_u32_e32 v3, v5, v7
	v_xor_b32_e32 v0, -1, v0
	v_xor_b32_e32 v1, -1, v1
	v_xor_b32_e32 v2, -1, v2
	v_xor_b32_e32 v3, -1, v3
	v_and_b32_e32 v0, 0x7f, v0
	v_and_b32_e32 v1, 0x7f, v1
	v_and_b32_e32 v2, 0x7f, v2
	v_and_b32_e32 v3, 0x7f, v3
	v_lshl_add_u32 v4, v0, 2, v169
	v_lshl_add_u32 v5, v1, 2, v169
	v_lshl_add_u32 v6, v2, 2, v169
	v_lshl_add_u32 v7, v3, 2, v169
	ds_read_b32 v4, v4 offset:17408
	ds_read_b32 v5, v5 offset:17408
	ds_read_b32 v6, v6 offset:17408
	ds_read_b32 v7, v7 offset:17408
	ds_write_b128 v253, v[0:3] offset:61504
	s_waitcnt lgkmcnt(1)
	ds_write_b128 v253, v[4:7] offset:53312
	s_waitcnt lgkmcnt(0)
	s_barrier
	ds_read_b96 v[0:2], v175 offset:53248
	ds_read_b32 v5, v186 offset:53312
	ds_read_b32 v3, v188 offset:53312
	ds_read_b32 v4, v175 offset:53312
	s_mov_b32 s16, 0xff61b1e6
	s_waitcnt lgkmcnt(3)
	v_mov_b32_e32 v7, v2
	s_waitcnt lgkmcnt(2)
	v_add_f32_e32 v2, v0, v5
	v_ashrrev_i32_e32 v5, 31, v2


; DI unsigned fkey(float f) { const unsigned u = __float_as_uint(f); return (u & 0x80000000u) ? ~u : (u | 0x80000000u); }
; DI void topk_phase(unsigned char* smem_, const bf16_t* __restrict__ qp, const bf16_t* __restrict__ keys, int* __restrict__ eidx, float* __restrict__ gate) {
;     ...
;     for (int i = 0; i < 13; ++i) {
;         const unsigned ab = (KT[i] >> (8 * q)) & 255u;
;         const float c = SV[row * 32 + (ab >> 4)] + SV[row * 32 + 16 + (ab & 15u)];
;         c16[i] = (fkey(c) & ~255u) | (255u - ab);
;     }
	v_mov_b32_e32 v6, v1
	v_or_b32_e32 v158, s24, v164
	v_bitop3_b32 v2, v5, s98, v2 bitop3:0x56

; DI unsigned fkey(float f) { const unsigned u = __float_as_uint(f); return (u & 0x80000000u) ? ~u : (u | 0x80000000u); }
; DI void topk_phase(unsigned char* smem_, const bf16_t* __restrict__ qp, const bf16_t* __restrict__ keys, int* __restrict__ eidx, float* __restrict__ gate) {
;     ...
;     for (int i = 0; i < 13; ++i) {
;         const unsigned ab = (KT[i] >> (8 * q)) & 255u;
;         const float c = SV[row * 32 + (ab >> 4)] + SV[row * 32 + 16 + (ab & 15u)];
;         c16[i] = (fkey(c) & ~255u) | (255u - ab);
;     }
	v_bitop3_b32 v5, v2, s71, v185 bitop3:0x76
	ds_read_b32 v2, v190 offset:53312
	ds_read_b32 v9, v211 offset:53312
	ds_read_b32 v8, v213 offset:53312
	ds_read_b32 v10, v215 offset:53312
	ds_read_b32 v11, v217 offset:53312
	ds_read_b32 v13, v219 offset:53248
	ds_read_b32 v15, v220 offset:53312
	ds_read_b32 v12, v222 offset:53248
	s_waitcnt lgkmcnt(7)
	v_pk_add_f32 v[2:3], v[0:1], v[2:3] op_sel_hi:[0,1]
	v_ashrrev_i32_e32 v14, 31, v3


; DI unsigned fkey(float f) { const unsigned u = __float_as_uint(f); return (u & 0x80000000u) ? ~u : (u | 0x80000000u); }
; DI void topk_phase(unsigned char* smem_, const bf16_t* __restrict__ qp, const bf16_t* __restrict__ keys, int* __restrict__ eidx, float* __restrict__ gate) {
;     ...
;     for (int i = 0; i < 13; ++i) {
;         const unsigned ab = (KT[i] >> (8 * q)) & 255u;
;         const float c = SV[row * 32 + (ab >> 4)] + SV[row * 32 + 16 + (ab & 15u)];
;         c16[i] = (fkey(c) & ~255u) | (255u - ab);
;     }
	v_ashrrev_i32_e32 v159, 31, v158
	v_lshlrev_b64 v[158:159], 7, v[158:159]
	v_bitop3_b32 v3, v14, s98, v3 bitop3:0x56

; DI unsigned fkey(float f) { const unsigned u = __float_as_uint(f); return (u & 0x80000000u) ? ~u : (u | 0x80000000u); }
; DI void topk_phase(unsigned char* smem_, const bf16_t* __restrict__ qp, const bf16_t* __restrict__ keys, int* __restrict__ eidx, float* __restrict__ gate) {
;     ...
;     for (int i = 0; i < 13; ++i) {
;         const unsigned ab = (KT[i] >> (8 * q)) & 255u;
;         const float c = SV[row * 32 + (ab >> 4)] + SV[row * 32 + 16 + (ab & 15u)];
;         c16[i] = (fkey(c) & ~255u) | (255u - ab);
;     }
	v_bitop3_b32 v16, v3, s71, v187 bitop3:0x76
	v_ashrrev_i32_e32 v3, 31, v2


; DI unsigned fkey(float f) { const unsigned u = __float_as_uint(f); return (u & 0x80000000u) ? ~u : (u | 0x80000000u); }
; DI void topk_phase(unsigned char* smem_, const bf16_t* __restrict__ qp, const bf16_t* __restrict__ keys, int* __restrict__ eidx, float* __restrict__ gate) {
;     ...
;     for (int i = 0; i < 13; ++i) {
;         const unsigned ab = (KT[i] >> (8 * q)) & 255u;
;         const float c = SV[row * 32 + (ab >> 4)] + SV[row * 32 + 16 + (ab & 15u)];
;         c16[i] = (fkey(c) & ~255u) | (255u - ab);
;     }
	v_lshl_or_b32 v158, s23, 4, v158
	v_lshlrev_b64 v[158:159], 2, v[158:159]
	v_bitop3_b32 v2, v3, s98, v2 bitop3:0x56

; DI unsigned fkey(float f) { const unsigned u = __float_as_uint(f); return (u & 0x80000000u) ? ~u : (u | 0x80000000u); }
; DI void topk_phase(unsigned char* smem_, const bf16_t* __restrict__ qp, const bf16_t* __restrict__ keys, int* __restrict__ eidx, float* __restrict__ gate) {
;     ...
;     for (int i = 0; i < 13; ++i) {
;         const unsigned ab = (KT[i] >> (8 * q)) & 255u;
;         const float c = SV[row * 32 + (ab >> 4)] + SV[row * 32 + 16 + (ab & 15u)];
;         c16[i] = (fkey(c) & ~255u) | (255u - ab);
;     }
	v_bitop3_b32 v17, v2, s71, v189 bitop3:0x76
	v_mov_b32_e32 v2, v1
	v_mov_b32_e32 v3, v0
	s_waitcnt lgkmcnt(5)
	v_pk_add_f32 v[0:1], v[2:3], v[8:9]
	s_nop 0
	v_ashrrev_i32_e32 v2, 31, v1


; DI unsigned fkey(float f) { const unsigned u = __float_as_uint(f); return (u & 0x80000000u) ? ~u : (u | 0x80000000u); }
; DI void topk_phase(unsigned char* smem_, const bf16_t* __restrict__ qp, const bf16_t* __restrict__ keys, int* __restrict__ eidx, float* __restrict__ gate) {
;     ...
;     for (int i = 0; i < 13; ++i) {
;         const unsigned ab = (KT[i] >> (8 * q)) & 255u;
;         const float c = SV[row * 32 + (ab >> 4)] + SV[row * 32 + 16 + (ab & 15u)];
;         c16[i] = (fkey(c) & ~255u) | (255u - ab);
;     }
	s_nop 1
	v_bitop3_b32 v1, v2, s98, v1 bitop3:0x56

; DI unsigned fkey(float f) { const unsigned u = __float_as_uint(f); return (u & 0x80000000u) ? ~u : (u | 0x80000000u); }
; DI void topk_phase(unsigned char* smem_, const bf16_t* __restrict__ qp, const bf16_t* __restrict__ keys, int* __restrict__ eidx, float* __restrict__ gate) {
;     ...
;     for (int i = 0; i < 13; ++i) {
;         const unsigned ab = (KT[i] >> (8 * q)) & 255u;
;         const float c = SV[row * 32 + (ab >> 4)] + SV[row * 32 + 16 + (ab & 15u)];
;         c16[i] = (fkey(c) & ~255u) | (255u - ab);
;     }
	v_bitop3_b32 v18, v1, s71, v191 bitop3:0x76
	v_ashrrev_i32_e32 v1, 31, v0


; DI unsigned fkey(float f) { const unsigned u = __float_as_uint(f); return (u & 0x80000000u) ? ~u : (u | 0x80000000u); }
; DI void topk_phase(unsigned char* smem_, const bf16_t* __restrict__ qp, const bf16_t* __restrict__ keys, int* __restrict__ eidx, float* __restrict__ gate) {
;     ...
;     for (int i = 0; i < 13; ++i) {
;         const unsigned ab = (KT[i] >> (8 * q)) & 255u;
;         const float c = SV[row * 32 + (ab >> 4)] + SV[row * 32 + 16 + (ab & 15u)];
;         c16[i] = (fkey(c) & ~255u) | (255u - ab);
;     }
	s_nop 1
	v_bitop3_b32 v0, v1, s98, v0 bitop3:0x56

; DI unsigned fkey(float f) { const unsigned u = __float_as_uint(f); return (u & 0x80000000u) ? ~u : (u | 0x80000000u); }
; DI void topk_phase(unsigned char* smem_, const bf16_t* __restrict__ qp, const bf16_t* __restrict__ keys, int* __restrict__ eidx, float* __restrict__ gate) {
;     ...
;     for (int i = 0; i < 13; ++i) {
;         const unsigned ab = (KT[i] >> (8 * q)) & 255u;
;         const float c = SV[row * 32 + (ab >> 4)] + SV[row * 32 + 16 + (ab & 15u)];
;         c16[i] = (fkey(c) & ~255u) | (255u - ab);
;     }
	v_bitop3_b32 v19, v0, s71, v212 bitop3:0x76
	s_waitcnt lgkmcnt(3)
	v_pk_add_f32 v[0:1], v[6:7], v[10:11]
	s_nop 0
	v_ashrrev_i32_e32 v2, 31, v0


; DI unsigned fkey(float f) { const unsigned u = __float_as_uint(f); return (u & 0x80000000u) ? ~u : (u | 0x80000000u); }
; DI void topk_phase(unsigned char* smem_, const bf16_t* __restrict__ qp, const bf16_t* __restrict__ keys, int* __restrict__ eidx, float* __restrict__ gate) {
;     ...
;     for (int i = 0; i < 13; ++i) {
;         const unsigned ab = (KT[i] >> (8 * q)) & 255u;
;         const float c = SV[row * 32 + (ab >> 4)] + SV[row * 32 + 16 + (ab & 15u)];
;         c16[i] = (fkey(c) & ~255u) | (255u - ab);
;     }
	s_nop 1
	v_bitop3_b32 v0, v2, s98, v0 bitop3:0x56

; DI unsigned fkey(float f) { const unsigned u = __float_as_uint(f); return (u & 0x80000000u) ? ~u : (u | 0x80000000u); }
; DI void topk_phase(unsigned char* smem_, const bf16_t* __restrict__ qp, const bf16_t* __restrict__ keys, int* __restrict__ eidx, float* __restrict__ gate) {
;     ...
;     for (int i = 0; i < 13; ++i) {
;         const unsigned ab = (KT[i] >> (8 * q)) & 255u;
;         const float c = SV[row * 32 + (ab >> 4)] + SV[row * 32 + 16 + (ab & 15u)];
;         c16[i] = (fkey(c) & ~255u) | (255u - ab);
;     }
	v_bitop3_b32 v10, v0, s71, v214 bitop3:0x76
	v_ashrrev_i32_e32 v0, 31, v1


; DI unsigned fkey(float f) { const unsigned u = __float_as_uint(f); return (u & 0x80000000u) ? ~u : (u | 0x80000000u); }
; DI void topk_phase(unsigned char* smem_, const bf16_t* __restrict__ qp, const bf16_t* __restrict__ keys, int* __restrict__ eidx, float* __restrict__ gate) {
;     ...
;     for (int i = 0; i < 13; ++i) {
;         const unsigned ab = (KT[i] >> (8 * q)) & 255u;
;         const float c = SV[row * 32 + (ab >> 4)] + SV[row * 32 + 16 + (ab & 15u)];
;         c16[i] = (fkey(c) & ~255u) | (255u - ab);
;     }
	s_nop 1
	v_bitop3_b32 v0, v0, s98, v1 bitop3:0x56

; DI unsigned fkey(float f) { const unsigned u = __float_as_uint(f); return (u & 0x80000000u) ? ~u : (u | 0x80000000u); }
; DI void topk_phase(unsigned char* smem_, const bf16_t* __restrict__ qp, const bf16_t* __restrict__ keys, int* __restrict__ eidx, float* __restrict__ gate) {
;     ...
;     for (int i = 0; i < 13; ++i) {
;         const unsigned ab = (KT[i] >> (8 * q)) & 255u;
;         const float c = SV[row * 32 + (ab >> 4)] + SV[row * 32 + 16 + (ab & 15u)];
;         c16[i] = (fkey(c) & ~255u) | (255u - ab);
;     }
	v_bitop3_b32 v11, v0, s71, v216 bitop3:0x76
	ds_read_b32 v14, v223 offset:53312
	ds_read_b32 v1, v225 offset:53248
	ds_read_b32 v3, v226 offset:53312
	ds_read_b32 v0, v228 offset:53248
	ds_read_b32 v2, v229 offset:53312
	ds_read_b32 v7, v232 offset:53248
	ds_read_b32 v6, v233 offset:53248
	s_waitcnt lgkmcnt(6)
	v_pk_add_f32 v[8:9], v[12:13], v[14:15]
	s_waitcnt lgkmcnt(2)
	v_pk_add_f32 v[0:1], v[0:1], v[2:3]
	v_ashrrev_i32_e32 v12, 31, v9


; DI unsigned fkey(float f) { const unsigned u = __float_as_uint(f); return (u & 0x80000000u) ? ~u : (u | 0x80000000u); }
; DI void topk_phase(unsigned char* smem_, const bf16_t* __restrict__ qp, const bf16_t* __restrict__ keys, int* __restrict__ eidx, float* __restrict__ gate) {
;     ...
;     for (int i = 0; i < 13; ++i) {
;         const unsigned ab = (KT[i] >> (8 * q)) & 255u;
;         const float c = SV[row * 32 + (ab >> 4)] + SV[row * 32 + 16 + (ab & 15u)];
;         c16[i] = (fkey(c) & ~255u) | (255u - ab);
;     }
	v_ashrrev_i32_e32 v2, 31, v1

; DI unsigned fkey(float f) { const unsigned u = __float_as_uint(f); return (u & 0x80000000u) ? ~u : (u | 0x80000000u); }
; DI void topk_phase(unsigned char* smem_, const bf16_t* __restrict__ qp, const bf16_t* __restrict__ keys, int* __restrict__ eidx, float* __restrict__ gate) {
;     ...
;     for (int i = 0; i < 13; ++i) {
;         const unsigned ab = (KT[i] >> (8 * q)) & 255u;
;         const float c = SV[row * 32 + (ab >> 4)] + SV[row * 32 + 16 + (ab & 15u)];
;         c16[i] = (fkey(c) & ~255u) | (255u - ab);
;     }
	v_bitop3_b32 v9, v12, s98, v9 bitop3:0x56
	v_ashrrev_i32_e32 v12, 31, v8


; DI unsigned fkey(float f) { const unsigned u = __float_as_uint(f); return (u & 0x80000000u) ? ~u : (u | 0x80000000u); }
; DI void topk_phase(unsigned char* smem_, const bf16_t* __restrict__ qp, const bf16_t* __restrict__ keys, int* __restrict__ eidx, float* __restrict__ gate) {
;     ...
;     for (int i = 0; i < 13; ++i) {
;         const unsigned ab = (KT[i] >> (8 * q)) & 255u;
;         const float c = SV[row * 32 + (ab >> 4)] + SV[row * 32 + 16 + (ab & 15u)];
;         c16[i] = (fkey(c) & ~255u) | (255u - ab);
;     }
	v_bitop3_b32 v9, v9, s71, v218 bitop3:0x76
	v_bitop3_b32 v8, v12, s98, v8 bitop3:0x56


; DI unsigned fkey(float f) { const unsigned u = __float_as_uint(f); return (u & 0x80000000u) ? ~u : (u | 0x80000000u); }
; DI void topk_phase(unsigned char* smem_, const bf16_t* __restrict__ qp, const bf16_t* __restrict__ keys, int* __restrict__ eidx, float* __restrict__ gate) {
;     ...
;     for (int i = 0; i < 13; ++i) {
;         const unsigned ab = (KT[i] >> (8 * q)) & 255u;
;         const float c = SV[row * 32 + (ab >> 4)] + SV[row * 32 + 16 + (ab & 15u)];
;         c16[i] = (fkey(c) & ~255u) | (255u - ab);
;     }
	v_bitop3_b32 v8, v8, s71, v221 bitop3:0x76
	v_bitop3_b32 v1, v2, s98, v1 bitop3:0x56

; DI unsigned fkey(float f) { const unsigned u = __float_as_uint(f); return (u & 0x80000000u) ? ~u : (u | 0x80000000u); }
; DI void topk_phase(unsigned char* smem_, const bf16_t* __restrict__ qp, const bf16_t* __restrict__ keys, int* __restrict__ eidx, float* __restrict__ gate) {
;     ...
;     for (int i = 0; i < 13; ++i) {
;         const unsigned ab = (KT[i] >> (8 * q)) & 255u;
;         const float c = SV[row * 32 + (ab >> 4)] + SV[row * 32 + 16 + (ab & 15u)];
;         c16[i] = (fkey(c) & ~255u) | (255u - ab);
;     }
	v_bitop3_b32 v2, v1, s71, v224 bitop3:0x76
	v_ashrrev_i32_e32 v1, 31, v0


; DI unsigned fkey(float f) { const unsigned u = __float_as_uint(f); return (u & 0x80000000u) ? ~u : (u | 0x80000000u); }
; DI void topk_phase(unsigned char* smem_, const bf16_t* __restrict__ qp, const bf16_t* __restrict__ keys, int* __restrict__ eidx, float* __restrict__ gate) {
;     ...
;     for (int i = 0; i < 13; ++i) {
;         const unsigned ab = (KT[i] >> (8 * q)) & 255u;
;         const float c = SV[row * 32 + (ab >> 4)] + SV[row * 32 + 16 + (ab & 15u)];
;         c16[i] = (fkey(c) & ~255u) | (255u - ab);
;     }
	v_max_u32_e32 v12, v19, v10
	v_min_u32_e32 v10, v19, v10
	v_bitop3_b32 v0, v1, s98, v0 bitop3:0x56

; DI unsigned fkey(float f) { const unsigned u = __float_as_uint(f); return (u & 0x80000000u) ? ~u : (u | 0x80000000u); }
; DI void topk_phase(unsigned char* smem_, const bf16_t* __restrict__ qp, const bf16_t* __restrict__ keys, int* __restrict__ eidx, float* __restrict__ gate) {
;     ...
;     for (int i = 0; i < 13; ++i) {
;         const unsigned ab = (KT[i] >> (8 * q)) & 255u;
;         const float c = SV[row * 32 + (ab >> 4)] + SV[row * 32 + 16 + (ab & 15u)];
;         c16[i] = (fkey(c) & ~255u) | (255u - ab);
;     }
	v_bitop3_b32 v3, v0, s71, v227 bitop3:0x76
	s_waitcnt lgkmcnt(0)
	v_pk_add_f32 v[0:1], v[6:7], v[4:5] op_sel_hi:[1,0]
	v_min_u32_e32 v7, v18, v17
	v_ashrrev_i32_e32 v4, 31, v1


; DI unsigned fkey(float f) { const unsigned u = __float_as_uint(f); return (u & 0x80000000u) ? ~u : (u | 0x80000000u); }
; DI void topk_phase(unsigned char* smem_, const bf16_t* __restrict__ qp, const bf16_t* __restrict__ keys, int* __restrict__ eidx, float* __restrict__ gate) {
;     ...
;     for (int i = 0; i < 13; ++i) {
;         const unsigned ab = (KT[i] >> (8 * q)) & 255u;
;         const float c = SV[row * 32 + (ab >> 4)] + SV[row * 32 + 16 + (ab & 15u)];
;         c16[i] = (fkey(c) & ~255u) | (255u - ab);
;     }
	v_max_u32_e32 v13, v9, v11
	v_min_u32_e32 v9, v9, v11
	v_bitop3_b32 v1, v4, s98, v1 bitop3:0x56

; DI unsigned fkey(float f) { const unsigned u = __float_as_uint(f); return (u & 0x80000000u) ? ~u : (u | 0x80000000u); }
; DI void topk_phase(unsigned char* smem_, const bf16_t* __restrict__ qp, const bf16_t* __restrict__ keys, int* __restrict__ eidx, float* __restrict__ gate) {
;     ...
;     for (int i = 0; i < 13; ++i) {
;         const unsigned ab = (KT[i] >> (8 * q)) & 255u;
;         const float c = SV[row * 32 + (ab >> 4)] + SV[row * 32 + 16 + (ab & 15u)];
;         c16[i] = (fkey(c) & ~255u) | (255u - ab);
;     }
	v_ashrrev_i32_e32 v4, 31, v0


; DI unsigned fkey(float f) { const unsigned u = __float_as_uint(f); return (u & 0x80000000u) ? ~u : (u | 0x80000000u); }
; DI void topk_phase(unsigned char* smem_, const bf16_t* __restrict__ qp, const bf16_t* __restrict__ keys, int* __restrict__ eidx, float* __restrict__ gate) {
;     ...
;     for (int i = 0; i < 13; ++i) {
;         const unsigned ab = (KT[i] >> (8 * q)) & 255u;
;         const float c = SV[row * 32 + (ab >> 4)] + SV[row * 32 + 16 + (ab & 15u)];
;         c16[i] = (fkey(c) & ~255u) | (255u - ab);
;     }
	v_bitop3_b32 v1, v1, s71, v230 bitop3:0x76
	v_max_u32_e32 v11, v8, v2
	v_bitop3_b32 v0, v4, s98, v0 bitop3:0x56

; template <int N> DI void bitonic_sort_desc(unsigned (&v)[N]) {
; #pragma unroll
;     for (int k = 2; k <= N; k <<= 1)
; #pragma unroll
;         for (int j = k >> 1; j > 0; j >>= 1)
; #pragma unroll
;             for (int i = 0; i < N; ++i) { const int l = i ^ j; if (l > i) { if ((i & k) == 0) cswap(v[i], v[l]); else cswap(v[l], v[i]); } }
; }
; DI void merge_top16(unsigned (&v)[16], int st) {
;     unsigned x[16];
; #pragma unroll
;     for (int i = 0; i < 16; ++i) x[i] = (unsigned)__shfl_xor((int)v[15 - i], st);
; #pragma unroll
;     for (int i = 0; i < 16; ++i) v[i] = max(v[i], x[i]);
; #pragma unroll
;     for (int j = 8; j > 0; j >>= 1)
; #pragma unroll
;         for (int i = 0; i < 16; ++i) { const int l = i ^ j; if (l > i) cswap(v[i], v[l]); }
; DI void topk_phase(unsigned char* smem_, const bf16_t* __restrict__ qp, const bf16_t* __restrict__ keys, int* __restrict__ eidx, float* __restrict__ gate) {
;     ...
;     if (q >= 2) c16[12] = 0u;
;     c16[13] = 0u; c16[14] = 0u; c16[15] = 0u;
;     bitonic_sort_desc<16>(c16);
;     merge_top16(c16, 1);
;     merge_top16(c16, 2);
	v_max_u32_e32 v4, v5, v16
	v_min_u32_e32 v5, v5, v16
	v_max_u32_e32 v6, v18, v17
	v_min_u32_e32 v2, v8, v2
	v_max_u32_e32 v8, v1, v3
	v_min_u32_e32 v1, v1, v3
	v_bitop3_b32 v0, v0, s71, v231 bitop3:0x76
	v_max_u32_e32 v3, v4, v7
	v_min_u32_e32 v4, v4, v7
	v_max_u32_e32 v7, v5, v6
	v_min_u32_e32 v5, v5, v6
	v_max_u32_e32 v6, v9, v12
	v_min_u32_e32 v9, v9, v12
	v_max_u32_e32 v12, v13, v10
	v_min_u32_e32 v10, v13, v10
	v_max_u32_e32 v13, v11, v1
	v_min_u32_e32 v1, v11, v1
	v_max_u32_e32 v11, v2, v8
	v_min_u32_e32 v2, v2, v8
	v_cndmask_b32_e64 v0, v0, 0, s[2:3]
	v_max_u32_e32 v8, v3, v7
	v_min_u32_e32 v3, v3, v7
	v_max_u32_e32 v7, v4, v5
	v_min_u32_e32 v4, v4, v5
	v_max_u32_e32 v5, v10, v9
	v_min_u32_e32 v9, v10, v9
	v_max_u32_e32 v10, v12, v6
	v_min_u32_e32 v6, v12, v6
	v_max_u32_e32 v12, v13, v11
	v_min_u32_e32 v11, v13, v11
	v_max_u32_e32 v13, v1, v2
	v_min_u32_e32 v1, v1, v2
	v_max_u32_e32 v2, v8, v9
	v_min_u32_e32 v8, v8, v9
	v_max_u32_e32 v9, v3, v5
	v_min_u32_e32 v3, v3, v5
	v_max_u32_e32 v5, v7, v6
	v_min_u32_e32 v6, v7, v6
	v_max_u32_e32 v7, v4, v10
	v_min_u32_e32 v4, v4, v10
	v_max_u32_e32 v10, v0, v1
	v_min_u32_e32 v0, v0, v1
	v_max_u32_e32 v1, v2, v5
	v_min_u32_e32 v2, v2, v5
	v_max_u32_e32 v5, v9, v7
	v_min_u32_e32 v7, v9, v7
	v_max_u32_e32 v9, v8, v6
	v_min_u32_e32 v6, v8, v6
	v_max_u32_e32 v8, v3, v4
	v_min_u32_e32 v3, v3, v4
	v_max_u32_e32 v4, v13, v12
	v_min_u32_e32 v12, v13, v12
	v_max_u32_e32 v13, v10, v11
	v_min_u32_e32 v10, v10, v11
	v_max_u32_e32 v11, v1, v5
	v_min_u32_e32 v1, v1, v5
	v_max_u32_e32 v5, v2, v7
	v_min_u32_e32 v2, v2, v7
	v_max_u32_e32 v7, v9, v8
	v_min_u32_e32 v8, v9, v8
	v_max_u32_e32 v9, v6, v3
	v_min_u32_e32 v3, v6, v3
	v_max_u32_e32 v6, v10, v12
	v_min_u32_e32 v10, v10, v12
	v_max_u32_e32 v12, v13, v4
	v_min_u32_e32 v4, v13, v4
	v_max_u32_e32 v13, v2, v0
	v_min_u32_e32 v0, v2, v0
	v_max_u32_e32 v2, v7, v10
	v_min_u32_e32 v7, v7, v10
	v_max_u32_e32 v10, v8, v6
	v_min_u32_e32 v6, v8, v6
	v_max_u32_e32 v8, v9, v4
	v_min_u32_e32 v4, v9, v4
	v_max_u32_e32 v9, v3, v12
	v_min_u32_e32 v3, v3, v12
	v_max_u32_e32 v12, v11, v2
	v_min_u32_e32 v2, v11, v2
	v_max_u32_e32 v11, v1, v10
	v_min_u32_e32 v1, v1, v10
	v_max_u32_e32 v10, v5, v8
	v_min_u32_e32 v5, v5, v8
	v_max_u32_e32 v8, v13, v9
	v_min_u32_e32 v9, v13, v9
	v_max_u32_e32 v13, v0, v3
	v_min_u32_e32 v0, v0, v3
	v_max_u32_e32 v3, v12, v10
	v_min_u32_e32 v10, v12, v10
	v_max_u32_e32 v12, v11, v8
	v_min_u32_e32 v8, v11, v8
	v_max_u32_e32 v11, v2, v5
	v_min_u32_e32 v2, v2, v5
	v_max_u32_e32 v5, v1, v9
	v_min_u32_e32 v1, v1, v9
	v_max_u32_e32 v9, v7, v4
	v_min_u32_e32 v4, v7, v4
	v_max_u32_e32 v7, v6, v13
	v_min_u32_e32 v6, v6, v13
	v_max_u32_e32 v13, v3, v12
	v_min_u32_e32 v3, v3, v12
	v_max_u32_e32 v12, v10, v8
	v_min_u32_e32 v8, v10, v8
	v_max_u32_e32 v10, v11, v5
	v_min_u32_e32 v5, v11, v5
	v_max_u32_e32 v11, v2, v1
	v_min_u32_e32 v1, v2, v1
	v_max_u32_e32 v2, v9, v7
	v_min_u32_e32 v7, v9, v7
	v_max_u32_e32 v9, v4, v6
	v_min_u32_e32 v4, v4, v6
	s_nop 1
	v_mov_b32_dpp v6, v0 quad_perm:[1,0,3,2] row_mask:0xf bank_mask:0xf
	v_mov_b32_dpp v14, v4 quad_perm:[1,0,3,2] row_mask:0xf bank_mask:0xf
	v_mov_b32_dpp v15, v9 quad_perm:[1,0,3,2] row_mask:0xf bank_mask:0xf
	v_mov_b32_dpp v16, v7 quad_perm:[1,0,3,2] row_mask:0xf bank_mask:0xf
	v_mov_b32_dpp v17, v2 quad_perm:[1,0,3,2] row_mask:0xf bank_mask:0xf
	v_mov_b32_dpp v18, v1 quad_perm:[1,0,3,2] row_mask:0xf bank_mask:0xf
	v_mov_b32_dpp v19, v11 quad_perm:[1,0,3,2] row_mask:0xf bank_mask:0xf
	v_mov_b32_dpp v20, v5 quad_perm:[1,0,3,2] row_mask:0xf bank_mask:0xf
	v_mov_b32_dpp v21, v10 quad_perm:[1,0,3,2] row_mask:0xf bank_mask:0xf
	v_mov_b32_dpp v22, v8 quad_perm:[1,0,3,2] row_mask:0xf bank_mask:0xf
	v_mov_b32_dpp v23, v12 quad_perm:[1,0,3,2] row_mask:0xf bank_mask:0xf
	v_mov_b32_dpp v24, v3 quad_perm:[1,0,3,2] row_mask:0xf bank_mask:0xf
	v_mov_b32_dpp v25, v13 quad_perm:[1,0,3,2] row_mask:0xf bank_mask:0xf
	s_waitcnt lgkmcnt(0)
	v_max_u32_e32 v6, v8, v6
	v_max_u32_e32 v8, v10, v14
	v_max_u32_e32 v5, v5, v15
	v_max_u32_e32 v10, v11, v16
	v_max_u32_e32 v1, v1, v17
	v_max_u32_e32 v2, v2, v18
	v_max_u32_e32 v7, v7, v19
	v_max_u32_e32 v9, v9, v20
	v_max_u32_e32 v4, v4, v21
	v_max_u32_e32 v0, v0, v22
	v_max_u32_e32 v11, v13, v2
	v_min_u32_e32 v2, v13, v2
	v_max_u32_e32 v13, v3, v7
	v_min_u32_e32 v3, v3, v7
	v_max_u32_e32 v7, v12, v9
	v_min_u32_e32 v9, v12, v9
	v_max_u32_e32 v12, v6, v4
	v_min_u32_e32 v4, v6, v4
	v_max_u32_e32 v6, v8, v0
	v_min_u32_e32 v0, v8, v0
	v_max_u32_e32 v8, v5, v23
	v_min_u32_e32 v5, v5, v23
	v_max_u32_e32 v14, v10, v24
	v_min_u32_e32 v10, v10, v24
	v_max_u32_e32 v15, v1, v25
	v_min_u32_e32 v1, v1, v25
	v_max_u32_e32 v16, v11, v6
	v_min_u32_e32 v6, v11, v6
	v_max_u32_e32 v11, v13, v8
	v_min_u32_e32 v8, v13, v8
	v_max_u32_e32 v13, v7, v14
	v_min_u32_e32 v7, v7, v14
	v_max_u32_e32 v14, v12, v15
	v_min_u32_e32 v12, v12, v15
	v_max_u32_e32 v15, v2, v0
	v_min_u32_e32 v0, v2, v0
	v_max_u32_e32 v2, v3, v5
	v_min_u32_e32 v3, v3, v5
	v_max_u32_e32 v5, v9, v10
	v_min_u32_e32 v9, v9, v10
	v_max_u32_e32 v10, v4, v1
	v_min_u32_e32 v1, v4, v1
	v_max_u32_e32 v4, v16, v13
	v_min_u32_e32 v13, v16, v13
	v_max_u32_e32 v16, v11, v14
	v_min_u32_e32 v11, v11, v14
	v_max_u32_e32 v14, v6, v7
	v_min_u32_e32 v6, v6, v7
	v_max_u32_e32 v7, v8, v12
	v_min_u32_e32 v8, v8, v12
	v_max_u32_e32 v12, v15, v5
	v_min_u32_e32 v5, v15, v5
	v_max_u32_e32 v15, v2, v10
	v_min_u32_e32 v2, v2, v10
	v_max_u32_e32 v10, v0, v9
	v_min_u32_e32 v0, v0, v9
	v_max_u32_e32 v9, v3, v1
	v_min_u32_e32 v1, v3, v1
	v_max_u32_e32 v3, v4, v16
	v_min_u32_e32 v4, v4, v16
	v_max_u32_e32 v16, v13, v11
	v_min_u32_e32 v11, v13, v11
	v_max_u32_e32 v13, v14, v7
; DI void merge_top16(unsigned (&v)[16], int st) {
;     unsigned x[16];
; #pragma unroll
;     for (int i = 0; i < 16; ++i) x[i] = (unsigned)__shfl_xor((int)v[15 - i], st);
; #pragma unroll
;     for (int i = 0; i < 16; ++i) v[i] = max(v[i], x[i]);
; #pragma unroll
;     for (int j = 8; j > 0; j >>= 1)
; #pragma unroll
;         for (int i = 0; i < 16; ++i) { const int l = i ^ j; if (l > i) cswap(v[i], v[l]); }
; DI void topk_phase(unsigned char* smem_, const bf16_t* __restrict__ qp, const bf16_t* __restrict__ keys, int* __restrict__ eidx, float* __restrict__ gate) {
;     ...
;     merge_top16(c16, 2);
;     float bv[16]; int be[16]; float mx = -3.0e38f;
; #pragma unroll
;     for (int i = 0; i < 16; ++i) {
;         const int ab = 255 - (int)(c16[i] & 255u), a = ab >> 4, b = ab & 15;
;         bv[i] = SV[row * 32 + a] + SV[row * 32 + 16 + b];
;         be[i] = SI[row * 32 + a] * 128 + SI[row * 32 + 16 + b];
;         mx = fmaxf(mx, bv[i]);
	v_min_u32_e32 v7, v14, v7
	v_max_u32_e32 v14, v6, v8
	v_min_u32_e32 v6, v6, v8
	v_max_u32_e32 v8, v12, v15
	v_min_u32_e32 v12, v12, v15
	v_max_u32_e32 v15, v5, v2
	v_min_u32_e32 v2, v5, v2
	v_max_u32_e32 v5, v10, v9
	v_min_u32_e32 v9, v10, v9
	v_max_u32_e32 v10, v0, v1
	v_min_u32_e32 v0, v0, v1
	s_nop 1
	v_mov_b32_dpp v1, v0 quad_perm:[2,3,0,1] row_mask:0xf bank_mask:0xf
	v_mov_b32_dpp v17, v10 quad_perm:[2,3,0,1] row_mask:0xf bank_mask:0xf
	v_mov_b32_dpp v18, v9 quad_perm:[2,3,0,1] row_mask:0xf bank_mask:0xf
	v_mov_b32_dpp v19, v5 quad_perm:[2,3,0,1] row_mask:0xf bank_mask:0xf
	v_mov_b32_dpp v20, v2 quad_perm:[2,3,0,1] row_mask:0xf bank_mask:0xf
	v_mov_b32_dpp v21, v15 quad_perm:[2,3,0,1] row_mask:0xf bank_mask:0xf
	v_mov_b32_dpp v22, v12 quad_perm:[2,3,0,1] row_mask:0xf bank_mask:0xf
	v_mov_b32_dpp v23, v8 quad_perm:[2,3,0,1] row_mask:0xf bank_mask:0xf
	v_mov_b32_dpp v24, v6 quad_perm:[2,3,0,1] row_mask:0xf bank_mask:0xf
	v_mov_b32_dpp v25, v14 quad_perm:[2,3,0,1] row_mask:0xf bank_mask:0xf
	v_mov_b32_dpp v26, v7 quad_perm:[2,3,0,1] row_mask:0xf bank_mask:0xf
	v_mov_b32_dpp v27, v13 quad_perm:[2,3,0,1] row_mask:0xf bank_mask:0xf
	v_mov_b32_dpp v28, v11 quad_perm:[2,3,0,1] row_mask:0xf bank_mask:0xf
	v_mov_b32_dpp v29, v16 quad_perm:[2,3,0,1] row_mask:0xf bank_mask:0xf
	v_mov_b32_dpp v30, v4 quad_perm:[2,3,0,1] row_mask:0xf bank_mask:0xf
	v_mov_b32_dpp v31, v3 quad_perm:[2,3,0,1] row_mask:0xf bank_mask:0xf
	s_waitcnt lgkmcnt(0)
	v_max_u32_e32 v1, v3, v1
	v_max_u32_e32 v3, v4, v17
	v_max_u32_e32 v4, v16, v18
	v_max_u32_e32 v11, v11, v19
	v_max_u32_e32 v13, v13, v20
	v_max_u32_e32 v7, v7, v21
	v_max_u32_e32 v14, v14, v22
	v_max_u32_e32 v6, v6, v23
	v_max_u32_e32 v8, v8, v24
	v_max_u32_e32 v12, v12, v25
	v_max_u32_e32 v15, v15, v26
	v_max_u32_e32 v2, v2, v27
	v_max_u32_e32 v5, v5, v28
	v_max_u32_e32 v9, v9, v29
	v_max_u32_e32 v10, v10, v30
	v_max_u32_e32 v0, v0, v31
	v_max_u32_e32 v16, v1, v8
	v_min_u32_e32 v1, v1, v8
	v_max_u32_e32 v8, v3, v12
	v_min_u32_e32 v3, v3, v12
	v_max_u32_e32 v12, v4, v15
	v_min_u32_e32 v4, v4, v15
	v_max_u32_e32 v15, v11, v2
	v_min_u32_e32 v2, v11, v2
	v_max_u32_e32 v11, v13, v5
	v_min_u32_e32 v5, v13, v5
	v_max_u32_e32 v13, v7, v9
	v_min_u32_e32 v7, v7, v9
	v_max_u32_e32 v9, v14, v10
	v_min_u32_e32 v10, v14, v10
	v_max_u32_e32 v14, v6, v0
	v_min_u32_e32 v0, v6, v0
	v_max_u32_e32 v6, v16, v11
	v_min_u32_e32 v11, v16, v11
	v_max_u32_e32 v16, v8, v13
	v_min_u32_e32 v8, v8, v13
	v_max_u32_e32 v13, v12, v9
	v_min_u32_e32 v9, v12, v9
	v_max_u32_e32 v12, v15, v14
	v_min_u32_e32 v14, v15, v14
	v_max_u32_e32 v15, v1, v5
	v_min_u32_e32 v1, v1, v5
	v_max_u32_e32 v5, v3, v7
	v_min_u32_e32 v3, v3, v7
	v_max_u32_e32 v7, v4, v10
	v_min_u32_e32 v4, v4, v10
	v_max_u32_e32 v10, v2, v0
	v_min_u32_e32 v0, v2, v0
	v_max_u32_e32 v2, v6, v13
	v_min_u32_e32 v6, v6, v13
	v_max_u32_e32 v13, v16, v12
	v_min_u32_e32 v12, v16, v12
	v_max_u32_e32 v16, v11, v9
	v_min_u32_e32 v9, v11, v9
	v_max_u32_e32 v11, v8, v14
	v_min_u32_e32 v8, v8, v14
	v_max_u32_e32 v14, v15, v7
	v_min_u32_e32 v7, v15, v7
	v_max_u32_e32 v15, v5, v10
	v_min_u32_e32 v5, v5, v10
	v_max_u32_e32 v10, v1, v4
	v_min_u32_e32 v1, v1, v4
	v_max_u32_e32 v4, v3, v0
	v_min_u32_e32 v0, v3, v0
	v_max_u32_e32 v3, v2, v13
	v_not_b32_e32 v17, v3
	v_min_u32_e32 v2, v2, v13
	v_max_u32_e32 v142, v1, v0
	v_min_u32_e32 v144, v1, v0
	v_lshrrev_b32_e32 v0, 4, v17
	v_not_b32_e32 v13, v2
	v_and_or_b32 v0, v0, 15, v174
	v_max_u32_e32 v18, v6, v12
	v_lshl_add_u32 v237, v0, 2, s19
	v_lshrrev_b32_e32 v0, 4, v13
	v_not_b32_e32 v19, v18
	v_and_or_b32 v0, v0, 15, v174
	v_min_u32_e32 v6, v6, v12
	v_bitop3_b32 v1, v3, 15, v3 bitop3:0xc
	v_lshl_add_u32 v239, v0, 2, s19
	v_lshrrev_b32_e32 v0, 4, v19
	v_not_b32_e32 v12, v6
	v_lshl_add_u32 v238, v1, 2, v184
	v_bitop3_b32 v1, v2, 15, v2 bitop3:0xc
	v_and_or_b32 v0, v0, 15, v174
	v_lshl_add_u32 v240, v1, 2, v175
	v_bitop3_b32 v1, v18, 15, v18 bitop3:0xc
	v_lshl_add_u32 v241, v0, 2, s19
	v_lshrrev_b32_e32 v0, 4, v12
	v_lshl_add_u32 v242, v1, 2, v184
	v_bitop3_b32 v1, v6, 15, v6 bitop3:0xc
	v_and_or_b32 v0, v0, 15, v174
	v_max_u32_e32 v30, v7, v5
	v_min_u32_e32 v116, v7, v5
	v_max_u32_e32 v120, v10, v4
	v_min_u32_e32 v124, v10, v4
	v_lshl_add_u32 v243, v0, 2, s19
	v_lshl_add_u32 v244, v1, 2, v175
	ds_read_b32 v0, v237 offset:53248
	ds_read_b32 v1, v238 offset:53312
	ds_read_b32 v2, v239 offset:53248
	ds_read_b32 v3, v240 offset:53312
	ds_read_b32 v4, v241 offset:53248
	ds_read_b32 v5, v242 offset:53312
	ds_read_b32 v6, v243 offset:53248
	ds_read_b32 v7, v244 offset:53312
	v_max_u32_e32 v20, v16, v11
	v_min_u32_e32 v11, v16, v11
	v_not_b32_e32 v16, v11
	s_waitcnt lgkmcnt(2)
	v_add_f32_e32 v148, v4, v5
	v_lshrrev_b32_e32 v5, 4, v16
	v_and_or_b32 v5, v5, 15, v174
	v_bitop3_b32 v10, v11, 15, v11 bitop3:0xc
	v_lshl_add_u32 v5, v5, 2, s19
	v_max_u32_e32 v22, v9, v8
	s_waitcnt lgkmcnt(0)
	v_add_f32_e32 v149, v6, v7
	ds_read2st64_b32 v[6:7], v5 offset0:208 offset1:240
	v_lshl_add_u32 v5, v10, 2, v175
	v_not_b32_e32 v23, v22
	v_add_u32_e32 v5, 64, v5
	ds_read2st64_b32 v[10:11], v5 offset0:208 offset1:240
	v_lshrrev_b32_e32 v5, 4, v23
	v_and_or_b32 v5, v5, 15, v174
	v_bitop3_b32 v12, v22, 15, v22 bitop3:0xc
	v_lshl_add_u32 v5, v5, 2, s19
	v_min_u32_e32 v8, v9, v8
	v_max_u32_e32 v24, v14, v15
	v_min_u32_e32 v26, v14, v15
	v_add_f32_e32 v146, v0, v1
	v_add_f32_e32 v147, v2, v3
	ds_read2st64_b32 v[14:15], v5 offset0:208 offset1:240
	v_lshl_add_u32 v5, v12, 2, v184
	v_not_b32_e32 v21, v20
	v_not_b32_e32 v9, v8
	v_max3_f32 v0, v146, s16, v147
	v_add_u32_e32 v5, 64, v5
	v_max3_f32 v4, v0, v148, v149
	v_lshrrev_b32_e32 v0, 4, v21
	v_bitop3_b32 v2, v20, 15, v20 bitop3:0xc
	ds_read2st64_b32 v[20:21], v5 offset0:208 offset1:240
	v_lshrrev_b32_e32 v5, 4, v9
	v_and_or_b32 v0, v0, 15, v174
	v_lshl_add_u32 v2, v2, 2, v184
	v_and_or_b32 v5, v5, 15, v174
	v_lshl_add_u32 v0, v0, 2, s19
	v_add_u32_e32 v2, 64, v2
	v_bitop3_b32 v8, v8, 15, v8 bitop3:0xc
	v_lshl_add_u32 v5, v5, 2, s19
	ds_read2st64_b32 v[0:1], v0 offset0:208 offset1:240
	ds_read2st64_b32 v[2:3], v2 offset0:208 offset1:240
	ds_read2st64_b32 v[28:29], v5 offset0:208 offset1:240
	v_lshl_add_u32 v5, v8, 2, v175
	v_add_u32_e32 v5, 64, v5
	v_not_b32_e32 v27, v26
	ds_read2st64_b32 v[118:119], v5 offset0:208 offset1:240
	v_lshrrev_b32_e32 v13, 4, v27
	v_and_or_b32 v13, v13, 15, v174
	s_waitcnt lgkmcnt(2)
; DI void topk_phase(unsigned char* smem_, const bf16_t* __restrict__ qp, const bf16_t* __restrict__ keys, int* __restrict__ eidx, float* __restrict__ gate) {
;     ...
;     float bv[16]; int be[16]; float mx = -3.0e38f;
; #pragma unroll
;     for (int i = 0; i < 16; ++i) {
;         const int ab = 255 - (int)(c16[i] & 255u), a = ab >> 4, b = ab & 15;
;         bv[i] = SV[row * 32 + a] + SV[row * 32 + 16 + b];
;         be[i] = SI[row * 32 + a] * 128 + SI[row * 32 + 16 + b];
;         mx = fmaxf(mx, bv[i]);
;     }
;     float sum = 0.f, ex[16];
; #pragma unroll
;     for (int i = 0; i < 16; ++i) { ex[i] = __expf(bv[i] - mx); sum += ex[i]; }
;     const float inv = 1.f / sum;
;     const size_t ob = (size_t)(tok0 + row) * 128 + h * 16;
; #pragma unroll
;     for (int i = 0; i < 16; ++i) if ((i >> 2) == q) { eidx[ob + i] = be[i]; gate[ob + i] = ex[i] * inv; }
	v_add_f32_e32 v0, v0, v2
	v_add_f32_e32 v2, v6, v10
	v_add_f32_e32 v6, v14, v20
	v_bitop3_b32 v14, v26, 15, v26 bitop3:0xc
	v_lshl_add_u32 v13, v13, 2, s19
	ds_read2st64_b32 v[16:17], v13 offset0:208 offset1:240
	v_lshl_add_u32 v13, v14, 2, v175
	v_not_b32_e32 v25, v24
	v_not_b32_e32 v31, v30
	v_max3_f32 v4, v4, v0, v2
	s_waitcnt lgkmcnt(1)
	v_add_f32_e32 v10, v28, v118
	v_add_u32_e32 v13, 64, v13
	v_max3_f32 v12, v4, v6, v10
	v_lshrrev_b32_e32 v4, 4, v25
	v_bitop3_b32 v8, v24, 15, v24 bitop3:0xc
	ds_read2st64_b32 v[22:23], v13 offset0:208 offset1:240
	v_lshrrev_b32_e32 v13, 4, v31
	v_and_or_b32 v4, v4, 15, v174
	v_lshl_add_u32 v8, v8, 2, v184
	v_and_or_b32 v13, v13, 15, v174
	v_lshl_add_u32 v4, v4, 2, s19
	v_add_u32_e32 v8, 64, v8
	v_bitop3_b32 v14, v30, 15, v30 bitop3:0xc
	v_lshl_add_u32 v13, v13, 2, s19
	ds_read2st64_b32 v[4:5], v4 offset0:208 offset1:240
	ds_read2st64_b32 v[8:9], v8 offset0:208 offset1:240
	ds_read2st64_b32 v[24:25], v13 offset0:208 offset1:240
	v_lshl_add_u32 v13, v14, 2, v184
	v_not_b32_e32 v117, v116
	v_add_u32_e32 v13, 64, v13
	ds_read2st64_b32 v[30:31], v13 offset0:208 offset1:240
	v_lshrrev_b32_e32 v13, 4, v117
	v_and_or_b32 v13, v13, 15, v174
	v_not_b32_e32 v125, v124
	v_bitop3_b32 v14, v116, 15, v116 bitop3:0xc
	v_lshl_add_u32 v13, v13, 2, s19
	ds_read2st64_b32 v[122:123], v13 offset0:208 offset1:240
	v_lshl_add_u32 v13, v14, 2, v175
	s_waitcnt lgkmcnt(3)
	v_add_f32_e32 v4, v4, v8
	v_add_f32_e32 v8, v16, v22
	v_lshrrev_b32_e32 v22, 4, v125
	v_add_u32_e32 v13, 64, v13
	v_and_or_b32 v22, v22, 15, v174
	ds_read2st64_b32 v[126:127], v13 offset0:208 offset1:240
	s_waitcnt lgkmcnt(2)
	v_add_f32_e32 v14, v24, v30
	v_bitop3_b32 v24, v124, 15, v124 bitop3:0xc
	v_lshl_add_u32 v22, v22, 2, s19
	ds_read2st64_b32 v[26:27], v22 offset0:208 offset1:240
	v_lshl_add_u32 v22, v24, 2, v175
	v_not_b32_e32 v143, v142
	v_add_u32_e32 v22, 64, v22
	ds_read2st64_b32 v[116:117], v22 offset0:208 offset1:240
	v_lshrrev_b32_e32 v22, 4, v143
	v_and_or_b32 v22, v22, 15, v174
	v_not_b32_e32 v121, v120
	v_max3_f32 v12, v12, v4, v8
	s_waitcnt lgkmcnt(2)
	v_add_f32_e32 v16, v122, v126
	v_bitop3_b32 v24, v142, 15, v142 bitop3:0xc
	v_lshl_add_u32 v22, v22, 2, s19
	v_max3_f32 v20, v12, v14, v16
	v_lshrrev_b32_e32 v12, 4, v121
	v_bitop3_b32 v18, v120, 15, v120 bitop3:0xc
	ds_read2st64_b32 v[120:121], v22 offset0:208 offset1:240
	v_lshl_add_u32 v22, v24, 2, v184
	v_not_b32_e32 v145, v144
	v_add_u32_e32 v22, 64, v22
	ds_read2st64_b32 v[124:125], v22 offset0:208 offset1:240
	v_lshrrev_b32_e32 v22, 4, v145
	v_and_or_b32 v22, v22, 15, v174
	v_and_or_b32 v12, v12, 15, v174
	v_lshl_add_u32 v18, v18, 2, v184
	v_bitop3_b32 v24, v144, 15, v144 bitop3:0xc
	v_lshl_add_u32 v22, v22, 2, s19
	v_lshl_add_u32 v12, v12, 2, s19
	v_add_u32_e32 v18, 64, v18
	ds_read2st64_b32 v[142:143], v22 offset0:208 offset1:240
	v_lshl_add_u32 v22, v24, 2, v175
	ds_read2st64_b32 v[12:13], v12 offset0:208 offset1:240
	ds_read2st64_b32 v[18:19], v18 offset0:208 offset1:240
	v_add_u32_e32 v22, 64, v22
	ds_read2st64_b32 v[144:145], v22 offset0:208 offset1:240
	s_waitcnt lgkmcnt(4)
	v_add_f32_e32 v22, v120, v124
	s_waitcnt lgkmcnt(1)
	v_add_f32_e32 v12, v12, v18
	v_add_f32_e32 v18, v26, v116
	v_max3_f32 v20, v20, v12, v18
	s_waitcnt lgkmcnt(0)
	v_add_f32_e32 v24, v142, v144
	v_max3_f32 v20, v20, v22, v24
	v_sub_f32_e32 v26, v146, v20
	v_mul_f32_e32 v26, 0x3fb8aa3b, v26
	v_exp_f32_e32 v160, v26
	v_sub_f32_e32 v26, v147, v20
	v_sub_f32_e32 v0, v0, v20
	v_mul_f32_e32 v26, 0x3fb8aa3b, v26
	v_mul_f32_e32 v0, 0x3fb8aa3b, v0
	v_exp_f32_e32 v161, v26
	v_sub_f32_e32 v26, v148, v20
	v_exp_f32_e32 v154, v0
	v_sub_f32_e32 v0, v2, v20
	v_sub_f32_e32 v2, v4, v20
	v_mul_f32_e32 v26, 0x3fb8aa3b, v26
	v_mul_f32_e32 v2, 0x3fb8aa3b, v2
	v_exp_f32_e32 v162, v26
	v_sub_f32_e32 v26, v149, v20
	v_exp_f32_e32 v150, v2
	v_sub_f32_e32 v2, v8, v20
	v_mul_f32_e32 v26, 0x3fb8aa3b, v26
	v_mul_f32_e32 v0, 0x3fb8aa3b, v0
	v_mul_f32_e32 v2, 0x3fb8aa3b, v2
	v_exp_f32_e32 v163, v26
	v_exp_f32_e32 v155, v0
	v_sub_f32_e32 v0, v6, v20
	v_exp_f32_e32 v151, v2
	v_sub_f32_e32 v2, v14, v20
	v_add_f32_e32 v26, 0, v160
	v_mul_f32_e32 v0, 0x3fb8aa3b, v0
	v_mul_f32_e32 v2, 0x3fb8aa3b, v2
	v_add_f32_e32 v26, v161, v26
	v_exp_f32_e32 v156, v0
	v_sub_f32_e32 v0, v10, v20
	v_exp_f32_e32 v152, v2
	v_sub_f32_e32 v2, v16, v20
	v_add_f32_e32 v26, v162, v26
	v_mul_f32_e32 v0, 0x3fb8aa3b, v0
	v_mul_f32_e32 v2, 0x3fb8aa3b, v2
	v_add_f32_e32 v26, v163, v26
	v_exp_f32_e32 v157, v0
	v_exp_f32_e32 v153, v2
	v_sub_f32_e32 v2, v12, v20
	v_add_f32_e32 v0, v154, v26
	v_mul_f32_e32 v2, 0x3fb8aa3b, v2
	v_add_f32_e32 v0, v155, v0
	v_exp_f32_e32 v146, v2
	v_sub_f32_e32 v2, v18, v20
	v_add_f32_e32 v0, v156, v0
	v_mul_f32_e32 v2, 0x3fb8aa3b, v2
	v_add_f32_e32 v0, v157, v0
	v_exp_f32_e32 v147, v2
	v_sub_f32_e32 v2, v22, v20
	v_add_f32_e32 v0, v150, v0
	v_mul_f32_e32 v2, 0x3fb8aa3b, v2
	v_add_f32_e32 v0, v151, v0
	v_exp_f32_e32 v148, v2
	v_sub_f32_e32 v2, v24, v20
	v_add_f32_e32 v0, v152, v0
	v_mul_f32_e32 v2, 0x3fb8aa3b, v2
	v_add_f32_e32 v0, v153, v0
	v_exp_f32_e32 v149, v2
	v_add_f32_e32 v0, v146, v0
	v_add_f32_e32 v0, v147, v0
	v_add_f32_e32 v0, v148, v0
	v_add_f32_e32 v0, v149, v0
	v_div_scale_f32 v2, s[16:17], v0, v0, 1.0
	v_rcp_f32_e32 v4, v2
	s_nop 0
	v_fma_f32 v6, -v2, v4, 1.0
	v_fmac_f32_e32 v4, v6, v4
	v_div_scale_f32 v6, vcc, 1.0, v0, 1.0
	v_mul_f32_e32 v8, v6, v4
	v_fma_f32 v10, -v2, v8, v6
	v_fmac_f32_e32 v8, v10, v4
	v_fma_f32 v2, -v2, v8, v6
	v_div_fmas_f32 v2, v2, v4, v8
	v_div_fixup_f32 v0, v2, v0, 1.0
	s_and_saveexec_b64 s[16:17], s[4:5]
	s_cbranch_execnz .LBB0_79
	s_or_b64 exec, exec, s[16:17]
	s_and_saveexec_b64 s[16:17], s[6:7]
	s_cbranch_execnz .LBB0_80
